# out-proj quarter units: the epilogue's residual rows are prefetched late in the lean K-loop into accumulator registers the quadrant does not use
# baseline (speedup 1.0000x reference)
;     DI void operator()(const f32x4 (&acc)[2][2][4][2], const pg8::Unit& u, int wr, int wc, int fr, int fq) const {
;     ...
;                 const int R = u.pm * 256 + ai * 128 + wr * 64 + m * 16 + fr;
;                 const float* xs = nullptr; float* yd = nullptr;
;                 if (R < ROWS_P) { const int b = R / LPAD, t = R - b * LPAD; if (t >= NMETA && t < LP) { const size_t idx = ((size_t)b * SEQ + t - NMETA) * DM; xs = p.x_prompt + idx; yd = p.out + O_YP + idx; } }
;                 else { const size_t idx = (size_t)(R - ROWS_P) * DM; xs = p.x_sample + idx; yd = p.out + O_YS + idx; }
;                 float ss = 0.f;
;                 if (xs) {
; #pragma unroll
;                     for (int bj = 0; bj < 2; ++bj) {
;                         const int n = colt + bj * 128 + wc * 32 + 8 * fq;
;                         const f32x4 x0 = *(const f32x4*)(xs + n), x1 = *(const f32x4*)(xs + n + 4);
;                         const f32x4 h0 = x0 + acc[ai][bj][m][0], h1 = x1 + acc[ai][bj][m][1];
;                         *(f32x4*)(yd + n) = h0; *(f32x4*)(yd + n + 4) = h1;
;                         ss += h0[0] * h0[0] + h0[1] * h0[1] + h0[2] * h0[2] + h0[3] * h0[3] + h1[0] * h1[0] + h1[1] * h1[1] + h1[2] * h1[2] + h1[3] * h1[3];
;                     }
;                 }
;                 ss += __shfl_xor(ss, 16); ss += __shfl_xor(ss, 32);
;                 if (xs && fq == 0) atomicAdd(p.rowss + R, ss);
.Lp3q_v0:
	s_add_i32 s87, s21, 0
	s_mul_hi_u32 s89, s87, 0x7e07e07f
	s_lshr_b32 s89, s89, 11
	s_mul_i32 vcc_lo, s89, 0x1040
	s_sub_i32 vcc_lo, s87, vcc_lo
	s_add_i32 vcc_lo, vcc_lo, -16
	s_lshl_b32 s89, s89, 12
	s_add_i32 s89, s89, vcc_lo
	s_cmp_lt_u32 vcc_lo, 0x1000
	s_cselect_b32 vcc_hi, 1, 0
	s_sub_i32 vcc_lo, s87, 0x4100
	s_cmp_ge_u32 s94, 65
	s_cselect_b32 s89, vcc_lo, s89
	s_cselect_b32 vcc_hi, 1, vcc_hi
	s_cmp_lg_u32 vcc_hi, 0
	s_cselect_b32 s89, s89, 0
	s_lshl_b32 s20, s89, 12
	s_lshl_b32 vcc_hi, vcc_hi, 0
	s_or_b32 s19, s19, vcc_hi
	s_add_i32 s87, s21, 16
	s_mul_hi_u32 s89, s87, 0x7e07e07f
	s_lshr_b32 s89, s89, 11
	s_mul_i32 vcc_lo, s89, 0x1040
	s_sub_i32 vcc_lo, s87, vcc_lo
	s_add_i32 vcc_lo, vcc_lo, -16
	s_lshl_b32 s89, s89, 12
	s_add_i32 s89, s89, vcc_lo
	s_cmp_lt_u32 vcc_lo, 0x1000
	s_cselect_b32 vcc_hi, 1, 0
	s_sub_i32 vcc_lo, s87, 0x4100
	s_cmp_ge_u32 s94, 65
	s_cselect_b32 s89, vcc_lo, s89
	s_cselect_b32 vcc_hi, 1, vcc_hi
	s_cmp_lg_u32 vcc_hi, 0
	s_cselect_b32 s89, s89, 0
	s_lshl_b32 s42, s89, 12
	s_lshl_b32 vcc_hi, vcc_hi, 1
	s_or_b32 s19, s19, vcc_hi
	s_add_i32 s87, s21, 32
	s_mul_hi_u32 s89, s87, 0x7e07e07f
	s_lshr_b32 s89, s89, 11
	s_mul_i32 vcc_lo, s89, 0x1040
	s_sub_i32 vcc_lo, s87, vcc_lo
	s_add_i32 vcc_lo, vcc_lo, -16
	s_lshl_b32 s89, s89, 12
	s_add_i32 s89, s89, vcc_lo
	s_cmp_lt_u32 vcc_lo, 0x1000
	s_cselect_b32 vcc_hi, 1, 0
	s_sub_i32 vcc_lo, s87, 0x4100
	s_cmp_ge_u32 s94, 65
	s_cselect_b32 s89, vcc_lo, s89
	s_cselect_b32 vcc_hi, 1, vcc_hi
	s_cmp_lg_u32 vcc_hi, 0
	s_cselect_b32 s89, s89, 0
	s_lshl_b32 s43, s89, 12
	s_lshl_b32 vcc_hi, vcc_hi, 2
	s_or_b32 s19, s19, vcc_hi
	s_add_i32 s87, s21, 48
	s_mul_hi_u32 s89, s87, 0x7e07e07f
	s_lshr_b32 s89, s89, 11
	s_mul_i32 vcc_lo, s89, 0x1040
	s_sub_i32 vcc_lo, s87, vcc_lo
	s_add_i32 vcc_lo, vcc_lo, -16
	s_lshl_b32 s89, s89, 12
	s_add_i32 s89, s89, vcc_lo
	s_cmp_lt_u32 vcc_lo, 0x1000
	s_cselect_b32 vcc_hi, 1, 0
	s_sub_i32 vcc_lo, s87, 0x4100
	s_cmp_ge_u32 s94, 65
	s_cselect_b32 s89, vcc_lo, s89
	s_cselect_b32 vcc_hi, 1, vcc_hi
	s_cmp_lg_u32 vcc_hi, 0
	s_cselect_b32 s89, s89, 0
	s_lshl_b32 s95, s89, 12
	s_lshl_b32 vcc_hi, vcc_hi, 3
	s_or_b32 s19, s19, vcc_hi
	s_waitcnt vmcnt(0)
	v_pk_add_f32 v[124:125], v[124:125], v[0:1]
	v_pk_add_f32 v[126:127], v[126:127], v[2:3]
	v_pk_add_f32 v[120:121], v[120:121], v[4:5]
	v_pk_add_f32 v[122:123], v[122:123], v[6:7]
	v_pk_mul_f32 v[172:173], v[124:125], v[124:125]
	v_pk_fma_f32 v[172:173], v[126:127], v[126:127], v[172:173]
	v_pk_fma_f32 v[172:173], v[120:121], v[120:121], v[172:173]
	v_pk_fma_f32 v[172:173], v[122:123], v[122:123], v[172:173]
	s_nop 0
	v_add_f32_e32 v168, v172, v173
	v_pk_add_f32 v[108:109], v[108:109], v[8:9]
	v_pk_add_f32 v[110:111], v[110:111], v[10:11]
	v_pk_add_f32 v[104:105], v[104:105], v[12:13]
	v_pk_add_f32 v[106:107], v[106:107], v[14:15]
	v_pk_mul_f32 v[172:173], v[108:109], v[108:109]
	v_pk_fma_f32 v[172:173], v[110:111], v[110:111], v[172:173]
	v_pk_fma_f32 v[172:173], v[104:105], v[104:105], v[172:173]
	v_pk_fma_f32 v[172:173], v[106:107], v[106:107], v[172:173]
	s_nop 0
	v_add_f32_e32 v169, v172, v173
	v_pk_add_f32 v[92:93], v[92:93], v[16:17]
	v_pk_add_f32 v[94:95], v[94:95], v[18:19]
	v_pk_add_f32 v[88:89], v[88:89], v[20:21]
	v_pk_add_f32 v[90:91], v[90:91], v[22:23]
	v_pk_mul_f32 v[172:173], v[92:93], v[92:93]
	v_pk_fma_f32 v[172:173], v[94:95], v[94:95], v[172:173]
	v_pk_fma_f32 v[172:173], v[88:89], v[88:89], v[172:173]
	v_pk_fma_f32 v[172:173], v[90:91], v[90:91], v[172:173]
	s_nop 0
	v_add_f32_e32 v170, v172, v173
	v_pk_add_f32 v[76:77], v[76:77], v[24:25]
	v_pk_add_f32 v[78:79], v[78:79], v[26:27]
	v_pk_add_f32 v[72:73], v[72:73], v[28:29]
	v_pk_add_f32 v[74:75], v[74:75], v[30:31]
	v_pk_mul_f32 v[172:173], v[76:77], v[76:77]
	v_pk_fma_f32 v[172:173], v[78:79], v[78:79], v[172:173]
	v_pk_fma_f32 v[172:173], v[72:73], v[72:73], v[172:173]
	v_pk_fma_f32 v[172:173], v[74:75], v[74:75], v[172:173]
	s_nop 0
	v_add_f32_e32 v171, v172, v173
	ds_bpermute_b32 v155, v153, v168
	ds_bpermute_b32 v156, v153, v169
	ds_bpermute_b32 v157, v153, v170
	ds_bpermute_b32 v132, v153, v171
	s_waitcnt lgkmcnt(0)
	v_add_f32_e32 v168, v168, v155
	v_add_f32_e32 v169, v169, v156
	v_add_f32_e32 v170, v170, v157
	v_add_f32_e32 v171, v171, v132
	ds_bpermute_b32 v155, v154, v168
	ds_bpermute_b32 v156, v154, v169
	ds_bpermute_b32 v157, v154, v170
	ds_bpermute_b32 v132, v154, v171
	s_waitcnt lgkmcnt(0)
	v_add_f32_e32 v168, v168, v155
	v_add_f32_e32 v169, v169, v156
	v_add_f32_e32 v170, v170, v157
	v_add_f32_e32 v171, v171, v132
	s_mov_b64 exec, s[36:37]
	s_bitcmp1_b32 s19, 0
	s_cbranch_scc0 .Lf3q0_at_q_0
	global_atomic_add_f32 v152, v168, s[60:61]

;     DI void operator()(const f32x4 (&acc)[2][2][4][2], const pg8::Unit& u, int wr, int wc, int fr, int fq) const {
;     ...
;                 const int R = u.pm * 256 + ai * 128 + wr * 64 + m * 16 + fr;
;                 const float* xs = nullptr; float* yd = nullptr;
;                 if (R < ROWS_P) { const int b = R / LPAD, t = R - b * LPAD; if (t >= NMETA && t < LP) { const size_t idx = ((size_t)b * SEQ + t - NMETA) * DM; xs = p.x_prompt + idx; yd = p.out + O_YP + idx; } }
;                 else { const size_t idx = (size_t)(R - ROWS_P) * DM; xs = p.x_sample + idx; yd = p.out + O_YS + idx; }
;                 float ss = 0.f;
;                 if (xs) {
; #pragma unroll
;                     for (int bj = 0; bj < 2; ++bj) {
;                         const int n = colt + bj * 128 + wc * 32 + 8 * fq;
;                         const f32x4 x0 = *(const f32x4*)(xs + n), x1 = *(const f32x4*)(xs + n + 4);
;                         const f32x4 h0 = x0 + acc[ai][bj][m][0], h1 = x1 + acc[ai][bj][m][1];
;                         *(f32x4*)(yd + n) = h0; *(f32x4*)(yd + n + 4) = h1;
;                         ss += h0[0] * h0[0] + h0[1] * h0[1] + h0[2] * h0[2] + h0[3] * h0[3] + h1[0] * h1[0] + h1[1] * h1[1] + h1[2] * h1[2] + h1[3] * h1[3];
;                     }
;                 }
;                 ss += __shfl_xor(ss, 16); ss += __shfl_xor(ss, 32);
;                 if (xs && fq == 0) atomicAdd(p.rowss + R, ss);
.Lp3q_v1:
	s_add_i32 s87, s21, 0
	s_mul_hi_u32 s89, s87, 0x7e07e07f
	s_lshr_b32 s89, s89, 11
	s_mul_i32 vcc_lo, s89, 0x1040
	s_sub_i32 vcc_lo, s87, vcc_lo
	s_add_i32 vcc_lo, vcc_lo, -16
	s_lshl_b32 s89, s89, 12
	s_add_i32 s89, s89, vcc_lo
	s_cmp_lt_u32 vcc_lo, 0x1000
	s_cselect_b32 vcc_hi, 1, 0
	s_sub_i32 vcc_lo, s87, 0x4100
	s_cmp_ge_u32 s94, 65
	s_cselect_b32 s89, vcc_lo, s89
	s_cselect_b32 vcc_hi, 1, vcc_hi
	s_cmp_lg_u32 vcc_hi, 0
	s_cselect_b32 s89, s89, 0
	s_lshl_b32 s20, s89, 12
	s_lshl_b32 vcc_hi, vcc_hi, 0
	s_or_b32 s19, s19, vcc_hi
	s_add_i32 s87, s21, 16
	s_mul_hi_u32 s89, s87, 0x7e07e07f
	s_lshr_b32 s89, s89, 11
	s_mul_i32 vcc_lo, s89, 0x1040
	s_sub_i32 vcc_lo, s87, vcc_lo
	s_add_i32 vcc_lo, vcc_lo, -16
	s_lshl_b32 s89, s89, 12
	s_add_i32 s89, s89, vcc_lo
	s_cmp_lt_u32 vcc_lo, 0x1000
	s_cselect_b32 vcc_hi, 1, 0
	s_sub_i32 vcc_lo, s87, 0x4100
	s_cmp_ge_u32 s94, 65
	s_cselect_b32 s89, vcc_lo, s89
	s_cselect_b32 vcc_hi, 1, vcc_hi
	s_cmp_lg_u32 vcc_hi, 0
	s_cselect_b32 s89, s89, 0
	s_lshl_b32 s42, s89, 12
	s_lshl_b32 vcc_hi, vcc_hi, 1
	s_or_b32 s19, s19, vcc_hi
	s_add_i32 s87, s21, 32
	s_mul_hi_u32 s89, s87, 0x7e07e07f
	s_lshr_b32 s89, s89, 11
	s_mul_i32 vcc_lo, s89, 0x1040
	s_sub_i32 vcc_lo, s87, vcc_lo
	s_add_i32 vcc_lo, vcc_lo, -16
	s_lshl_b32 s89, s89, 12
	s_add_i32 s89, s89, vcc_lo
	s_cmp_lt_u32 vcc_lo, 0x1000
	s_cselect_b32 vcc_hi, 1, 0
	s_sub_i32 vcc_lo, s87, 0x4100
	s_cmp_ge_u32 s94, 65
	s_cselect_b32 s89, vcc_lo, s89
	s_cselect_b32 vcc_hi, 1, vcc_hi
	s_cmp_lg_u32 vcc_hi, 0
	s_cselect_b32 s89, s89, 0
	s_lshl_b32 s43, s89, 12
	s_lshl_b32 vcc_hi, vcc_hi, 2
	s_or_b32 s19, s19, vcc_hi
	s_add_i32 s87, s21, 48
	s_mul_hi_u32 s89, s87, 0x7e07e07f
	s_lshr_b32 s89, s89, 11
	s_mul_i32 vcc_lo, s89, 0x1040
	s_sub_i32 vcc_lo, s87, vcc_lo
	s_add_i32 vcc_lo, vcc_lo, -16
	s_lshl_b32 s89, s89, 12
	s_add_i32 s89, s89, vcc_lo
	s_cmp_lt_u32 vcc_lo, 0x1000
	s_cselect_b32 vcc_hi, 1, 0
	s_sub_i32 vcc_lo, s87, 0x4100
	s_cmp_ge_u32 s94, 65
	s_cselect_b32 s89, vcc_lo, s89
	s_cselect_b32 vcc_hi, 1, vcc_hi
	s_cmp_lg_u32 vcc_hi, 0
	s_cselect_b32 s89, s89, 0
	s_lshl_b32 s95, s89, 12
	s_lshl_b32 vcc_hi, vcc_hi, 3
	s_or_b32 s19, s19, vcc_hi
	s_waitcnt vmcnt(0)
	v_pk_add_f32 v[116:117], v[116:117], v[0:1]
	v_pk_add_f32 v[118:119], v[118:119], v[2:3]
	v_pk_add_f32 v[112:113], v[112:113], v[4:5]
	v_pk_add_f32 v[114:115], v[114:115], v[6:7]
	v_pk_mul_f32 v[172:173], v[116:117], v[116:117]
	v_pk_fma_f32 v[172:173], v[118:119], v[118:119], v[172:173]
	v_pk_fma_f32 v[172:173], v[112:113], v[112:113], v[172:173]
	v_pk_fma_f32 v[172:173], v[114:115], v[114:115], v[172:173]
	s_nop 0
	v_add_f32_e32 v168, v172, v173
	v_pk_add_f32 v[100:101], v[100:101], v[8:9]
	v_pk_add_f32 v[102:103], v[102:103], v[10:11]
	v_pk_add_f32 v[96:97], v[96:97], v[12:13]
	v_pk_add_f32 v[98:99], v[98:99], v[14:15]
	v_pk_mul_f32 v[172:173], v[100:101], v[100:101]
	v_pk_fma_f32 v[172:173], v[102:103], v[102:103], v[172:173]
	v_pk_fma_f32 v[172:173], v[96:97], v[96:97], v[172:173]
	v_pk_fma_f32 v[172:173], v[98:99], v[98:99], v[172:173]
	s_nop 0
	v_add_f32_e32 v169, v172, v173
	v_pk_add_f32 v[84:85], v[84:85], v[16:17]
	v_pk_add_f32 v[86:87], v[86:87], v[18:19]
	v_pk_add_f32 v[80:81], v[80:81], v[20:21]
	v_pk_add_f32 v[82:83], v[82:83], v[22:23]
	v_pk_mul_f32 v[172:173], v[84:85], v[84:85]
	v_pk_fma_f32 v[172:173], v[86:87], v[86:87], v[172:173]
	v_pk_fma_f32 v[172:173], v[80:81], v[80:81], v[172:173]
	v_pk_fma_f32 v[172:173], v[82:83], v[82:83], v[172:173]
	s_nop 0
	v_add_f32_e32 v170, v172, v173
	v_pk_add_f32 v[68:69], v[68:69], v[24:25]
	v_pk_add_f32 v[70:71], v[70:71], v[26:27]
	v_pk_add_f32 v[64:65], v[64:65], v[28:29]
	v_pk_add_f32 v[66:67], v[66:67], v[30:31]
	v_pk_mul_f32 v[172:173], v[68:69], v[68:69]
	v_pk_fma_f32 v[172:173], v[70:71], v[70:71], v[172:173]
	v_pk_fma_f32 v[172:173], v[64:65], v[64:65], v[172:173]
	v_pk_fma_f32 v[172:173], v[66:67], v[66:67], v[172:173]
	s_nop 0
	v_add_f32_e32 v171, v172, v173
	ds_bpermute_b32 v155, v153, v168
	ds_bpermute_b32 v156, v153, v169
	ds_bpermute_b32 v157, v153, v170
	ds_bpermute_b32 v132, v153, v171
	s_waitcnt lgkmcnt(0)
	v_add_f32_e32 v168, v168, v155
	v_add_f32_e32 v169, v169, v156
	v_add_f32_e32 v170, v170, v157
	v_add_f32_e32 v171, v171, v132
	ds_bpermute_b32 v155, v154, v168
	ds_bpermute_b32 v156, v154, v169
	ds_bpermute_b32 v157, v154, v170
	ds_bpermute_b32 v132, v154, v171
	s_waitcnt lgkmcnt(0)
	v_add_f32_e32 v168, v168, v155
	v_add_f32_e32 v169, v169, v156
	v_add_f32_e32 v170, v170, v157
	v_add_f32_e32 v171, v171, v132
	s_mov_b64 exec, s[36:37]
	s_bitcmp1_b32 s19, 0
	s_cbranch_scc0 .Lf3q1_at_q_0
	global_atomic_add_f32 v152, v168, s[60:61]

;     DI void operator()(const f32x4 (&acc)[2][2][4][2], const pg8::Unit& u, int wr, int wc, int fr, int fq) const {
;     ...
;                 const int R = u.pm * 256 + ai * 128 + wr * 64 + m * 16 + fr;
;                 const float* xs = nullptr; float* yd = nullptr;
;                 if (R < ROWS_P) { const int b = R / LPAD, t = R - b * LPAD; if (t >= NMETA && t < LP) { const size_t idx = ((size_t)b * SEQ + t - NMETA) * DM; xs = p.x_prompt + idx; yd = p.out + O_YP + idx; } }
;                 else { const size_t idx = (size_t)(R - ROWS_P) * DM; xs = p.x_sample + idx; yd = p.out + O_YS + idx; }
;                 float ss = 0.f;
;                 if (xs) {
; #pragma unroll
;                     for (int bj = 0; bj < 2; ++bj) {
;                         const int n = colt + bj * 128 + wc * 32 + 8 * fq;
;                         const f32x4 x0 = *(const f32x4*)(xs + n), x1 = *(const f32x4*)(xs + n + 4);
;                         const f32x4 h0 = x0 + acc[ai][bj][m][0], h1 = x1 + acc[ai][bj][m][1];
;                         *(f32x4*)(yd + n) = h0; *(f32x4*)(yd + n + 4) = h1;
;                         ss += h0[0] * h0[0] + h0[1] * h0[1] + h0[2] * h0[2] + h0[3] * h0[3] + h1[0] * h1[0] + h1[1] * h1[1] + h1[2] * h1[2] + h1[3] * h1[3];
;                     }
;                 }
;                 ss += __shfl_xor(ss, 16); ss += __shfl_xor(ss, 32);
;                 if (xs && fq == 0) atomicAdd(p.rowss + R, ss);
.Lp3q_v2:
	s_add_i32 s87, s21, 128
	s_mul_hi_u32 s89, s87, 0x7e07e07f
	s_lshr_b32 s89, s89, 11
	s_mul_i32 vcc_lo, s89, 0x1040
	s_sub_i32 vcc_lo, s87, vcc_lo
	s_add_i32 vcc_lo, vcc_lo, -16
	s_lshl_b32 s89, s89, 12
	s_add_i32 s89, s89, vcc_lo
	s_cmp_lt_u32 vcc_lo, 0x1000
	s_cselect_b32 vcc_hi, 1, 0
	s_sub_i32 vcc_lo, s87, 0x4100
	s_cmp_ge_u32 s94, 65
	s_cselect_b32 s89, vcc_lo, s89
	s_cselect_b32 vcc_hi, 1, vcc_hi
	s_cmp_lg_u32 vcc_hi, 0
	s_cselect_b32 s89, s89, 0
	s_lshl_b32 s20, s89, 12
	s_lshl_b32 vcc_hi, vcc_hi, 0
	s_or_b32 s19, s19, vcc_hi
	s_add_i32 s87, s21, 144
	s_mul_hi_u32 s89, s87, 0x7e07e07f
	s_lshr_b32 s89, s89, 11
	s_mul_i32 vcc_lo, s89, 0x1040
	s_sub_i32 vcc_lo, s87, vcc_lo
	s_add_i32 vcc_lo, vcc_lo, -16
	s_lshl_b32 s89, s89, 12
	s_add_i32 s89, s89, vcc_lo
	s_cmp_lt_u32 vcc_lo, 0x1000
	s_cselect_b32 vcc_hi, 1, 0
	s_sub_i32 vcc_lo, s87, 0x4100
	s_cmp_ge_u32 s94, 65
	s_cselect_b32 s89, vcc_lo, s89
	s_cselect_b32 vcc_hi, 1, vcc_hi
	s_cmp_lg_u32 vcc_hi, 0
	s_cselect_b32 s89, s89, 0
	s_lshl_b32 s42, s89, 12
	s_lshl_b32 vcc_hi, vcc_hi, 1
	s_or_b32 s19, s19, vcc_hi
	s_add_i32 s87, s21, 160
	s_mul_hi_u32 s89, s87, 0x7e07e07f
	s_lshr_b32 s89, s89, 11
	s_mul_i32 vcc_lo, s89, 0x1040
	s_sub_i32 vcc_lo, s87, vcc_lo
	s_add_i32 vcc_lo, vcc_lo, -16
	s_lshl_b32 s89, s89, 12
	s_add_i32 s89, s89, vcc_lo
	s_cmp_lt_u32 vcc_lo, 0x1000
	s_cselect_b32 vcc_hi, 1, 0
	s_sub_i32 vcc_lo, s87, 0x4100
	s_cmp_ge_u32 s94, 65
	s_cselect_b32 s89, vcc_lo, s89
	s_cselect_b32 vcc_hi, 1, vcc_hi
	s_cmp_lg_u32 vcc_hi, 0
	s_cselect_b32 s89, s89, 0
	s_lshl_b32 s43, s89, 12
	s_lshl_b32 vcc_hi, vcc_hi, 2
	s_or_b32 s19, s19, vcc_hi
	s_add_i32 s87, s21, 176
	s_mul_hi_u32 s89, s87, 0x7e07e07f
	s_lshr_b32 s89, s89, 11
	s_mul_i32 vcc_lo, s89, 0x1040
	s_sub_i32 vcc_lo, s87, vcc_lo
	s_add_i32 vcc_lo, vcc_lo, -16
	s_lshl_b32 s89, s89, 12
	s_add_i32 s89, s89, vcc_lo
	s_cmp_lt_u32 vcc_lo, 0x1000
	s_cselect_b32 vcc_hi, 1, 0
	s_sub_i32 vcc_lo, s87, 0x4100
	s_cmp_ge_u32 s94, 65
	s_cselect_b32 s89, vcc_lo, s89
	s_cselect_b32 vcc_hi, 1, vcc_hi
	s_cmp_lg_u32 vcc_hi, 0
	s_cselect_b32 s89, s89, 0
	s_lshl_b32 s95, s89, 12
	s_lshl_b32 vcc_hi, vcc_hi, 3
	s_or_b32 s19, s19, vcc_hi
	s_waitcnt vmcnt(0)
	v_pk_add_f32 v[60:61], v[60:61], v[64:65]
	v_pk_add_f32 v[62:63], v[62:63], v[66:67]
	v_pk_add_f32 v[56:57], v[56:57], v[68:69]
	v_pk_add_f32 v[58:59], v[58:59], v[70:71]
	v_pk_mul_f32 v[172:173], v[60:61], v[60:61]
	v_pk_fma_f32 v[172:173], v[62:63], v[62:63], v[172:173]
	v_pk_fma_f32 v[172:173], v[56:57], v[56:57], v[172:173]
	v_pk_fma_f32 v[172:173], v[58:59], v[58:59], v[172:173]
	s_nop 0
	v_add_f32_e32 v168, v172, v173
	v_pk_add_f32 v[44:45], v[44:45], v[72:73]
	v_pk_add_f32 v[46:47], v[46:47], v[74:75]
	v_pk_add_f32 v[40:41], v[40:41], v[76:77]
	v_pk_add_f32 v[42:43], v[42:43], v[78:79]
	v_pk_mul_f32 v[172:173], v[44:45], v[44:45]
	v_pk_fma_f32 v[172:173], v[46:47], v[46:47], v[172:173]
	v_pk_fma_f32 v[172:173], v[40:41], v[40:41], v[172:173]
	v_pk_fma_f32 v[172:173], v[42:43], v[42:43], v[172:173]
	s_nop 0
	v_add_f32_e32 v169, v172, v173
	v_pk_add_f32 v[28:29], v[28:29], v[80:81]
	v_pk_add_f32 v[30:31], v[30:31], v[82:83]
	v_pk_add_f32 v[24:25], v[24:25], v[84:85]
	v_pk_add_f32 v[26:27], v[26:27], v[86:87]
	v_pk_mul_f32 v[172:173], v[28:29], v[28:29]
	v_pk_fma_f32 v[172:173], v[30:31], v[30:31], v[172:173]
	v_pk_fma_f32 v[172:173], v[24:25], v[24:25], v[172:173]
	v_pk_fma_f32 v[172:173], v[26:27], v[26:27], v[172:173]
	s_nop 0
	v_add_f32_e32 v170, v172, v173
	v_pk_add_f32 v[12:13], v[12:13], v[88:89]
	v_pk_add_f32 v[14:15], v[14:15], v[90:91]
	v_pk_add_f32 v[8:9], v[8:9], v[92:93]
	v_pk_add_f32 v[10:11], v[10:11], v[94:95]
	v_pk_mul_f32 v[172:173], v[12:13], v[12:13]
	v_pk_fma_f32 v[172:173], v[14:15], v[14:15], v[172:173]
	v_pk_fma_f32 v[172:173], v[8:9], v[8:9], v[172:173]
	v_pk_fma_f32 v[172:173], v[10:11], v[10:11], v[172:173]
	s_nop 0
	v_add_f32_e32 v171, v172, v173
	ds_bpermute_b32 v155, v153, v168
	ds_bpermute_b32 v156, v153, v169
	ds_bpermute_b32 v157, v153, v170
	ds_bpermute_b32 v132, v153, v171
	s_waitcnt lgkmcnt(0)
	v_add_f32_e32 v168, v168, v155
	v_add_f32_e32 v169, v169, v156
	v_add_f32_e32 v170, v170, v157
	v_add_f32_e32 v171, v171, v132
	ds_bpermute_b32 v155, v154, v168
	ds_bpermute_b32 v156, v154, v169
	ds_bpermute_b32 v157, v154, v170
	ds_bpermute_b32 v132, v154, v171
	s_waitcnt lgkmcnt(0)
	v_add_f32_e32 v168, v168, v155
	v_add_f32_e32 v169, v169, v156
	v_add_f32_e32 v170, v170, v157
	v_add_f32_e32 v171, v171, v132
	s_mov_b64 exec, s[36:37]
	s_bitcmp1_b32 s19, 0
	s_cbranch_scc0 .Lf3q2_at_q_0
	global_atomic_add_f32 v152, v168, s[60:61] offset:512

;     DI void operator()(const f32x4 (&acc)[2][2][4][2], const pg8::Unit& u, int wr, int wc, int fr, int fq) const {
;     ...
;                 const int R = u.pm * 256 + ai * 128 + wr * 64 + m * 16 + fr;
;                 const float* xs = nullptr; float* yd = nullptr;
;                 if (R < ROWS_P) { const int b = R / LPAD, t = R - b * LPAD; if (t >= NMETA && t < LP) { const size_t idx = ((size_t)b * SEQ + t - NMETA) * DM; xs = p.x_prompt + idx; yd = p.out + O_YP + idx; } }
;                 else { const size_t idx = (size_t)(R - ROWS_P) * DM; xs = p.x_sample + idx; yd = p.out + O_YS + idx; }
;                 float ss = 0.f;
;                 if (xs) {
; #pragma unroll
;                     for (int bj = 0; bj < 2; ++bj) {
;                         const int n = colt + bj * 128 + wc * 32 + 8 * fq;
;                         const f32x4 x0 = *(const f32x4*)(xs + n), x1 = *(const f32x4*)(xs + n + 4);
;                         const f32x4 h0 = x0 + acc[ai][bj][m][0], h1 = x1 + acc[ai][bj][m][1];
;                         *(f32x4*)(yd + n) = h0; *(f32x4*)(yd + n + 4) = h1;
;                         ss += h0[0] * h0[0] + h0[1] * h0[1] + h0[2] * h0[2] + h0[3] * h0[3] + h1[0] * h1[0] + h1[1] * h1[1] + h1[2] * h1[2] + h1[3] * h1[3];
;                     }
;                 }
;                 ss += __shfl_xor(ss, 16); ss += __shfl_xor(ss, 32);
;                 if (xs && fq == 0) atomicAdd(p.rowss + R, ss);
.Lp3q_v3:
	s_add_i32 s87, s21, 128
	s_mul_hi_u32 s89, s87, 0x7e07e07f
	s_lshr_b32 s89, s89, 11
	s_mul_i32 vcc_lo, s89, 0x1040
	s_sub_i32 vcc_lo, s87, vcc_lo
	s_add_i32 vcc_lo, vcc_lo, -16
	s_lshl_b32 s89, s89, 12
	s_add_i32 s89, s89, vcc_lo
	s_cmp_lt_u32 vcc_lo, 0x1000
	s_cselect_b32 vcc_hi, 1, 0
	s_sub_i32 vcc_lo, s87, 0x4100
	s_cmp_ge_u32 s94, 65
	s_cselect_b32 s89, vcc_lo, s89
	s_cselect_b32 vcc_hi, 1, vcc_hi
	s_cmp_lg_u32 vcc_hi, 0
	s_cselect_b32 s89, s89, 0
	s_lshl_b32 s20, s89, 12
	s_lshl_b32 vcc_hi, vcc_hi, 0
	s_or_b32 s19, s19, vcc_hi
	s_add_i32 s87, s21, 144
	s_mul_hi_u32 s89, s87, 0x7e07e07f
	s_lshr_b32 s89, s89, 11
	s_mul_i32 vcc_lo, s89, 0x1040
	s_sub_i32 vcc_lo, s87, vcc_lo
	s_add_i32 vcc_lo, vcc_lo, -16
	s_lshl_b32 s89, s89, 12
	s_add_i32 s89, s89, vcc_lo
	s_cmp_lt_u32 vcc_lo, 0x1000
	s_cselect_b32 vcc_hi, 1, 0
	s_sub_i32 vcc_lo, s87, 0x4100
	s_cmp_ge_u32 s94, 65
	s_cselect_b32 s89, vcc_lo, s89
	s_cselect_b32 vcc_hi, 1, vcc_hi
	s_cmp_lg_u32 vcc_hi, 0
	s_cselect_b32 s89, s89, 0
	s_lshl_b32 s42, s89, 12
	s_lshl_b32 vcc_hi, vcc_hi, 1
	s_or_b32 s19, s19, vcc_hi
	s_add_i32 s87, s21, 160
	s_mul_hi_u32 s89, s87, 0x7e07e07f
	s_lshr_b32 s89, s89, 11
	s_mul_i32 vcc_lo, s89, 0x1040
	s_sub_i32 vcc_lo, s87, vcc_lo
	s_add_i32 vcc_lo, vcc_lo, -16
	s_lshl_b32 s89, s89, 12
	s_add_i32 s89, s89, vcc_lo
	s_cmp_lt_u32 vcc_lo, 0x1000
	s_cselect_b32 vcc_hi, 1, 0
	s_sub_i32 vcc_lo, s87, 0x4100
	s_cmp_ge_u32 s94, 65
	s_cselect_b32 s89, vcc_lo, s89
	s_cselect_b32 vcc_hi, 1, vcc_hi
	s_cmp_lg_u32 vcc_hi, 0
	s_cselect_b32 s89, s89, 0
	s_lshl_b32 s43, s89, 12
	s_lshl_b32 vcc_hi, vcc_hi, 2
	s_or_b32 s19, s19, vcc_hi
	s_add_i32 s87, s21, 176
	s_mul_hi_u32 s89, s87, 0x7e07e07f
	s_lshr_b32 s89, s89, 11
	s_mul_i32 vcc_lo, s89, 0x1040
	s_sub_i32 vcc_lo, s87, vcc_lo
	s_add_i32 vcc_lo, vcc_lo, -16
	s_lshl_b32 s89, s89, 12
	s_add_i32 s89, s89, vcc_lo
	s_cmp_lt_u32 vcc_lo, 0x1000
	s_cselect_b32 vcc_hi, 1, 0
	s_sub_i32 vcc_lo, s87, 0x4100
	s_cmp_ge_u32 s94, 65
	s_cselect_b32 s89, vcc_lo, s89
	s_cselect_b32 vcc_hi, 1, vcc_hi
	s_cmp_lg_u32 vcc_hi, 0
	s_cselect_b32 s89, s89, 0
	s_lshl_b32 s95, s89, 12
	s_lshl_b32 vcc_hi, vcc_hi, 3
	s_or_b32 s19, s19, vcc_hi
	s_waitcnt vmcnt(0)
	v_pk_add_f32 v[52:53], v[52:53], v[64:65]
	v_pk_add_f32 v[54:55], v[54:55], v[66:67]
	v_pk_add_f32 v[48:49], v[48:49], v[68:69]
	v_pk_add_f32 v[50:51], v[50:51], v[70:71]
	v_pk_mul_f32 v[172:173], v[52:53], v[52:53]
	v_pk_fma_f32 v[172:173], v[54:55], v[54:55], v[172:173]
	v_pk_fma_f32 v[172:173], v[48:49], v[48:49], v[172:173]
	v_pk_fma_f32 v[172:173], v[50:51], v[50:51], v[172:173]
	s_nop 0
	v_add_f32_e32 v168, v172, v173
	v_pk_add_f32 v[36:37], v[36:37], v[72:73]
	v_pk_add_f32 v[38:39], v[38:39], v[74:75]
	v_pk_add_f32 v[32:33], v[32:33], v[76:77]
	v_pk_add_f32 v[34:35], v[34:35], v[78:79]
	v_pk_mul_f32 v[172:173], v[36:37], v[36:37]
	v_pk_fma_f32 v[172:173], v[38:39], v[38:39], v[172:173]
	v_pk_fma_f32 v[172:173], v[32:33], v[32:33], v[172:173]
	v_pk_fma_f32 v[172:173], v[34:35], v[34:35], v[172:173]
	s_nop 0
	v_add_f32_e32 v169, v172, v173
	v_pk_add_f32 v[20:21], v[20:21], v[80:81]
	v_pk_add_f32 v[22:23], v[22:23], v[82:83]
	v_pk_add_f32 v[16:17], v[16:17], v[84:85]
	v_pk_add_f32 v[18:19], v[18:19], v[86:87]
	v_pk_mul_f32 v[172:173], v[20:21], v[20:21]
	v_pk_fma_f32 v[172:173], v[22:23], v[22:23], v[172:173]
	v_pk_fma_f32 v[172:173], v[16:17], v[16:17], v[172:173]
	v_pk_fma_f32 v[172:173], v[18:19], v[18:19], v[172:173]
	s_nop 0
	v_add_f32_e32 v170, v172, v173
	v_pk_add_f32 v[4:5], v[4:5], v[88:89]
	v_pk_add_f32 v[6:7], v[6:7], v[90:91]
	v_pk_add_f32 v[0:1], v[0:1], v[92:93]
	v_pk_add_f32 v[2:3], v[2:3], v[94:95]
	v_pk_mul_f32 v[172:173], v[4:5], v[4:5]
	v_pk_fma_f32 v[172:173], v[6:7], v[6:7], v[172:173]
	v_pk_fma_f32 v[172:173], v[0:1], v[0:1], v[172:173]
	v_pk_fma_f32 v[172:173], v[2:3], v[2:3], v[172:173]
	s_nop 0
	v_add_f32_e32 v171, v172, v173
	ds_bpermute_b32 v155, v153, v168
	ds_bpermute_b32 v156, v153, v169
	ds_bpermute_b32 v157, v153, v170
	ds_bpermute_b32 v132, v153, v171
	s_waitcnt lgkmcnt(0)
	v_add_f32_e32 v168, v168, v155
	v_add_f32_e32 v169, v169, v156
	v_add_f32_e32 v170, v170, v157
	v_add_f32_e32 v171, v171, v132
	ds_bpermute_b32 v155, v154, v168
	ds_bpermute_b32 v156, v154, v169
	ds_bpermute_b32 v157, v154, v170
	ds_bpermute_b32 v132, v154, v171
	s_waitcnt lgkmcnt(0)
	v_add_f32_e32 v168, v168, v155
	v_add_f32_e32 v169, v169, v156
	v_add_f32_e32 v170, v170, v157
	v_add_f32_e32 v171, v171, v132
	s_mov_b64 exec, s[36:37]
	s_bitcmp1_b32 s19, 0
	s_cbranch_scc0 .Lf3q3_at_q_0
	global_atomic_add_f32 v152, v168, s[60:61] offset:512

; #define PG8_WAIT_V(n) asm volatile("s_waitcnt vmcnt(" #n ")" ::: "memory")
; template <class Epi, class Sched, bool ALIGN_EPI = false, bool SP2 = false>
; __device__ __forceinline__ void gemm_phase(PG8_LAS unsigned char* lds, const Gemm g, const Sched& S, const Epi& E) {
;     ...
;         for (int t = 0; t < nt; t += 2) {
;             const bool last = (t == nt - 2);
;             const char* a1 = cA + (size_t)(t + 1) * kstep;
;             const char* a2 = last ? nA : cA + (size_t)(t + 2) * kstep; const char* b2 = last ? nB : cB + (size_t)(t + 2) * kstep;
;             const char* a3 = a2 + kstep; const char* b3 = b2 + kstep;
;             if (last && has_next) S.a_ready(nxt);
;             if constexpr (SP2) {
;             PG8_LDB(B0, 0, 0); PG8_LDB(B1, 0, 1); PG8_SCHED; PG8_LDA(At, 0, 0); PG8_STAGE(PG8_SA(1, 1), a1 + hstep, voffA);
;             PG8_WAIT_V(8); PG8_WAIT_L(0); PG8_BAR; PG8_MMA(0, 0, At, B0); PG8_MMA(0, 1, At, B1); PG8_BAR; PG8_SCHED;
;             PG8_LDA(At, 0, 1); PG8_STAGE(PG8_SB(0, 0), b2, voffB); PG8_STAGE(PG8_SB(0, 1), b2 + hstep, voffB); PG8_STAGE(PG8_SA(0, 0), a2, voffA);
;             PG8_WAIT_V(8); PG8_WAIT_L(0); PG8_BAR; PG8_MMA(1, 0, At, B0); PG8_MMA(1, 1, At, B1); PG8_BAR; PG8_SCHED;
;             PG8_LDB(B0, 1, 0); PG8_LDB(B1, 1, 1); PG8_SCHED; PG8_LDA(At, 1, 0); PG8_STAGE(PG8_SA(0, 1), a2 + hstep, voffA);
;             PG8_WAIT_V(8); PG8_WAIT_L(0); PG8_BAR; PG8_MMA(0, 0, At, B0); PG8_MMA(0, 1, At, B1); PG8_BAR; PG8_SCHED;
;             PG8_LDA(At, 1, 1); PG8_STAGE(PG8_SB(1, 0), b3, voffB); PG8_STAGE(PG8_SB(1, 1), b3 + hstep, voffB); PG8_STAGE(PG8_SA(1, 0), a3, voffA);
;             PG8_WAIT_V(8); PG8_WAIT_L(0); PG8_BAR; PG8_MMA(1, 0, At, B0); PG8_MMA(1, 1, At, B1); PG8_BAR; PG8_SCHED;
;             } else {
;             PG8_LDB(B0, 0, 0); PG8_SCHED; PG8_LDA(At, 0, 0); PG8_STAGE(PG8_SA(1, 1), a1 + hstep, voffA);
;             PG8_WAIT_L(8); PG8_BAR; PG8_WAIT_L(0); PG8_MMA(0, 0, At, B0); PG8_BAR; PG8_SCHED;
;             PG8_LDB(B1, 0, 1); PG8_STAGE(PG8_SB(0, 0), b2, voffB);
;             PG8_BAR; PG8_WAIT_L(0); PG8_MMA(0, 1, At, B1); PG8_BAR;
;             PG8_LDA(At, 0, 1); PG8_STAGE(PG8_SA(0, 0), a2, voffA);
;             PG8_BAR; PG8_WAIT_L(0); PG8_MMA(1, 0, At, B0); PG8_BAR; PG8_SCHED;
;             PG8_STAGE(PG8_SB(0, 1), b2 + hstep, voffB);
;             PG8_WAIT_V(6); PG8_BAR; PG8_MMA(1, 1, At, B1); PG8_BAR;
.Lp3q_lean_q0:
	s_mov_b32 s22, s94
	s_mov_b32 s23, 0
	s_lshl_b64 s[22:23], s[22:23], 19
	s_add_u32 s22, s22, s70
	s_addc_u32 s23, s23, s71
	s_add_u32 s22, s22, 0x80
	s_addc_u32 s23, s23, 0
	s_mov_b32 s24, s42
	s_mov_b32 s25, 0
	s_lshl_b64 s[24:25], s[24:25], 19
	s_add_u32 s24, s24, s64
	s_addc_u32 s25, s25, s65
	s_add_u32 s24, s24, 0x80
	s_addc_u32 s25, s25, 0
	s_waitcnt vmcnt(0) lgkmcnt(0)
	s_barrier
	s_add_u32 s22, s22, 0x80
	s_addc_u32 s23, s23, 0
	s_add_u32 s24, s24, 0x80
	s_addc_u32 s25, s25, 0
	s_add_i32 m0, s0, 0x4000
	s_nop 0
	global_load_lds_dwordx4 v140, s[22:23]
	s_add_i32 m0, s0, 0x6000
	s_nop 0
	global_load_lds_dwordx4 v144, s[22:23]
	s_add_i32 m0, s0, 0x14000
	s_nop 0
	global_load_lds_dwordx4 v142, s[24:25]
	s_add_i32 m0, s0, 0x16000
	s_nop 0
	global_load_lds_dwordx4 v146, s[24:25]
	s_add_u32 s22, s22, 0x80
	s_addc_u32 s23, s23, 0
	s_add_u32 s24, s24, 0x80
	s_addc_u32 s25, s25, 0
	s_add_i32 m0, s0, 0xc000
	s_nop 0
	global_load_lds_dwordx4 v140, s[22:23]
	s_add_i32 m0, s0, 0xe000
	s_nop 0
	global_load_lds_dwordx4 v144, s[22:23]
	s_add_i32 m0, s0, 0x1c000
	s_nop 0
	global_load_lds_dwordx4 v142, s[24:25]
	s_add_i32 m0, s0, 0x1e000
	s_nop 0
	global_load_lds_dwordx4 v146, s[24:25]
	ds_read_b128 v[150:153], v160
	ds_read_b128 v[154:157], v160 offset:1024
	ds_read_b128 v[168:171], v160 offset:2048
	ds_read_b128 v[176:179], v160 offset:3072
	ds_read_b128 v[196:199], v162
	ds_read_b128 v[200:203], v162 offset:1024
	ds_read_b128 v[204:207], v162 offset:2048
	ds_read_b128 v[208:211], v162 offset:3072
	ds_read_b128 v[212:215], v162 offset:4096
	ds_read_b128 v[216:219], v162 offset:5120
	ds_read_b128 v[220:223], v162 offset:6144
	ds_read_b128 v[224:227], v162 offset:7168
	s_waitcnt lgkmcnt(0)
	v_mfma_f32_16x16x32_bf16 v[124:127], v[150:153], v[196:199], v[124:127]
	v_mfma_f32_16x16x32_bf16 v[120:123], v[168:171], v[196:199], v[120:123]
	v_mfma_f32_16x16x32_bf16 v[108:111], v[150:153], v[204:207], v[108:111]
	v_mfma_f32_16x16x32_bf16 v[104:107], v[168:171], v[204:207], v[104:107]
	v_mfma_f32_16x16x32_bf16 v[92:95], v[150:153], v[212:215], v[92:95]
	v_mfma_f32_16x16x32_bf16 v[88:91], v[168:171], v[212:215], v[88:91]
	v_mfma_f32_16x16x32_bf16 v[76:79], v[150:153], v[220:223], v[76:79]
	v_mfma_f32_16x16x32_bf16 v[72:75], v[168:171], v[220:223], v[72:75]
	v_mfma_f32_16x16x32_bf16 v[124:127], v[154:157], v[200:203], v[124:127]
	v_mfma_f32_16x16x32_bf16 v[120:123], v[176:179], v[200:203], v[120:123]
	v_mfma_f32_16x16x32_bf16 v[108:111], v[154:157], v[208:211], v[108:111]
	v_mfma_f32_16x16x32_bf16 v[104:107], v[176:179], v[208:211], v[104:107]
	v_mfma_f32_16x16x32_bf16 v[92:95], v[154:157], v[216:219], v[92:95]
	v_mfma_f32_16x16x32_bf16 v[88:91], v[176:179], v[216:219], v[88:91]
	v_mfma_f32_16x16x32_bf16 v[76:79], v[154:157], v[224:227], v[76:79]
	v_mfma_f32_16x16x32_bf16 v[72:75], v[176:179], v[224:227], v[72:75]
	s_waitcnt vmcnt(8)
	s_barrier
	ds_read_b128 v[150:153], v163
	ds_read_b128 v[154:157], v163 offset:1024
	ds_read_b128 v[168:171], v163 offset:2048
	ds_read_b128 v[176:179], v163 offset:3072
	ds_read_b128 v[196:199], v162 offset:32768
	ds_read_b128 v[200:203], v162 offset:33792
	ds_read_b128 v[204:207], v162 offset:34816
	ds_read_b128 v[208:211], v162 offset:35840
	ds_read_b128 v[212:215], v162 offset:36864
	ds_read_b128 v[216:219], v162 offset:37888
	ds_read_b128 v[220:223], v162 offset:38912
	ds_read_b128 v[224:227], v162 offset:39936
	s_add_u32 s22, s22, 0x80
	s_addc_u32 s23, s23, 0
	s_add_u32 s24, s24, 0x80
	s_addc_u32 s25, s25, 0
	s_mov_b32 m0, s0
	s_nop 0
	global_load_lds_dwordx4 v140, s[22:23]
	s_add_i32 m0, s0, 0x2000
	s_nop 0
	global_load_lds_dwordx4 v144, s[22:23]
	s_add_i32 m0, s0, 0x10000
	s_nop 0
	global_load_lds_dwordx4 v142, s[24:25]
	s_add_i32 m0, s0, 0x12000
	s_nop 0
	global_load_lds_dwordx4 v146, s[24:25]
	s_waitcnt lgkmcnt(0)
	v_mfma_f32_16x16x32_bf16 v[124:127], v[150:153], v[196:199], v[124:127]
	v_mfma_f32_16x16x32_bf16 v[120:123], v[168:171], v[196:199], v[120:123]
	v_mfma_f32_16x16x32_bf16 v[108:111], v[150:153], v[204:207], v[108:111]
	v_mfma_f32_16x16x32_bf16 v[104:107], v[168:171], v[204:207], v[104:107]
	v_mfma_f32_16x16x32_bf16 v[92:95], v[150:153], v[212:215], v[92:95]
	v_mfma_f32_16x16x32_bf16 v[88:91], v[168:171], v[212:215], v[88:91]
	v_mfma_f32_16x16x32_bf16 v[76:79], v[150:153], v[220:223], v[76:79]
	v_mfma_f32_16x16x32_bf16 v[72:75], v[168:171], v[220:223], v[72:75]
	v_mfma_f32_16x16x32_bf16 v[124:127], v[154:157], v[200:203], v[124:127]
	v_mfma_f32_16x16x32_bf16 v[120:123], v[176:179], v[200:203], v[120:123]
	v_mfma_f32_16x16x32_bf16 v[108:111], v[154:157], v[208:211], v[108:111]
	v_mfma_f32_16x16x32_bf16 v[104:107], v[176:179], v[208:211], v[104:107]
	v_mfma_f32_16x16x32_bf16 v[92:95], v[154:157], v[216:219], v[92:95]
	v_mfma_f32_16x16x32_bf16 v[88:91], v[176:179], v[216:219], v[88:91]
	v_mfma_f32_16x16x32_bf16 v[76:79], v[154:157], v[224:227], v[76:79]
	v_mfma_f32_16x16x32_bf16 v[72:75], v[176:179], v[224:227], v[72:75]
	s_waitcnt vmcnt(8)
	s_barrier
; #define PG8_WAIT_V(n) asm volatile("s_waitcnt vmcnt(" #n ")" ::: "memory")
; template <class Epi, class Sched, bool ALIGN_EPI = false, bool SP2 = false>
; __device__ __forceinline__ void gemm_phase(PG8_LAS unsigned char* lds, const Gemm g, const Sched& S, const Epi& E) {
;     ...
;         for (int t = 0; t < nt; t += 2) {
;             const bool last = (t == nt - 2);
;             const char* a1 = cA + (size_t)(t + 1) * kstep;
;             const char* a2 = last ? nA : cA + (size_t)(t + 2) * kstep; const char* b2 = last ? nB : cB + (size_t)(t + 2) * kstep;
;             const char* a3 = a2 + kstep; const char* b3 = b2 + kstep;
;             if (last && has_next) S.a_ready(nxt);
;             if constexpr (SP2) {
;             PG8_LDB(B0, 0, 0); PG8_LDB(B1, 0, 1); PG8_SCHED; PG8_LDA(At, 0, 0); PG8_STAGE(PG8_SA(1, 1), a1 + hstep, voffA);
;             PG8_WAIT_V(8); PG8_WAIT_L(0); PG8_BAR; PG8_MMA(0, 0, At, B0); PG8_MMA(0, 1, At, B1); PG8_BAR; PG8_SCHED;
;             PG8_LDA(At, 0, 1); PG8_STAGE(PG8_SB(0, 0), b2, voffB); PG8_STAGE(PG8_SB(0, 1), b2 + hstep, voffB); PG8_STAGE(PG8_SA(0, 0), a2, voffA);
;             PG8_WAIT_V(8); PG8_WAIT_L(0); PG8_BAR; PG8_MMA(1, 0, At, B0); PG8_MMA(1, 1, At, B1); PG8_BAR; PG8_SCHED;
;             PG8_LDB(B0, 1, 0); PG8_LDB(B1, 1, 1); PG8_SCHED; PG8_LDA(At, 1, 0); PG8_STAGE(PG8_SA(0, 1), a2 + hstep, voffA);
;             PG8_WAIT_V(8); PG8_WAIT_L(0); PG8_BAR; PG8_MMA(0, 0, At, B0); PG8_MMA(0, 1, At, B1); PG8_BAR; PG8_SCHED;
;             PG8_LDA(At, 1, 1); PG8_STAGE(PG8_SB(1, 0), b3, voffB); PG8_STAGE(PG8_SB(1, 1), b3 + hstep, voffB); PG8_STAGE(PG8_SA(1, 0), a3, voffA);
;             PG8_WAIT_V(8); PG8_WAIT_L(0); PG8_BAR; PG8_MMA(1, 0, At, B0); PG8_MMA(1, 1, At, B1); PG8_BAR; PG8_SCHED;
;             } else {
;             PG8_LDB(B0, 0, 0); PG8_SCHED; PG8_LDA(At, 0, 0); PG8_STAGE(PG8_SA(1, 1), a1 + hstep, voffA);
;             PG8_WAIT_L(8); PG8_BAR; PG8_WAIT_L(0); PG8_MMA(0, 0, At, B0); PG8_BAR; PG8_SCHED;
;             PG8_LDB(B1, 0, 1); PG8_STAGE(PG8_SB(0, 0), b2, voffB);
;             PG8_BAR; PG8_WAIT_L(0); PG8_MMA(0, 1, At, B1); PG8_BAR;
;             PG8_LDA(At, 0, 1); PG8_STAGE(PG8_SA(0, 0), a2, voffA);
;             PG8_BAR; PG8_WAIT_L(0); PG8_MMA(1, 0, At, B0); PG8_BAR; PG8_SCHED;
;             PG8_STAGE(PG8_SB(0, 1), b2 + hstep, voffB);
;             PG8_WAIT_V(6); PG8_BAR; PG8_MMA(1, 1, At, B1); PG8_BAR;
	ds_read_b128 v[150:153], v161
	ds_read_b128 v[154:157], v161 offset:1024
	ds_read_b128 v[168:171], v161 offset:2048
	ds_read_b128 v[176:179], v161 offset:3072
	ds_read_b128 v[196:199], v162 offset:16384
	ds_read_b128 v[200:203], v162 offset:17408
	ds_read_b128 v[204:207], v162 offset:18432
	ds_read_b128 v[208:211], v162 offset:19456
	ds_read_b128 v[212:215], v162 offset:20480
	ds_read_b128 v[216:219], v162 offset:21504
	ds_read_b128 v[220:223], v162 offset:22528
	ds_read_b128 v[224:227], v162 offset:23552
	s_add_u32 s22, s22, 0x80
	s_addc_u32 s23, s23, 0
	s_add_u32 s24, s24, 0x80
	s_addc_u32 s25, s25, 0
	s_add_i32 m0, s0, 0x8000
	s_nop 0
	global_load_lds_dwordx4 v140, s[22:23]
	s_add_i32 m0, s0, 0xa000
	s_nop 0
	global_load_lds_dwordx4 v144, s[22:23]
	s_add_i32 m0, s0, 0x18000
	s_nop 0
	global_load_lds_dwordx4 v142, s[24:25]
	s_add_i32 m0, s0, 0x1a000
	s_nop 0
	global_load_lds_dwordx4 v146, s[24:25]
	s_waitcnt lgkmcnt(0)
	v_mfma_f32_16x16x32_bf16 v[124:127], v[150:153], v[196:199], v[124:127]
	v_mfma_f32_16x16x32_bf16 v[120:123], v[168:171], v[196:199], v[120:123]
	v_mfma_f32_16x16x32_bf16 v[108:111], v[150:153], v[204:207], v[108:111]
	v_mfma_f32_16x16x32_bf16 v[104:107], v[168:171], v[204:207], v[104:107]
	v_mfma_f32_16x16x32_bf16 v[92:95], v[150:153], v[212:215], v[92:95]
	v_mfma_f32_16x16x32_bf16 v[88:91], v[168:171], v[212:215], v[88:91]
	v_mfma_f32_16x16x32_bf16 v[76:79], v[150:153], v[220:223], v[76:79]
	v_mfma_f32_16x16x32_bf16 v[72:75], v[168:171], v[220:223], v[72:75]
	v_mfma_f32_16x16x32_bf16 v[124:127], v[154:157], v[200:203], v[124:127]
	v_mfma_f32_16x16x32_bf16 v[120:123], v[176:179], v[200:203], v[120:123]
	v_mfma_f32_16x16x32_bf16 v[108:111], v[154:157], v[208:211], v[108:111]
	v_mfma_f32_16x16x32_bf16 v[104:107], v[176:179], v[208:211], v[104:107]
	v_mfma_f32_16x16x32_bf16 v[92:95], v[154:157], v[216:219], v[92:95]
	v_mfma_f32_16x16x32_bf16 v[88:91], v[176:179], v[216:219], v[88:91]
	v_mfma_f32_16x16x32_bf16 v[76:79], v[154:157], v[224:227], v[76:79]
	v_mfma_f32_16x16x32_bf16 v[72:75], v[176:179], v[224:227], v[72:75]
	s_waitcnt vmcnt(8)
	s_barrier
	ds_read_b128 v[150:153], v164
	ds_read_b128 v[154:157], v164 offset:1024
	ds_read_b128 v[168:171], v164 offset:2048
	ds_read_b128 v[176:179], v164 offset:3072
	ds_read_b128 v[196:199], v162 offset:49152
	ds_read_b128 v[200:203], v162 offset:50176
	ds_read_b128 v[204:207], v162 offset:51200
	ds_read_b128 v[208:211], v162 offset:52224
	ds_read_b128 v[212:215], v162 offset:53248
	ds_read_b128 v[216:219], v162 offset:54272
	ds_read_b128 v[220:223], v162 offset:55296
	ds_read_b128 v[224:227], v162 offset:56320
	s_add_u32 s22, s22, 0x80
	s_addc_u32 s23, s23, 0
	s_add_u32 s24, s24, 0x80
	s_addc_u32 s25, s25, 0
	s_add_i32 m0, s0, 0x4000
	s_nop 0
	global_load_lds_dwordx4 v140, s[22:23]
	s_add_i32 m0, s0, 0x6000
	s_nop 0
	global_load_lds_dwordx4 v144, s[22:23]
	s_add_i32 m0, s0, 0x14000
	s_nop 0
	global_load_lds_dwordx4 v142, s[24:25]
	s_add_i32 m0, s0, 0x16000
	s_nop 0
	global_load_lds_dwordx4 v146, s[24:25]
	s_waitcnt lgkmcnt(0)
	v_mfma_f32_16x16x32_bf16 v[124:127], v[150:153], v[196:199], v[124:127]
	v_mfma_f32_16x16x32_bf16 v[120:123], v[168:171], v[196:199], v[120:123]
	v_mfma_f32_16x16x32_bf16 v[108:111], v[150:153], v[204:207], v[108:111]
	v_mfma_f32_16x16x32_bf16 v[104:107], v[168:171], v[204:207], v[104:107]
	v_mfma_f32_16x16x32_bf16 v[92:95], v[150:153], v[212:215], v[92:95]
	v_mfma_f32_16x16x32_bf16 v[88:91], v[168:171], v[212:215], v[88:91]
	v_mfma_f32_16x16x32_bf16 v[76:79], v[150:153], v[220:223], v[76:79]
	v_mfma_f32_16x16x32_bf16 v[72:75], v[168:171], v[220:223], v[72:75]
	v_mfma_f32_16x16x32_bf16 v[124:127], v[154:157], v[200:203], v[124:127]
	v_mfma_f32_16x16x32_bf16 v[120:123], v[176:179], v[200:203], v[120:123]
	v_mfma_f32_16x16x32_bf16 v[108:111], v[154:157], v[208:211], v[108:111]
	v_mfma_f32_16x16x32_bf16 v[104:107], v[176:179], v[208:211], v[104:107]
	v_mfma_f32_16x16x32_bf16 v[92:95], v[154:157], v[216:219], v[92:95]
	v_mfma_f32_16x16x32_bf16 v[88:91], v[176:179], v[216:219], v[88:91]
	v_mfma_f32_16x16x32_bf16 v[76:79], v[154:157], v[224:227], v[76:79]
	v_mfma_f32_16x16x32_bf16 v[72:75], v[176:179], v[224:227], v[72:75]
	s_waitcnt vmcnt(8)
	s_barrier
	ds_read_b128 v[150:153], v160
	ds_read_b128 v[154:157], v160 offset:1024
	ds_read_b128 v[168:171], v160 offset:2048
	ds_read_b128 v[176:179], v160 offset:3072
	ds_read_b128 v[196:199], v162
	ds_read_b128 v[200:203], v162 offset:1024
	ds_read_b128 v[204:207], v162 offset:2048
	ds_read_b128 v[208:211], v162 offset:3072
	ds_read_b128 v[212:215], v162 offset:4096
	ds_read_b128 v[216:219], v162 offset:5120
	ds_read_b128 v[220:223], v162 offset:6144
	ds_read_b128 v[224:227], v162 offset:7168
	s_add_u32 s22, s22, 0x80
	s_addc_u32 s23, s23, 0
	s_add_u32 s24, s24, 0x80
	s_addc_u32 s25, s25, 0
	s_add_i32 m0, s0, 0xc000
	s_nop 0
	global_load_lds_dwordx4 v140, s[22:23]
	s_add_i32 m0, s0, 0xe000
	s_nop 0
	global_load_lds_dwordx4 v144, s[22:23]
	s_add_i32 m0, s0, 0x1c000
	s_nop 0
	global_load_lds_dwordx4 v142, s[24:25]
	s_add_i32 m0, s0, 0x1e000
	s_nop 0
	global_load_lds_dwordx4 v146, s[24:25]
	s_waitcnt lgkmcnt(0)
	v_mfma_f32_16x16x32_bf16 v[124:127], v[150:153], v[196:199], v[124:127]
	v_mfma_f32_16x16x32_bf16 v[120:123], v[168:171], v[196:199], v[120:123]
	v_mfma_f32_16x16x32_bf16 v[108:111], v[150:153], v[204:207], v[108:111]
	v_mfma_f32_16x16x32_bf16 v[104:107], v[168:171], v[204:207], v[104:107]
	v_mfma_f32_16x16x32_bf16 v[92:95], v[150:153], v[212:215], v[92:95]
	v_mfma_f32_16x16x32_bf16 v[88:91], v[168:171], v[212:215], v[88:91]
	v_mfma_f32_16x16x32_bf16 v[76:79], v[150:153], v[220:223], v[76:79]
	v_mfma_f32_16x16x32_bf16 v[72:75], v[168:171], v[220:223], v[72:75]
	v_mfma_f32_16x16x32_bf16 v[124:127], v[154:157], v[200:203], v[124:127]
	v_mfma_f32_16x16x32_bf16 v[120:123], v[176:179], v[200:203], v[120:123]
	v_mfma_f32_16x16x32_bf16 v[108:111], v[154:157], v[208:211], v[108:111]
	v_mfma_f32_16x16x32_bf16 v[104:107], v[176:179], v[208:211], v[104:107]
	v_mfma_f32_16x16x32_bf16 v[92:95], v[154:157], v[216:219], v[92:95]
	v_mfma_f32_16x16x32_bf16 v[88:91], v[176:179], v[216:219], v[88:91]
	v_mfma_f32_16x16x32_bf16 v[76:79], v[154:157], v[224:227], v[76:79]
	v_mfma_f32_16x16x32_bf16 v[72:75], v[176:179], v[224:227], v[72:75]
	s_waitcnt vmcnt(8)
	s_barrier
; #define PG8_WAIT_V(n) asm volatile("s_waitcnt vmcnt(" #n ")" ::: "memory")
; template <class Epi, class Sched, bool ALIGN_EPI = false, bool SP2 = false>
; __device__ __forceinline__ void gemm_phase(PG8_LAS unsigned char* lds, const Gemm g, const Sched& S, const Epi& E) {
;     ...
;         for (int t = 0; t < nt; t += 2) {
;             const bool last = (t == nt - 2);
;             const char* a1 = cA + (size_t)(t + 1) * kstep;
;             const char* a2 = last ? nA : cA + (size_t)(t + 2) * kstep; const char* b2 = last ? nB : cB + (size_t)(t + 2) * kstep;
;             const char* a3 = a2 + kstep; const char* b3 = b2 + kstep;
;             if (last && has_next) S.a_ready(nxt);
;             if constexpr (SP2) {
;             PG8_LDB(B0, 0, 0); PG8_LDB(B1, 0, 1); PG8_SCHED; PG8_LDA(At, 0, 0); PG8_STAGE(PG8_SA(1, 1), a1 + hstep, voffA);
;             PG8_WAIT_V(8); PG8_WAIT_L(0); PG8_BAR; PG8_MMA(0, 0, At, B0); PG8_MMA(0, 1, At, B1); PG8_BAR; PG8_SCHED;
;             PG8_LDA(At, 0, 1); PG8_STAGE(PG8_SB(0, 0), b2, voffB); PG8_STAGE(PG8_SB(0, 1), b2 + hstep, voffB); PG8_STAGE(PG8_SA(0, 0), a2, voffA);
;             PG8_WAIT_V(8); PG8_WAIT_L(0); PG8_BAR; PG8_MMA(1, 0, At, B0); PG8_MMA(1, 1, At, B1); PG8_BAR; PG8_SCHED;
;             PG8_LDB(B0, 1, 0); PG8_LDB(B1, 1, 1); PG8_SCHED; PG8_LDA(At, 1, 0); PG8_STAGE(PG8_SA(0, 1), a2 + hstep, voffA);
;             PG8_WAIT_V(8); PG8_WAIT_L(0); PG8_BAR; PG8_MMA(0, 0, At, B0); PG8_MMA(0, 1, At, B1); PG8_BAR; PG8_SCHED;
;             PG8_LDA(At, 1, 1); PG8_STAGE(PG8_SB(1, 0), b3, voffB); PG8_STAGE(PG8_SB(1, 1), b3 + hstep, voffB); PG8_STAGE(PG8_SA(1, 0), a3, voffA);
;             PG8_WAIT_V(8); PG8_WAIT_L(0); PG8_BAR; PG8_MMA(1, 0, At, B0); PG8_MMA(1, 1, At, B1); PG8_BAR; PG8_SCHED;
;             } else {
;             PG8_LDB(B0, 0, 0); PG8_SCHED; PG8_LDA(At, 0, 0); PG8_STAGE(PG8_SA(1, 1), a1 + hstep, voffA);
;             PG8_WAIT_L(8); PG8_BAR; PG8_WAIT_L(0); PG8_MMA(0, 0, At, B0); PG8_BAR; PG8_SCHED;
;             PG8_LDB(B1, 0, 1); PG8_STAGE(PG8_SB(0, 0), b2, voffB);
;             PG8_BAR; PG8_WAIT_L(0); PG8_MMA(0, 1, At, B1); PG8_BAR;
;             PG8_LDA(At, 0, 1); PG8_STAGE(PG8_SA(0, 0), a2, voffA);
;             PG8_BAR; PG8_WAIT_L(0); PG8_MMA(1, 0, At, B0); PG8_BAR; PG8_SCHED;
;             PG8_STAGE(PG8_SB(0, 1), b2 + hstep, voffB);
;             PG8_WAIT_V(6); PG8_BAR; PG8_MMA(1, 1, At, B1); PG8_BAR;
	ds_read_b128 v[150:153], v163
	ds_read_b128 v[154:157], v163 offset:1024
	ds_read_b128 v[168:171], v163 offset:2048
	ds_read_b128 v[176:179], v163 offset:3072
	ds_read_b128 v[196:199], v162 offset:32768
	ds_read_b128 v[200:203], v162 offset:33792
	ds_read_b128 v[204:207], v162 offset:34816
	ds_read_b128 v[208:211], v162 offset:35840
	ds_read_b128 v[212:215], v162 offset:36864
	ds_read_b128 v[216:219], v162 offset:37888
	ds_read_b128 v[220:223], v162 offset:38912
	ds_read_b128 v[224:227], v162 offset:39936
	s_add_u32 s22, s22, 0x80
	s_addc_u32 s23, s23, 0
	s_add_u32 s24, s24, 0x80
	s_addc_u32 s25, s25, 0
	s_mov_b32 m0, s0
	s_nop 0
	global_load_lds_dwordx4 v140, s[22:23]
	s_add_i32 m0, s0, 0x2000
	s_nop 0
	global_load_lds_dwordx4 v144, s[22:23]
	s_add_i32 m0, s0, 0x10000
	s_nop 0
	global_load_lds_dwordx4 v142, s[24:25]
	s_add_i32 m0, s0, 0x12000
	s_nop 0
	global_load_lds_dwordx4 v146, s[24:25]
	s_waitcnt lgkmcnt(0)
	v_mfma_f32_16x16x32_bf16 v[124:127], v[150:153], v[196:199], v[124:127]
	v_mfma_f32_16x16x32_bf16 v[120:123], v[168:171], v[196:199], v[120:123]
	v_mfma_f32_16x16x32_bf16 v[108:111], v[150:153], v[204:207], v[108:111]
	v_mfma_f32_16x16x32_bf16 v[104:107], v[168:171], v[204:207], v[104:107]
	v_mfma_f32_16x16x32_bf16 v[92:95], v[150:153], v[212:215], v[92:95]
	v_mfma_f32_16x16x32_bf16 v[88:91], v[168:171], v[212:215], v[88:91]
	v_mfma_f32_16x16x32_bf16 v[76:79], v[150:153], v[220:223], v[76:79]
	v_mfma_f32_16x16x32_bf16 v[72:75], v[168:171], v[220:223], v[72:75]
	v_mfma_f32_16x16x32_bf16 v[124:127], v[154:157], v[200:203], v[124:127]
	v_mfma_f32_16x16x32_bf16 v[120:123], v[176:179], v[200:203], v[120:123]
	v_mfma_f32_16x16x32_bf16 v[108:111], v[154:157], v[208:211], v[108:111]
	v_mfma_f32_16x16x32_bf16 v[104:107], v[176:179], v[208:211], v[104:107]
	v_mfma_f32_16x16x32_bf16 v[92:95], v[154:157], v[216:219], v[92:95]
	v_mfma_f32_16x16x32_bf16 v[88:91], v[176:179], v[216:219], v[88:91]
	v_mfma_f32_16x16x32_bf16 v[76:79], v[154:157], v[224:227], v[76:79]
	v_mfma_f32_16x16x32_bf16 v[72:75], v[176:179], v[224:227], v[72:75]
	s_waitcnt vmcnt(8)
	s_barrier
	ds_read_b128 v[150:153], v161
	ds_read_b128 v[154:157], v161 offset:1024
	ds_read_b128 v[168:171], v161 offset:2048
	ds_read_b128 v[176:179], v161 offset:3072
	ds_read_b128 v[196:199], v162 offset:16384
	ds_read_b128 v[200:203], v162 offset:17408
	ds_read_b128 v[204:207], v162 offset:18432
	ds_read_b128 v[208:211], v162 offset:19456
	ds_read_b128 v[212:215], v162 offset:20480
	ds_read_b128 v[216:219], v162 offset:21504
	ds_read_b128 v[220:223], v162 offset:22528
	ds_read_b128 v[224:227], v162 offset:23552
	s_add_u32 s22, s22, 0x80
	s_addc_u32 s23, s23, 0
	s_add_u32 s24, s24, 0x80
	s_addc_u32 s25, s25, 0
	s_add_i32 m0, s0, 0x8000
	s_nop 0
	global_load_lds_dwordx4 v140, s[22:23]
	s_add_i32 m0, s0, 0xa000
	s_nop 0
	global_load_lds_dwordx4 v144, s[22:23]
	s_add_i32 m0, s0, 0x18000
	s_nop 0
	global_load_lds_dwordx4 v142, s[24:25]
	s_add_i32 m0, s0, 0x1a000
	s_nop 0
	global_load_lds_dwordx4 v146, s[24:25]
	s_waitcnt lgkmcnt(0)
	v_mfma_f32_16x16x32_bf16 v[124:127], v[150:153], v[196:199], v[124:127]
	v_mfma_f32_16x16x32_bf16 v[120:123], v[168:171], v[196:199], v[120:123]
	v_mfma_f32_16x16x32_bf16 v[108:111], v[150:153], v[204:207], v[108:111]
	v_mfma_f32_16x16x32_bf16 v[104:107], v[168:171], v[204:207], v[104:107]
	v_mfma_f32_16x16x32_bf16 v[92:95], v[150:153], v[212:215], v[92:95]
	v_mfma_f32_16x16x32_bf16 v[88:91], v[168:171], v[212:215], v[88:91]
	v_mfma_f32_16x16x32_bf16 v[76:79], v[150:153], v[220:223], v[76:79]
	v_mfma_f32_16x16x32_bf16 v[72:75], v[168:171], v[220:223], v[72:75]
	v_mfma_f32_16x16x32_bf16 v[124:127], v[154:157], v[200:203], v[124:127]
	v_mfma_f32_16x16x32_bf16 v[120:123], v[176:179], v[200:203], v[120:123]
	v_mfma_f32_16x16x32_bf16 v[108:111], v[154:157], v[208:211], v[108:111]
	v_mfma_f32_16x16x32_bf16 v[104:107], v[176:179], v[208:211], v[104:107]
	v_mfma_f32_16x16x32_bf16 v[92:95], v[154:157], v[216:219], v[92:95]
	v_mfma_f32_16x16x32_bf16 v[88:91], v[176:179], v[216:219], v[88:91]
	v_mfma_f32_16x16x32_bf16 v[76:79], v[154:157], v[224:227], v[76:79]
	v_mfma_f32_16x16x32_bf16 v[72:75], v[176:179], v[224:227], v[72:75]
	s_waitcnt vmcnt(8)
	s_barrier
	ds_read_b128 v[150:153], v164
	ds_read_b128 v[154:157], v164 offset:1024
	ds_read_b128 v[168:171], v164 offset:2048
	ds_read_b128 v[176:179], v164 offset:3072
	ds_read_b128 v[196:199], v162 offset:49152
	ds_read_b128 v[200:203], v162 offset:50176
	ds_read_b128 v[204:207], v162 offset:51200
	ds_read_b128 v[208:211], v162 offset:52224
	ds_read_b128 v[212:215], v162 offset:53248
	ds_read_b128 v[216:219], v162 offset:54272
	ds_read_b128 v[220:223], v162 offset:55296
	ds_read_b128 v[224:227], v162 offset:56320
	s_add_u32 s22, s22, 0x80
	s_addc_u32 s23, s23, 0
	s_add_u32 s24, s24, 0x80
	s_addc_u32 s25, s25, 0
	s_add_i32 m0, s0, 0x4000
	s_nop 0
	global_load_lds_dwordx4 v140, s[22:23]
	s_add_i32 m0, s0, 0x6000
	s_nop 0
	global_load_lds_dwordx4 v144, s[22:23]
	s_add_i32 m0, s0, 0x14000
	s_nop 0
	global_load_lds_dwordx4 v142, s[24:25]
	s_add_i32 m0, s0, 0x16000
	s_nop 0
	global_load_lds_dwordx4 v146, s[24:25]
	s_waitcnt lgkmcnt(0)
	v_mfma_f32_16x16x32_bf16 v[124:127], v[150:153], v[196:199], v[124:127]
	v_mfma_f32_16x16x32_bf16 v[120:123], v[168:171], v[196:199], v[120:123]
	v_mfma_f32_16x16x32_bf16 v[108:111], v[150:153], v[204:207], v[108:111]
	v_mfma_f32_16x16x32_bf16 v[104:107], v[168:171], v[204:207], v[104:107]
	v_mfma_f32_16x16x32_bf16 v[92:95], v[150:153], v[212:215], v[92:95]
	v_mfma_f32_16x16x32_bf16 v[88:91], v[168:171], v[212:215], v[88:91]
	v_mfma_f32_16x16x32_bf16 v[76:79], v[150:153], v[220:223], v[76:79]
	v_mfma_f32_16x16x32_bf16 v[72:75], v[168:171], v[220:223], v[72:75]
	v_mfma_f32_16x16x32_bf16 v[124:127], v[154:157], v[200:203], v[124:127]
	v_mfma_f32_16x16x32_bf16 v[120:123], v[176:179], v[200:203], v[120:123]
	v_mfma_f32_16x16x32_bf16 v[108:111], v[154:157], v[208:211], v[108:111]
	v_mfma_f32_16x16x32_bf16 v[104:107], v[176:179], v[208:211], v[104:107]
	v_mfma_f32_16x16x32_bf16 v[92:95], v[154:157], v[216:219], v[92:95]
	v_mfma_f32_16x16x32_bf16 v[88:91], v[176:179], v[216:219], v[88:91]
	v_mfma_f32_16x16x32_bf16 v[76:79], v[154:157], v[224:227], v[76:79]
	v_mfma_f32_16x16x32_bf16 v[72:75], v[176:179], v[224:227], v[72:75]
	s_waitcnt vmcnt(8)
	s_barrier
; #define PG8_WAIT_V(n) asm volatile("s_waitcnt vmcnt(" #n ")" ::: "memory")
; template <class Epi, class Sched, bool ALIGN_EPI = false, bool SP2 = false>
; __device__ __forceinline__ void gemm_phase(PG8_LAS unsigned char* lds, const Gemm g, const Sched& S, const Epi& E) {
;     ...
;         for (int t = 0; t < nt; t += 2) {
;             const bool last = (t == nt - 2);
;             const char* a1 = cA + (size_t)(t + 1) * kstep;
;             const char* a2 = last ? nA : cA + (size_t)(t + 2) * kstep; const char* b2 = last ? nB : cB + (size_t)(t + 2) * kstep;
;             const char* a3 = a2 + kstep; const char* b3 = b2 + kstep;
;             if (last && has_next) S.a_ready(nxt);
;             if constexpr (SP2) {
;             PG8_LDB(B0, 0, 0); PG8_LDB(B1, 0, 1); PG8_SCHED; PG8_LDA(At, 0, 0); PG8_STAGE(PG8_SA(1, 1), a1 + hstep, voffA);
;             PG8_WAIT_V(8); PG8_WAIT_L(0); PG8_BAR; PG8_MMA(0, 0, At, B0); PG8_MMA(0, 1, At, B1); PG8_BAR; PG8_SCHED;
;             PG8_LDA(At, 0, 1); PG8_STAGE(PG8_SB(0, 0), b2, voffB); PG8_STAGE(PG8_SB(0, 1), b2 + hstep, voffB); PG8_STAGE(PG8_SA(0, 0), a2, voffA);
;             PG8_WAIT_V(8); PG8_WAIT_L(0); PG8_BAR; PG8_MMA(1, 0, At, B0); PG8_MMA(1, 1, At, B1); PG8_BAR; PG8_SCHED;
;             PG8_LDB(B0, 1, 0); PG8_LDB(B1, 1, 1); PG8_SCHED; PG8_LDA(At, 1, 0); PG8_STAGE(PG8_SA(0, 1), a2 + hstep, voffA);
;             PG8_WAIT_V(8); PG8_WAIT_L(0); PG8_BAR; PG8_MMA(0, 0, At, B0); PG8_MMA(0, 1, At, B1); PG8_BAR; PG8_SCHED;
;             PG8_LDA(At, 1, 1); PG8_STAGE(PG8_SB(1, 0), b3, voffB); PG8_STAGE(PG8_SB(1, 1), b3 + hstep, voffB); PG8_STAGE(PG8_SA(1, 0), a3, voffA);
;             PG8_WAIT_V(8); PG8_WAIT_L(0); PG8_BAR; PG8_MMA(1, 0, At, B0); PG8_MMA(1, 1, At, B1); PG8_BAR; PG8_SCHED;
;             } else {
;             PG8_LDB(B0, 0, 0); PG8_SCHED; PG8_LDA(At, 0, 0); PG8_STAGE(PG8_SA(1, 1), a1 + hstep, voffA);
;             PG8_WAIT_L(8); PG8_BAR; PG8_WAIT_L(0); PG8_MMA(0, 0, At, B0); PG8_BAR; PG8_SCHED;
;             PG8_LDB(B1, 0, 1); PG8_STAGE(PG8_SB(0, 0), b2, voffB);
;             PG8_BAR; PG8_WAIT_L(0); PG8_MMA(0, 1, At, B1); PG8_BAR;
;             PG8_LDA(At, 0, 1); PG8_STAGE(PG8_SA(0, 0), a2, voffA);
;             PG8_BAR; PG8_WAIT_L(0); PG8_MMA(1, 0, At, B0); PG8_BAR; PG8_SCHED;
;             PG8_STAGE(PG8_SB(0, 1), b2 + hstep, voffB);
;             PG8_WAIT_V(6); PG8_BAR; PG8_MMA(1, 1, At, B1); PG8_BAR;
	ds_read_b128 v[150:153], v160
	ds_read_b128 v[154:157], v160 offset:1024
	ds_read_b128 v[168:171], v160 offset:2048
	ds_read_b128 v[176:179], v160 offset:3072
	ds_read_b128 v[196:199], v162
	ds_read_b128 v[200:203], v162 offset:1024
	ds_read_b128 v[204:207], v162 offset:2048
	ds_read_b128 v[208:211], v162 offset:3072
	ds_read_b128 v[212:215], v162 offset:4096
	ds_read_b128 v[216:219], v162 offset:5120
	ds_read_b128 v[220:223], v162 offset:6144
	ds_read_b128 v[224:227], v162 offset:7168
	s_add_u32 s22, s22, 0x80
	s_addc_u32 s23, s23, 0
	s_add_u32 s24, s24, 0x80
	s_addc_u32 s25, s25, 0
	s_add_i32 m0, s0, 0xc000
	s_nop 0
	global_load_lds_dwordx4 v140, s[22:23]
	s_add_i32 m0, s0, 0xe000
	s_nop 0
	global_load_lds_dwordx4 v144, s[22:23]
	s_add_i32 m0, s0, 0x1c000
	s_nop 0
	global_load_lds_dwordx4 v142, s[24:25]
	s_add_i32 m0, s0, 0x1e000
	s_nop 0
	global_load_lds_dwordx4 v146, s[24:25]
	s_waitcnt lgkmcnt(0)
	v_mfma_f32_16x16x32_bf16 v[124:127], v[150:153], v[196:199], v[124:127]
	v_mfma_f32_16x16x32_bf16 v[120:123], v[168:171], v[196:199], v[120:123]
	v_mfma_f32_16x16x32_bf16 v[108:111], v[150:153], v[204:207], v[108:111]
	v_mfma_f32_16x16x32_bf16 v[104:107], v[168:171], v[204:207], v[104:107]
	v_mfma_f32_16x16x32_bf16 v[92:95], v[150:153], v[212:215], v[92:95]
	v_mfma_f32_16x16x32_bf16 v[88:91], v[168:171], v[212:215], v[88:91]
	v_mfma_f32_16x16x32_bf16 v[76:79], v[150:153], v[220:223], v[76:79]
	v_mfma_f32_16x16x32_bf16 v[72:75], v[168:171], v[220:223], v[72:75]
	v_mfma_f32_16x16x32_bf16 v[124:127], v[154:157], v[200:203], v[124:127]
	v_mfma_f32_16x16x32_bf16 v[120:123], v[176:179], v[200:203], v[120:123]
	v_mfma_f32_16x16x32_bf16 v[108:111], v[154:157], v[208:211], v[108:111]
	v_mfma_f32_16x16x32_bf16 v[104:107], v[176:179], v[208:211], v[104:107]
	v_mfma_f32_16x16x32_bf16 v[92:95], v[154:157], v[216:219], v[92:95]
	v_mfma_f32_16x16x32_bf16 v[88:91], v[176:179], v[216:219], v[88:91]
	v_mfma_f32_16x16x32_bf16 v[76:79], v[154:157], v[224:227], v[76:79]
	v_mfma_f32_16x16x32_bf16 v[72:75], v[176:179], v[224:227], v[72:75]
	s_waitcnt vmcnt(8)
	s_barrier
	ds_read_b128 v[150:153], v163
	ds_read_b128 v[154:157], v163 offset:1024
	ds_read_b128 v[168:171], v163 offset:2048
	ds_read_b128 v[176:179], v163 offset:3072
	ds_read_b128 v[196:199], v162 offset:32768
	ds_read_b128 v[200:203], v162 offset:33792
	ds_read_b128 v[204:207], v162 offset:34816
	ds_read_b128 v[208:211], v162 offset:35840
	ds_read_b128 v[212:215], v162 offset:36864
	ds_read_b128 v[216:219], v162 offset:37888
	ds_read_b128 v[220:223], v162 offset:38912
	ds_read_b128 v[224:227], v162 offset:39936
	s_add_u32 s22, s22, 0x80
	s_addc_u32 s23, s23, 0
	s_add_u32 s24, s24, 0x80
	s_addc_u32 s25, s25, 0
	s_mov_b32 m0, s0
	s_nop 0
	global_load_lds_dwordx4 v140, s[22:23]
	s_add_i32 m0, s0, 0x2000
	s_nop 0
	global_load_lds_dwordx4 v144, s[22:23]
	s_add_i32 m0, s0, 0x10000
	s_nop 0
	global_load_lds_dwordx4 v142, s[24:25]
	s_add_i32 m0, s0, 0x12000
	s_nop 0
	global_load_lds_dwordx4 v146, s[24:25]
	s_waitcnt lgkmcnt(0)
	v_mfma_f32_16x16x32_bf16 v[124:127], v[150:153], v[196:199], v[124:127]
	v_mfma_f32_16x16x32_bf16 v[120:123], v[168:171], v[196:199], v[120:123]
	v_mfma_f32_16x16x32_bf16 v[108:111], v[150:153], v[204:207], v[108:111]
	v_mfma_f32_16x16x32_bf16 v[104:107], v[168:171], v[204:207], v[104:107]
	v_mfma_f32_16x16x32_bf16 v[92:95], v[150:153], v[212:215], v[92:95]
	v_mfma_f32_16x16x32_bf16 v[88:91], v[168:171], v[212:215], v[88:91]
	v_mfma_f32_16x16x32_bf16 v[76:79], v[150:153], v[220:223], v[76:79]
	v_mfma_f32_16x16x32_bf16 v[72:75], v[168:171], v[220:223], v[72:75]
	v_mfma_f32_16x16x32_bf16 v[124:127], v[154:157], v[200:203], v[124:127]
	v_mfma_f32_16x16x32_bf16 v[120:123], v[176:179], v[200:203], v[120:123]
	v_mfma_f32_16x16x32_bf16 v[108:111], v[154:157], v[208:211], v[108:111]
	v_mfma_f32_16x16x32_bf16 v[104:107], v[176:179], v[208:211], v[104:107]
	v_mfma_f32_16x16x32_bf16 v[92:95], v[154:157], v[216:219], v[92:95]
	v_mfma_f32_16x16x32_bf16 v[88:91], v[176:179], v[216:219], v[88:91]
	v_mfma_f32_16x16x32_bf16 v[76:79], v[154:157], v[224:227], v[76:79]
	v_mfma_f32_16x16x32_bf16 v[72:75], v[176:179], v[224:227], v[72:75]
	s_waitcnt vmcnt(8)
	s_barrier
	ds_read_b128 v[150:153], v161
	ds_read_b128 v[154:157], v161 offset:1024
	ds_read_b128 v[168:171], v161 offset:2048
	ds_read_b128 v[176:179], v161 offset:3072
	ds_read_b128 v[196:199], v162 offset:16384
	ds_read_b128 v[200:203], v162 offset:17408
	ds_read_b128 v[204:207], v162 offset:18432
	ds_read_b128 v[208:211], v162 offset:19456
	ds_read_b128 v[212:215], v162 offset:20480
	ds_read_b128 v[216:219], v162 offset:21504
	ds_read_b128 v[220:223], v162 offset:22528
	ds_read_b128 v[224:227], v162 offset:23552
	s_add_u32 s22, s22, 0x80
	s_addc_u32 s23, s23, 0
	s_add_u32 s24, s24, 0x80
	s_addc_u32 s25, s25, 0
	s_add_i32 m0, s0, 0x8000
	s_nop 0
	global_load_lds_dwordx4 v140, s[22:23]
	s_add_i32 m0, s0, 0xa000
	s_nop 0
	global_load_lds_dwordx4 v144, s[22:23]
	s_add_i32 m0, s0, 0x18000
	s_nop 0
	global_load_lds_dwordx4 v142, s[24:25]
	s_add_i32 m0, s0, 0x1a000
	s_nop 0
	global_load_lds_dwordx4 v146, s[24:25]
	s_waitcnt lgkmcnt(0)
	v_mfma_f32_16x16x32_bf16 v[124:127], v[150:153], v[196:199], v[124:127]
	v_mfma_f32_16x16x32_bf16 v[120:123], v[168:171], v[196:199], v[120:123]
	v_mfma_f32_16x16x32_bf16 v[108:111], v[150:153], v[204:207], v[108:111]
	v_mfma_f32_16x16x32_bf16 v[104:107], v[168:171], v[204:207], v[104:107]
	v_mfma_f32_16x16x32_bf16 v[92:95], v[150:153], v[212:215], v[92:95]
	v_mfma_f32_16x16x32_bf16 v[88:91], v[168:171], v[212:215], v[88:91]
	v_mfma_f32_16x16x32_bf16 v[76:79], v[150:153], v[220:223], v[76:79]
	v_mfma_f32_16x16x32_bf16 v[72:75], v[168:171], v[220:223], v[72:75]
	v_mfma_f32_16x16x32_bf16 v[124:127], v[154:157], v[200:203], v[124:127]
	v_mfma_f32_16x16x32_bf16 v[120:123], v[176:179], v[200:203], v[120:123]
	v_mfma_f32_16x16x32_bf16 v[108:111], v[154:157], v[208:211], v[108:111]
	v_mfma_f32_16x16x32_bf16 v[104:107], v[176:179], v[208:211], v[104:107]
	v_mfma_f32_16x16x32_bf16 v[92:95], v[154:157], v[216:219], v[92:95]
	v_mfma_f32_16x16x32_bf16 v[88:91], v[176:179], v[216:219], v[88:91]
	v_mfma_f32_16x16x32_bf16 v[76:79], v[154:157], v[224:227], v[76:79]
	v_mfma_f32_16x16x32_bf16 v[72:75], v[176:179], v[224:227], v[72:75]
	s_waitcnt vmcnt(8)
	s_barrier
;     DI void operator()(const f32x4 (&acc)[2][2][4][2], const pg8::Unit& u, int wr, int wc, int fr, int fq) const {
;     ...
;                 if (R < ROWS_P) { const int b = R / LPAD, t = R - b * LPAD; if (t >= NMETA && t < LP) { const size_t idx = ((size_t)b * SEQ + t - NMETA) * DM; xs = p.x_prompt + idx; yd = p.out + O_YP + idx; } }
;                 else { const size_t idx = (size_t)(R - ROWS_P) * DM; xs = p.x_sample + idx; yd = p.out + O_YS + idx; }
;                 float ss = 0.f;
;                 if (xs) {
; #pragma unroll
;                     for (int bj = 0; bj < 2; ++bj) {
;                         const int n = colt + bj * 128 + wc * 32 + 8 * fq;
;                         const f32x4 x0 = *(const f32x4*)(xs + n), x1 = *(const f32x4*)(xs + n + 4);
	ds_read_b128 v[150:153], v164
	ds_read_b128 v[154:157], v164 offset:1024
	ds_read_b128 v[168:171], v164 offset:2048
	ds_read_b128 v[176:179], v164 offset:3072
	ds_read_b128 v[196:199], v162 offset:49152
	ds_read_b128 v[200:203], v162 offset:50176
	ds_read_b128 v[204:207], v162 offset:51200
	ds_read_b128 v[208:211], v162 offset:52224
	ds_read_b128 v[212:215], v162 offset:53248
	ds_read_b128 v[216:219], v162 offset:54272
	ds_read_b128 v[220:223], v162 offset:55296
	ds_read_b128 v[224:227], v162 offset:56320
	s_add_u32 s22, s22, 0x80
	s_addc_u32 s23, s23, 0
	s_add_u32 s24, s24, 0x80
	s_addc_u32 s25, s25, 0
	s_add_i32 m0, s0, 0x4000
	s_nop 0
	global_load_lds_dwordx4 v140, s[22:23]
	s_add_i32 m0, s0, 0x6000
	s_nop 0
	global_load_lds_dwordx4 v144, s[22:23]
	s_add_i32 m0, s0, 0x14000
	s_nop 0
	global_load_lds_dwordx4 v142, s[24:25]
	s_add_i32 m0, s0, 0x16000
	s_nop 0
	global_load_lds_dwordx4 v146, s[24:25]
	s_waitcnt lgkmcnt(0)
	v_mfma_f32_16x16x32_bf16 v[124:127], v[150:153], v[196:199], v[124:127]
	v_mfma_f32_16x16x32_bf16 v[120:123], v[168:171], v[196:199], v[120:123]
	v_mfma_f32_16x16x32_bf16 v[108:111], v[150:153], v[204:207], v[108:111]
	v_mfma_f32_16x16x32_bf16 v[104:107], v[168:171], v[204:207], v[104:107]
	v_mfma_f32_16x16x32_bf16 v[92:95], v[150:153], v[212:215], v[92:95]
	v_mfma_f32_16x16x32_bf16 v[88:91], v[168:171], v[212:215], v[88:91]
	v_mfma_f32_16x16x32_bf16 v[76:79], v[150:153], v[220:223], v[76:79]
	v_mfma_f32_16x16x32_bf16 v[72:75], v[168:171], v[220:223], v[72:75]
	v_mfma_f32_16x16x32_bf16 v[124:127], v[154:157], v[200:203], v[124:127]
	v_mfma_f32_16x16x32_bf16 v[120:123], v[176:179], v[200:203], v[120:123]
	v_mfma_f32_16x16x32_bf16 v[108:111], v[154:157], v[208:211], v[108:111]
	v_mfma_f32_16x16x32_bf16 v[104:107], v[176:179], v[208:211], v[104:107]
	v_mfma_f32_16x16x32_bf16 v[92:95], v[154:157], v[216:219], v[92:95]
	v_mfma_f32_16x16x32_bf16 v[88:91], v[176:179], v[216:219], v[88:91]
	v_mfma_f32_16x16x32_bf16 v[76:79], v[154:157], v[224:227], v[76:79]
	v_mfma_f32_16x16x32_bf16 v[72:75], v[176:179], v[224:227], v[72:75]
	s_waitcnt vmcnt(8)
	s_barrier
	ds_read_b128 v[150:153], v160
	ds_read_b128 v[154:157], v160 offset:1024
	ds_read_b128 v[168:171], v160 offset:2048
	ds_read_b128 v[176:179], v160 offset:3072
	ds_read_b128 v[196:199], v162
	ds_read_b128 v[200:203], v162 offset:1024
	ds_read_b128 v[204:207], v162 offset:2048
	ds_read_b128 v[208:211], v162 offset:3072
	ds_read_b128 v[212:215], v162 offset:4096
	ds_read_b128 v[216:219], v162 offset:5120
	ds_read_b128 v[220:223], v162 offset:6144
	ds_read_b128 v[224:227], v162 offset:7168
	s_add_u32 s22, s22, 0x80
	s_addc_u32 s23, s23, 0
	s_add_u32 s24, s24, 0x80
	s_addc_u32 s25, s25, 0
	s_add_i32 m0, s0, 0xc000
	s_nop 0
	global_load_lds_dwordx4 v140, s[22:23]
	s_add_i32 m0, s0, 0xe000
	s_nop 0
	global_load_lds_dwordx4 v144, s[22:23]
	s_add_i32 m0, s0, 0x1c000
	s_nop 0
	global_load_lds_dwordx4 v142, s[24:25]
	s_add_i32 m0, s0, 0x1e000
	s_nop 0
	global_load_lds_dwordx4 v146, s[24:25]
	v_lshl_or_b32 v236, s42, 8, v159
	v_and_b32_e32 v237, 15, v158
	v_lshlrev_b32_e32 v236, 2, v236
	v_lshl_or_b32 v236, v237, 12, v236
	s_and_b64 vcc, s[72:73], exec
	s_cselect_b32 s35, 64, 0
	s_lshl_b32 s32, s94, 8
	s_add_i32 s35, s35, s32
	s_add_i32 s32, s35, 0
	s_mul_hi_u32 s34, s32, 0x7e07e07f
	s_lshr_b32 s34, s34, 11
	s_mul_i32 vcc_lo, s34, 0x1040
	s_sub_i32 vcc_lo, s32, vcc_lo
	s_add_i32 vcc_lo, vcc_lo, -16
	s_lshl_b32 s34, s34, 12
	s_add_i32 s34, s34, vcc_lo
	s_cmp_lt_u32 vcc_lo, 0x1000
	s_cselect_b32 vcc_hi, 1, 0
	s_sub_i32 vcc_lo, s32, 0x4100
	s_cmp_ge_u32 s94, 65
	s_cselect_b32 s34, vcc_lo, s34
	s_cselect_b32 vcc_hi, 1, vcc_hi
	s_cselect_b32 s30, s78, s76
	s_cselect_b32 s31, s79, s77
	s_cmp_lg_u32 vcc_hi, 0
	s_cselect_b32 s34, s34, 0
	s_lshl_b32 s34, s34, 12
	s_add_u32 s30, s30, s34
	s_addc_u32 s31, s31, 0
	global_load_dwordx4 v[0:3], v236, s[30:31]
	global_load_dwordx4 v[4:7], v236, s[30:31] offset:16
	s_add_i32 s32, s35, 16
	s_mul_hi_u32 s34, s32, 0x7e07e07f
	s_lshr_b32 s34, s34, 11
	s_mul_i32 vcc_lo, s34, 0x1040
	s_sub_i32 vcc_lo, s32, vcc_lo
	s_add_i32 vcc_lo, vcc_lo, -16
	s_lshl_b32 s34, s34, 12
	s_add_i32 s34, s34, vcc_lo
	s_cmp_lt_u32 vcc_lo, 0x1000
	s_cselect_b32 vcc_hi, 1, 0
	s_sub_i32 vcc_lo, s32, 0x4100
	s_cmp_ge_u32 s94, 65
	s_cselect_b32 s34, vcc_lo, s34
	s_cselect_b32 vcc_hi, 1, vcc_hi
	s_cselect_b32 s30, s78, s76
	s_cselect_b32 s31, s79, s77
	s_cmp_lg_u32 vcc_hi, 0
	s_cselect_b32 s34, s34, 0
	s_lshl_b32 s34, s34, 12
	s_add_u32 s30, s30, s34
	s_addc_u32 s31, s31, 0
	global_load_dwordx4 v[8:11], v236, s[30:31]
	global_load_dwordx4 v[12:15], v236, s[30:31] offset:16
	s_add_i32 s32, s35, 32
	s_mul_hi_u32 s34, s32, 0x7e07e07f
	s_lshr_b32 s34, s34, 11
	s_mul_i32 vcc_lo, s34, 0x1040
	s_sub_i32 vcc_lo, s32, vcc_lo
	s_add_i32 vcc_lo, vcc_lo, -16
	s_lshl_b32 s34, s34, 12
	s_add_i32 s34, s34, vcc_lo
	s_cmp_lt_u32 vcc_lo, 0x1000
	s_cselect_b32 vcc_hi, 1, 0
	s_sub_i32 vcc_lo, s32, 0x4100
	s_cmp_ge_u32 s94, 65
	s_cselect_b32 s34, vcc_lo, s34
	s_cselect_b32 vcc_hi, 1, vcc_hi
	s_cselect_b32 s30, s78, s76
	s_cselect_b32 s31, s79, s77
	s_cmp_lg_u32 vcc_hi, 0
	s_cselect_b32 s34, s34, 0
	s_lshl_b32 s34, s34, 12
	s_add_u32 s30, s30, s34
	s_addc_u32 s31, s31, 0
	global_load_dwordx4 v[16:19], v236, s[30:31]
	global_load_dwordx4 v[20:23], v236, s[30:31] offset:16
	s_add_i32 s32, s35, 48
	s_mul_hi_u32 s34, s32, 0x7e07e07f
	s_lshr_b32 s34, s34, 11
	s_mul_i32 vcc_lo, s34, 0x1040
	s_sub_i32 vcc_lo, s32, vcc_lo
	s_add_i32 vcc_lo, vcc_lo, -16
	s_lshl_b32 s34, s34, 12
	s_add_i32 s34, s34, vcc_lo
	s_cmp_lt_u32 vcc_lo, 0x1000
	s_cselect_b32 vcc_hi, 1, 0
	s_sub_i32 vcc_lo, s32, 0x4100
	s_cmp_ge_u32 s94, 65
	s_cselect_b32 s34, vcc_lo, s34
	s_cselect_b32 vcc_hi, 1, vcc_hi
	s_cselect_b32 s30, s78, s76
	s_cselect_b32 s31, s79, s77
	s_cmp_lg_u32 vcc_hi, 0
	s_cselect_b32 s34, s34, 0
	s_lshl_b32 s34, s34, 12
	s_add_u32 s30, s30, s34
	s_addc_u32 s31, s31, 0
	global_load_dwordx4 v[24:27], v236, s[30:31]
	global_load_dwordx4 v[28:31], v236, s[30:31] offset:16
	s_waitcnt lgkmcnt(0)
; #define PG8_WAIT_V(n) asm volatile("s_waitcnt vmcnt(" #n ")" ::: "memory")
; template <class Epi, class Sched, bool ALIGN_EPI = false, bool SP2 = false>
; __device__ __forceinline__ void gemm_phase(PG8_LAS unsigned char* lds, const Gemm g, const Sched& S, const Epi& E) {
;     ...
;         for (int t = 0; t < nt; t += 2) {
;             const bool last = (t == nt - 2);
;             const char* a1 = cA + (size_t)(t + 1) * kstep;
;             const char* a2 = last ? nA : cA + (size_t)(t + 2) * kstep; const char* b2 = last ? nB : cB + (size_t)(t + 2) * kstep;
;             const char* a3 = a2 + kstep; const char* b3 = b2 + kstep;
;             if (last && has_next) S.a_ready(nxt);
;             if constexpr (SP2) {
;             PG8_LDB(B0, 0, 0); PG8_LDB(B1, 0, 1); PG8_SCHED; PG8_LDA(At, 0, 0); PG8_STAGE(PG8_SA(1, 1), a1 + hstep, voffA);
;             PG8_WAIT_V(8); PG8_WAIT_L(0); PG8_BAR; PG8_MMA(0, 0, At, B0); PG8_MMA(0, 1, At, B1); PG8_BAR; PG8_SCHED;
;             PG8_LDA(At, 0, 1); PG8_STAGE(PG8_SB(0, 0), b2, voffB); PG8_STAGE(PG8_SB(0, 1), b2 + hstep, voffB); PG8_STAGE(PG8_SA(0, 0), a2, voffA);
;             PG8_WAIT_V(8); PG8_WAIT_L(0); PG8_BAR; PG8_MMA(1, 0, At, B0); PG8_MMA(1, 1, At, B1); PG8_BAR; PG8_SCHED;
;             PG8_LDB(B0, 1, 0); PG8_LDB(B1, 1, 1); PG8_SCHED; PG8_LDA(At, 1, 0); PG8_STAGE(PG8_SA(0, 1), a2 + hstep, voffA);
;             PG8_WAIT_V(8); PG8_WAIT_L(0); PG8_BAR; PG8_MMA(0, 0, At, B0); PG8_MMA(0, 1, At, B1); PG8_BAR; PG8_SCHED;
;             PG8_LDA(At, 1, 1); PG8_STAGE(PG8_SB(1, 0), b3, voffB); PG8_STAGE(PG8_SB(1, 1), b3 + hstep, voffB); PG8_STAGE(PG8_SA(1, 0), a3, voffA);
;             PG8_WAIT_V(8); PG8_WAIT_L(0); PG8_BAR; PG8_MMA(1, 0, At, B0); PG8_MMA(1, 1, At, B1); PG8_BAR; PG8_SCHED;
;             } else {
;             PG8_LDB(B0, 0, 0); PG8_SCHED; PG8_LDA(At, 0, 0); PG8_STAGE(PG8_SA(1, 1), a1 + hstep, voffA);
;             PG8_WAIT_L(8); PG8_BAR; PG8_WAIT_L(0); PG8_MMA(0, 0, At, B0); PG8_BAR; PG8_SCHED;
;             PG8_LDB(B1, 0, 1); PG8_STAGE(PG8_SB(0, 0), b2, voffB);
;             PG8_BAR; PG8_WAIT_L(0); PG8_MMA(0, 1, At, B1); PG8_BAR;
;             PG8_LDA(At, 0, 1); PG8_STAGE(PG8_SA(0, 0), a2, voffA);
;             PG8_BAR; PG8_WAIT_L(0); PG8_MMA(1, 0, At, B0); PG8_BAR; PG8_SCHED;
;             PG8_STAGE(PG8_SB(0, 1), b2 + hstep, voffB);
;             PG8_WAIT_V(6); PG8_BAR; PG8_MMA(1, 1, At, B1); PG8_BAR;
	v_mfma_f32_16x16x32_bf16 v[124:127], v[150:153], v[196:199], v[124:127]
	v_mfma_f32_16x16x32_bf16 v[120:123], v[168:171], v[196:199], v[120:123]
	v_mfma_f32_16x16x32_bf16 v[108:111], v[150:153], v[204:207], v[108:111]
	v_mfma_f32_16x16x32_bf16 v[104:107], v[168:171], v[204:207], v[104:107]
	v_mfma_f32_16x16x32_bf16 v[92:95], v[150:153], v[212:215], v[92:95]
	v_mfma_f32_16x16x32_bf16 v[88:91], v[168:171], v[212:215], v[88:91]
	v_mfma_f32_16x16x32_bf16 v[76:79], v[150:153], v[220:223], v[76:79]
	v_mfma_f32_16x16x32_bf16 v[72:75], v[168:171], v[220:223], v[72:75]
	v_mfma_f32_16x16x32_bf16 v[124:127], v[154:157], v[200:203], v[124:127]
	v_mfma_f32_16x16x32_bf16 v[120:123], v[176:179], v[200:203], v[120:123]
	v_mfma_f32_16x16x32_bf16 v[108:111], v[154:157], v[208:211], v[108:111]
	v_mfma_f32_16x16x32_bf16 v[104:107], v[176:179], v[208:211], v[104:107]
	v_mfma_f32_16x16x32_bf16 v[92:95], v[154:157], v[216:219], v[92:95]
	v_mfma_f32_16x16x32_bf16 v[88:91], v[176:179], v[216:219], v[88:91]
	v_mfma_f32_16x16x32_bf16 v[76:79], v[154:157], v[224:227], v[76:79]
	v_mfma_f32_16x16x32_bf16 v[72:75], v[176:179], v[224:227], v[72:75]
	s_waitcnt vmcnt(16)
	s_barrier
	ds_read_b128 v[150:153], v163
	ds_read_b128 v[154:157], v163 offset:1024
	ds_read_b128 v[168:171], v163 offset:2048
	ds_read_b128 v[176:179], v163 offset:3072
	ds_read_b128 v[196:199], v162 offset:32768
	ds_read_b128 v[200:203], v162 offset:33792
	ds_read_b128 v[204:207], v162 offset:34816
	ds_read_b128 v[208:211], v162 offset:35840
	ds_read_b128 v[212:215], v162 offset:36864
	ds_read_b128 v[216:219], v162 offset:37888
	ds_read_b128 v[220:223], v162 offset:38912
	ds_read_b128 v[224:227], v162 offset:39936
	s_waitcnt lgkmcnt(0)
	v_mfma_f32_16x16x32_bf16 v[124:127], v[150:153], v[196:199], v[124:127]
	v_mfma_f32_16x16x32_bf16 v[120:123], v[168:171], v[196:199], v[120:123]
	v_mfma_f32_16x16x32_bf16 v[108:111], v[150:153], v[204:207], v[108:111]
	v_mfma_f32_16x16x32_bf16 v[104:107], v[168:171], v[204:207], v[104:107]
	v_mfma_f32_16x16x32_bf16 v[92:95], v[150:153], v[212:215], v[92:95]
	v_mfma_f32_16x16x32_bf16 v[88:91], v[168:171], v[212:215], v[88:91]
	v_mfma_f32_16x16x32_bf16 v[76:79], v[150:153], v[220:223], v[76:79]
	v_mfma_f32_16x16x32_bf16 v[72:75], v[168:171], v[220:223], v[72:75]
	v_mfma_f32_16x16x32_bf16 v[124:127], v[154:157], v[200:203], v[124:127]
	v_mfma_f32_16x16x32_bf16 v[120:123], v[176:179], v[200:203], v[120:123]
	v_mfma_f32_16x16x32_bf16 v[108:111], v[154:157], v[208:211], v[108:111]
	v_mfma_f32_16x16x32_bf16 v[104:107], v[176:179], v[208:211], v[104:107]
	v_mfma_f32_16x16x32_bf16 v[92:95], v[154:157], v[216:219], v[92:95]
	v_mfma_f32_16x16x32_bf16 v[88:91], v[176:179], v[216:219], v[88:91]
	v_mfma_f32_16x16x32_bf16 v[76:79], v[154:157], v[224:227], v[76:79]
	v_mfma_f32_16x16x32_bf16 v[72:75], v[176:179], v[224:227], v[72:75]
	s_waitcnt vmcnt(12)
	s_barrier
	ds_read_b128 v[150:153], v161
	ds_read_b128 v[154:157], v161 offset:1024
	ds_read_b128 v[168:171], v161 offset:2048
	ds_read_b128 v[176:179], v161 offset:3072
	ds_read_b128 v[196:199], v162 offset:16384
	ds_read_b128 v[200:203], v162 offset:17408
	ds_read_b128 v[204:207], v162 offset:18432
	ds_read_b128 v[208:211], v162 offset:19456
	ds_read_b128 v[212:215], v162 offset:20480
	ds_read_b128 v[216:219], v162 offset:21504
	ds_read_b128 v[220:223], v162 offset:22528
	ds_read_b128 v[224:227], v162 offset:23552
	s_waitcnt lgkmcnt(0)
	v_mfma_f32_16x16x32_bf16 v[124:127], v[150:153], v[196:199], v[124:127]
	v_mfma_f32_16x16x32_bf16 v[120:123], v[168:171], v[196:199], v[120:123]
	v_mfma_f32_16x16x32_bf16 v[108:111], v[150:153], v[204:207], v[108:111]
	v_mfma_f32_16x16x32_bf16 v[104:107], v[168:171], v[204:207], v[104:107]
	v_mfma_f32_16x16x32_bf16 v[92:95], v[150:153], v[212:215], v[92:95]
	v_mfma_f32_16x16x32_bf16 v[88:91], v[168:171], v[212:215], v[88:91]
	v_mfma_f32_16x16x32_bf16 v[76:79], v[150:153], v[220:223], v[76:79]
	v_mfma_f32_16x16x32_bf16 v[72:75], v[168:171], v[220:223], v[72:75]
	v_mfma_f32_16x16x32_bf16 v[124:127], v[154:157], v[200:203], v[124:127]
	v_mfma_f32_16x16x32_bf16 v[120:123], v[176:179], v[200:203], v[120:123]
	v_mfma_f32_16x16x32_bf16 v[108:111], v[154:157], v[208:211], v[108:111]
	v_mfma_f32_16x16x32_bf16 v[104:107], v[176:179], v[208:211], v[104:107]
	v_mfma_f32_16x16x32_bf16 v[92:95], v[154:157], v[216:219], v[92:95]
	v_mfma_f32_16x16x32_bf16 v[88:91], v[176:179], v[216:219], v[88:91]
	v_mfma_f32_16x16x32_bf16 v[76:79], v[154:157], v[224:227], v[76:79]
	v_mfma_f32_16x16x32_bf16 v[72:75], v[176:179], v[224:227], v[72:75]
	s_waitcnt vmcnt(8)
	s_barrier
	ds_read_b128 v[150:153], v164
	ds_read_b128 v[154:157], v164 offset:1024
	ds_read_b128 v[168:171], v164 offset:2048
	ds_read_b128 v[176:179], v164 offset:3072
	ds_read_b128 v[196:199], v162 offset:49152
	ds_read_b128 v[200:203], v162 offset:50176
	ds_read_b128 v[204:207], v162 offset:51200
	ds_read_b128 v[208:211], v162 offset:52224
	ds_read_b128 v[212:215], v162 offset:53248
	ds_read_b128 v[216:219], v162 offset:54272
	ds_read_b128 v[220:223], v162 offset:55296
	ds_read_b128 v[224:227], v162 offset:56320
	s_waitcnt lgkmcnt(0)
	v_mfma_f32_16x16x32_bf16 v[124:127], v[150:153], v[196:199], v[124:127]
	v_mfma_f32_16x16x32_bf16 v[120:123], v[168:171], v[196:199], v[120:123]
	v_mfma_f32_16x16x32_bf16 v[108:111], v[150:153], v[204:207], v[108:111]
	v_mfma_f32_16x16x32_bf16 v[104:107], v[168:171], v[204:207], v[104:107]
	v_mfma_f32_16x16x32_bf16 v[92:95], v[150:153], v[212:215], v[92:95]
	v_mfma_f32_16x16x32_bf16 v[88:91], v[168:171], v[212:215], v[88:91]
	v_mfma_f32_16x16x32_bf16 v[76:79], v[150:153], v[220:223], v[76:79]
	v_mfma_f32_16x16x32_bf16 v[72:75], v[168:171], v[220:223], v[72:75]
	v_mfma_f32_16x16x32_bf16 v[124:127], v[154:157], v[200:203], v[124:127]
	v_mfma_f32_16x16x32_bf16 v[120:123], v[176:179], v[200:203], v[120:123]
	v_mfma_f32_16x16x32_bf16 v[108:111], v[154:157], v[208:211], v[108:111]
	v_mfma_f32_16x16x32_bf16 v[104:107], v[176:179], v[208:211], v[104:107]
	v_mfma_f32_16x16x32_bf16 v[92:95], v[154:157], v[216:219], v[92:95]
	v_mfma_f32_16x16x32_bf16 v[88:91], v[176:179], v[216:219], v[88:91]
	v_mfma_f32_16x16x32_bf16 v[76:79], v[154:157], v[224:227], v[76:79]
	v_mfma_f32_16x16x32_bf16 v[72:75], v[176:179], v[224:227], v[72:75]
	s_branch .LBB0_620
; #define PG8_WAIT_V(n) asm volatile("s_waitcnt vmcnt(" #n ")" ::: "memory")
; template <class Epi, class Sched, bool ALIGN_EPI = false, bool SP2 = false>
; __device__ __forceinline__ void gemm_phase(PG8_LAS unsigned char* lds, const Gemm g, const Sched& S, const Epi& E) {
;     ...
;         for (int t = 0; t < nt; t += 2) {
;             const bool last = (t == nt - 2);
;             const char* a1 = cA + (size_t)(t + 1) * kstep;
;             const char* a2 = last ? nA : cA + (size_t)(t + 2) * kstep; const char* b2 = last ? nB : cB + (size_t)(t + 2) * kstep;
;             const char* a3 = a2 + kstep; const char* b3 = b2 + kstep;
;             if (last && has_next) S.a_ready(nxt);
;             if constexpr (SP2) {
;             PG8_LDB(B0, 0, 0); PG8_LDB(B1, 0, 1); PG8_SCHED; PG8_LDA(At, 0, 0); PG8_STAGE(PG8_SA(1, 1), a1 + hstep, voffA);
;             PG8_WAIT_V(8); PG8_WAIT_L(0); PG8_BAR; PG8_MMA(0, 0, At, B0); PG8_MMA(0, 1, At, B1); PG8_BAR; PG8_SCHED;
;             PG8_LDA(At, 0, 1); PG8_STAGE(PG8_SB(0, 0), b2, voffB); PG8_STAGE(PG8_SB(0, 1), b2 + hstep, voffB); PG8_STAGE(PG8_SA(0, 0), a2, voffA);
;             PG8_WAIT_V(8); PG8_WAIT_L(0); PG8_BAR; PG8_MMA(1, 0, At, B0); PG8_MMA(1, 1, At, B1); PG8_BAR; PG8_SCHED;
;             PG8_LDB(B0, 1, 0); PG8_LDB(B1, 1, 1); PG8_SCHED; PG8_LDA(At, 1, 0); PG8_STAGE(PG8_SA(0, 1), a2 + hstep, voffA);
;             PG8_WAIT_V(8); PG8_WAIT_L(0); PG8_BAR; PG8_MMA(0, 0, At, B0); PG8_MMA(0, 1, At, B1); PG8_BAR; PG8_SCHED;
;             PG8_LDA(At, 1, 1); PG8_STAGE(PG8_SB(1, 0), b3, voffB); PG8_STAGE(PG8_SB(1, 1), b3 + hstep, voffB); PG8_STAGE(PG8_SA(1, 0), a3, voffA);
;             PG8_WAIT_V(8); PG8_WAIT_L(0); PG8_BAR; PG8_MMA(1, 0, At, B0); PG8_MMA(1, 1, At, B1); PG8_BAR; PG8_SCHED;
;             } else {
;             PG8_LDB(B0, 0, 0); PG8_SCHED; PG8_LDA(At, 0, 0); PG8_STAGE(PG8_SA(1, 1), a1 + hstep, voffA);
;             PG8_WAIT_L(8); PG8_BAR; PG8_WAIT_L(0); PG8_MMA(0, 0, At, B0); PG8_BAR; PG8_SCHED;
;             PG8_LDB(B1, 0, 1); PG8_STAGE(PG8_SB(0, 0), b2, voffB);
;             PG8_BAR; PG8_WAIT_L(0); PG8_MMA(0, 1, At, B1); PG8_BAR;
;             PG8_LDA(At, 0, 1); PG8_STAGE(PG8_SA(0, 0), a2, voffA);
;             PG8_BAR; PG8_WAIT_L(0); PG8_MMA(1, 0, At, B0); PG8_BAR; PG8_SCHED;
;             PG8_STAGE(PG8_SB(0, 1), b2 + hstep, voffB);
;             PG8_WAIT_V(6); PG8_BAR; PG8_MMA(1, 1, At, B1); PG8_BAR;
.Lp3q_lean_q1:
	s_mov_b32 s22, s94
	s_mov_b32 s23, 0
	s_lshl_b64 s[22:23], s[22:23], 19
	s_add_u32 s22, s22, s70
	s_addc_u32 s23, s23, s71
	s_add_u32 s22, s22, 0x80
	s_addc_u32 s23, s23, 0
	s_mov_b32 s24, s42
	s_mov_b32 s25, 0
	s_lshl_b64 s[24:25], s[24:25], 19
	s_add_u32 s24, s24, s64
	s_addc_u32 s25, s25, s65
	s_add_u32 s24, s24, 0x80
	s_addc_u32 s25, s25, 0
	s_add_u32 s24, s24, 0x40000
	s_addc_u32 s25, s25, 0
	s_waitcnt vmcnt(0) lgkmcnt(0)
	s_barrier
	s_add_u32 s22, s22, 0x80
	s_addc_u32 s23, s23, 0
	s_add_u32 s24, s24, 0x80
	s_addc_u32 s25, s25, 0
	s_add_i32 m0, s0, 0x4000
	s_nop 0
	global_load_lds_dwordx4 v140, s[22:23]
	s_add_i32 m0, s0, 0x6000
	s_nop 0
	global_load_lds_dwordx4 v144, s[22:23]
	s_add_i32 m0, s0, 0x10000
	s_nop 0
	global_load_lds_dwordx4 v142, s[24:25]
	s_add_i32 m0, s0, 0x12000
	s_nop 0
	global_load_lds_dwordx4 v146, s[24:25]
	s_add_u32 s22, s22, 0x80
	s_addc_u32 s23, s23, 0
	s_add_u32 s24, s24, 0x80
	s_addc_u32 s25, s25, 0
	s_add_i32 m0, s0, 0xc000
	s_nop 0
	global_load_lds_dwordx4 v140, s[22:23]
	s_add_i32 m0, s0, 0xe000
	s_nop 0
	global_load_lds_dwordx4 v144, s[22:23]
	s_add_i32 m0, s0, 0x18000
	s_nop 0
	global_load_lds_dwordx4 v142, s[24:25]
	s_add_i32 m0, s0, 0x1a000
	s_nop 0
	global_load_lds_dwordx4 v146, s[24:25]
	ds_read_b128 v[180:183], v161
	ds_read_b128 v[184:187], v161 offset:1024
	ds_read_b128 v[188:191], v161 offset:2048
	ds_read_b128 v[192:195], v161 offset:3072
	ds_read_b128 v[196:199], v162
	ds_read_b128 v[200:203], v162 offset:1024
	ds_read_b128 v[204:207], v162 offset:2048
	ds_read_b128 v[208:211], v162 offset:3072
	ds_read_b128 v[212:215], v162 offset:4096
	ds_read_b128 v[216:219], v162 offset:5120
	ds_read_b128 v[220:223], v162 offset:6144
	ds_read_b128 v[224:227], v162 offset:7168
	s_waitcnt lgkmcnt(0)
	v_mfma_f32_16x16x32_bf16 v[116:119], v[180:183], v[196:199], v[116:119]
	v_mfma_f32_16x16x32_bf16 v[112:115], v[188:191], v[196:199], v[112:115]
	v_mfma_f32_16x16x32_bf16 v[100:103], v[180:183], v[204:207], v[100:103]
	v_mfma_f32_16x16x32_bf16 v[96:99], v[188:191], v[204:207], v[96:99]
	v_mfma_f32_16x16x32_bf16 v[84:87], v[180:183], v[212:215], v[84:87]
	v_mfma_f32_16x16x32_bf16 v[80:83], v[188:191], v[212:215], v[80:83]
	v_mfma_f32_16x16x32_bf16 v[68:71], v[180:183], v[220:223], v[68:71]
	v_mfma_f32_16x16x32_bf16 v[64:67], v[188:191], v[220:223], v[64:67]
	v_mfma_f32_16x16x32_bf16 v[116:119], v[184:187], v[200:203], v[116:119]
	v_mfma_f32_16x16x32_bf16 v[112:115], v[192:195], v[200:203], v[112:115]
	v_mfma_f32_16x16x32_bf16 v[100:103], v[184:187], v[208:211], v[100:103]
	v_mfma_f32_16x16x32_bf16 v[96:99], v[192:195], v[208:211], v[96:99]
	v_mfma_f32_16x16x32_bf16 v[84:87], v[184:187], v[216:219], v[84:87]
	v_mfma_f32_16x16x32_bf16 v[80:83], v[192:195], v[216:219], v[80:83]
	v_mfma_f32_16x16x32_bf16 v[68:71], v[184:187], v[224:227], v[68:71]
	v_mfma_f32_16x16x32_bf16 v[64:67], v[192:195], v[224:227], v[64:67]
	s_waitcnt vmcnt(8)
	s_barrier
	ds_read_b128 v[180:183], v164
	ds_read_b128 v[184:187], v164 offset:1024
	ds_read_b128 v[188:191], v164 offset:2048
	ds_read_b128 v[192:195], v164 offset:3072
	ds_read_b128 v[196:199], v162 offset:32768
	ds_read_b128 v[200:203], v162 offset:33792
	ds_read_b128 v[204:207], v162 offset:34816
	ds_read_b128 v[208:211], v162 offset:35840
	ds_read_b128 v[212:215], v162 offset:36864
	ds_read_b128 v[216:219], v162 offset:37888
	ds_read_b128 v[220:223], v162 offset:38912
	ds_read_b128 v[224:227], v162 offset:39936
	s_add_u32 s22, s22, 0x80
	s_addc_u32 s23, s23, 0
	s_add_u32 s24, s24, 0x80
	s_addc_u32 s25, s25, 0
	s_mov_b32 m0, s0
	s_nop 0
	global_load_lds_dwordx4 v140, s[22:23]
	s_add_i32 m0, s0, 0x2000
	s_nop 0
	global_load_lds_dwordx4 v144, s[22:23]
	s_add_i32 m0, s0, 0x14000
	s_nop 0
	global_load_lds_dwordx4 v142, s[24:25]
	s_add_i32 m0, s0, 0x16000
	s_nop 0
	global_load_lds_dwordx4 v146, s[24:25]
	s_waitcnt lgkmcnt(0)
	v_mfma_f32_16x16x32_bf16 v[116:119], v[180:183], v[196:199], v[116:119]
	v_mfma_f32_16x16x32_bf16 v[112:115], v[188:191], v[196:199], v[112:115]
	v_mfma_f32_16x16x32_bf16 v[100:103], v[180:183], v[204:207], v[100:103]
	v_mfma_f32_16x16x32_bf16 v[96:99], v[188:191], v[204:207], v[96:99]
	v_mfma_f32_16x16x32_bf16 v[84:87], v[180:183], v[212:215], v[84:87]
	v_mfma_f32_16x16x32_bf16 v[80:83], v[188:191], v[212:215], v[80:83]
	v_mfma_f32_16x16x32_bf16 v[68:71], v[180:183], v[220:223], v[68:71]
	v_mfma_f32_16x16x32_bf16 v[64:67], v[188:191], v[220:223], v[64:67]
	v_mfma_f32_16x16x32_bf16 v[116:119], v[184:187], v[200:203], v[116:119]
	v_mfma_f32_16x16x32_bf16 v[112:115], v[192:195], v[200:203], v[112:115]
	v_mfma_f32_16x16x32_bf16 v[100:103], v[184:187], v[208:211], v[100:103]
	v_mfma_f32_16x16x32_bf16 v[96:99], v[192:195], v[208:211], v[96:99]
	v_mfma_f32_16x16x32_bf16 v[84:87], v[184:187], v[216:219], v[84:87]
	v_mfma_f32_16x16x32_bf16 v[80:83], v[192:195], v[216:219], v[80:83]
	v_mfma_f32_16x16x32_bf16 v[68:71], v[184:187], v[224:227], v[68:71]
	v_mfma_f32_16x16x32_bf16 v[64:67], v[192:195], v[224:227], v[64:67]
	s_waitcnt vmcnt(8)
	s_barrier
; #define PG8_WAIT_V(n) asm volatile("s_waitcnt vmcnt(" #n ")" ::: "memory")
; template <class Epi, class Sched, bool ALIGN_EPI = false, bool SP2 = false>
; __device__ __forceinline__ void gemm_phase(PG8_LAS unsigned char* lds, const Gemm g, const Sched& S, const Epi& E) {
;     ...
;         for (int t = 0; t < nt; t += 2) {
;             const bool last = (t == nt - 2);
;             const char* a1 = cA + (size_t)(t + 1) * kstep;
;             const char* a2 = last ? nA : cA + (size_t)(t + 2) * kstep; const char* b2 = last ? nB : cB + (size_t)(t + 2) * kstep;
;             const char* a3 = a2 + kstep; const char* b3 = b2 + kstep;
;             if (last && has_next) S.a_ready(nxt);
;             if constexpr (SP2) {
;             PG8_LDB(B0, 0, 0); PG8_LDB(B1, 0, 1); PG8_SCHED; PG8_LDA(At, 0, 0); PG8_STAGE(PG8_SA(1, 1), a1 + hstep, voffA);
;             PG8_WAIT_V(8); PG8_WAIT_L(0); PG8_BAR; PG8_MMA(0, 0, At, B0); PG8_MMA(0, 1, At, B1); PG8_BAR; PG8_SCHED;
;             PG8_LDA(At, 0, 1); PG8_STAGE(PG8_SB(0, 0), b2, voffB); PG8_STAGE(PG8_SB(0, 1), b2 + hstep, voffB); PG8_STAGE(PG8_SA(0, 0), a2, voffA);
;             PG8_WAIT_V(8); PG8_WAIT_L(0); PG8_BAR; PG8_MMA(1, 0, At, B0); PG8_MMA(1, 1, At, B1); PG8_BAR; PG8_SCHED;
;             PG8_LDB(B0, 1, 0); PG8_LDB(B1, 1, 1); PG8_SCHED; PG8_LDA(At, 1, 0); PG8_STAGE(PG8_SA(0, 1), a2 + hstep, voffA);
;             PG8_WAIT_V(8); PG8_WAIT_L(0); PG8_BAR; PG8_MMA(0, 0, At, B0); PG8_MMA(0, 1, At, B1); PG8_BAR; PG8_SCHED;
;             PG8_LDA(At, 1, 1); PG8_STAGE(PG8_SB(1, 0), b3, voffB); PG8_STAGE(PG8_SB(1, 1), b3 + hstep, voffB); PG8_STAGE(PG8_SA(1, 0), a3, voffA);
;             PG8_WAIT_V(8); PG8_WAIT_L(0); PG8_BAR; PG8_MMA(1, 0, At, B0); PG8_MMA(1, 1, At, B1); PG8_BAR; PG8_SCHED;
;             } else {
;             PG8_LDB(B0, 0, 0); PG8_SCHED; PG8_LDA(At, 0, 0); PG8_STAGE(PG8_SA(1, 1), a1 + hstep, voffA);
;             PG8_WAIT_L(8); PG8_BAR; PG8_WAIT_L(0); PG8_MMA(0, 0, At, B0); PG8_BAR; PG8_SCHED;
;             PG8_LDB(B1, 0, 1); PG8_STAGE(PG8_SB(0, 0), b2, voffB);
;             PG8_BAR; PG8_WAIT_L(0); PG8_MMA(0, 1, At, B1); PG8_BAR;
;             PG8_LDA(At, 0, 1); PG8_STAGE(PG8_SA(0, 0), a2, voffA);
;             PG8_BAR; PG8_WAIT_L(0); PG8_MMA(1, 0, At, B0); PG8_BAR; PG8_SCHED;
;             PG8_STAGE(PG8_SB(0, 1), b2 + hstep, voffB);
;             PG8_WAIT_V(6); PG8_BAR; PG8_MMA(1, 1, At, B1); PG8_BAR;
	ds_read_b128 v[180:183], v160
	ds_read_b128 v[184:187], v160 offset:1024
	ds_read_b128 v[188:191], v160 offset:2048
	ds_read_b128 v[192:195], v160 offset:3072
	ds_read_b128 v[196:199], v162 offset:16384
	ds_read_b128 v[200:203], v162 offset:17408
	ds_read_b128 v[204:207], v162 offset:18432
	ds_read_b128 v[208:211], v162 offset:19456
	ds_read_b128 v[212:215], v162 offset:20480
	ds_read_b128 v[216:219], v162 offset:21504
	ds_read_b128 v[220:223], v162 offset:22528
	ds_read_b128 v[224:227], v162 offset:23552
	s_add_u32 s22, s22, 0x80
	s_addc_u32 s23, s23, 0
	s_add_u32 s24, s24, 0x80
	s_addc_u32 s25, s25, 0
	s_add_i32 m0, s0, 0x8000
	s_nop 0
	global_load_lds_dwordx4 v140, s[22:23]
	s_add_i32 m0, s0, 0xa000
	s_nop 0
	global_load_lds_dwordx4 v144, s[22:23]
	s_add_i32 m0, s0, 0x1c000
	s_nop 0
	global_load_lds_dwordx4 v142, s[24:25]
	s_add_i32 m0, s0, 0x1e000
	s_nop 0
	global_load_lds_dwordx4 v146, s[24:25]
	s_waitcnt lgkmcnt(0)
	v_mfma_f32_16x16x32_bf16 v[116:119], v[180:183], v[196:199], v[116:119]
	v_mfma_f32_16x16x32_bf16 v[112:115], v[188:191], v[196:199], v[112:115]
	v_mfma_f32_16x16x32_bf16 v[100:103], v[180:183], v[204:207], v[100:103]
	v_mfma_f32_16x16x32_bf16 v[96:99], v[188:191], v[204:207], v[96:99]
	v_mfma_f32_16x16x32_bf16 v[84:87], v[180:183], v[212:215], v[84:87]
	v_mfma_f32_16x16x32_bf16 v[80:83], v[188:191], v[212:215], v[80:83]
	v_mfma_f32_16x16x32_bf16 v[68:71], v[180:183], v[220:223], v[68:71]
	v_mfma_f32_16x16x32_bf16 v[64:67], v[188:191], v[220:223], v[64:67]
	v_mfma_f32_16x16x32_bf16 v[116:119], v[184:187], v[200:203], v[116:119]
	v_mfma_f32_16x16x32_bf16 v[112:115], v[192:195], v[200:203], v[112:115]
	v_mfma_f32_16x16x32_bf16 v[100:103], v[184:187], v[208:211], v[100:103]
	v_mfma_f32_16x16x32_bf16 v[96:99], v[192:195], v[208:211], v[96:99]
	v_mfma_f32_16x16x32_bf16 v[84:87], v[184:187], v[216:219], v[84:87]
	v_mfma_f32_16x16x32_bf16 v[80:83], v[192:195], v[216:219], v[80:83]
	v_mfma_f32_16x16x32_bf16 v[68:71], v[184:187], v[224:227], v[68:71]
	v_mfma_f32_16x16x32_bf16 v[64:67], v[192:195], v[224:227], v[64:67]
	s_waitcnt vmcnt(8)
	s_barrier
	ds_read_b128 v[180:183], v163
	ds_read_b128 v[184:187], v163 offset:1024
	ds_read_b128 v[188:191], v163 offset:2048
	ds_read_b128 v[192:195], v163 offset:3072
	ds_read_b128 v[196:199], v162 offset:49152
	ds_read_b128 v[200:203], v162 offset:50176
	ds_read_b128 v[204:207], v162 offset:51200
	ds_read_b128 v[208:211], v162 offset:52224
	ds_read_b128 v[212:215], v162 offset:53248
	ds_read_b128 v[216:219], v162 offset:54272
	ds_read_b128 v[220:223], v162 offset:55296
	ds_read_b128 v[224:227], v162 offset:56320
	s_add_u32 s22, s22, 0x80
	s_addc_u32 s23, s23, 0
	s_add_u32 s24, s24, 0x80
	s_addc_u32 s25, s25, 0
	s_add_i32 m0, s0, 0x4000
	s_nop 0
	global_load_lds_dwordx4 v140, s[22:23]
	s_add_i32 m0, s0, 0x6000
	s_nop 0
	global_load_lds_dwordx4 v144, s[22:23]
	s_add_i32 m0, s0, 0x10000
	s_nop 0
	global_load_lds_dwordx4 v142, s[24:25]
	s_add_i32 m0, s0, 0x12000
	s_nop 0
	global_load_lds_dwordx4 v146, s[24:25]
	s_waitcnt lgkmcnt(0)
	v_mfma_f32_16x16x32_bf16 v[116:119], v[180:183], v[196:199], v[116:119]
	v_mfma_f32_16x16x32_bf16 v[112:115], v[188:191], v[196:199], v[112:115]
	v_mfma_f32_16x16x32_bf16 v[100:103], v[180:183], v[204:207], v[100:103]
	v_mfma_f32_16x16x32_bf16 v[96:99], v[188:191], v[204:207], v[96:99]
	v_mfma_f32_16x16x32_bf16 v[84:87], v[180:183], v[212:215], v[84:87]
	v_mfma_f32_16x16x32_bf16 v[80:83], v[188:191], v[212:215], v[80:83]
	v_mfma_f32_16x16x32_bf16 v[68:71], v[180:183], v[220:223], v[68:71]
	v_mfma_f32_16x16x32_bf16 v[64:67], v[188:191], v[220:223], v[64:67]
	v_mfma_f32_16x16x32_bf16 v[116:119], v[184:187], v[200:203], v[116:119]
	v_mfma_f32_16x16x32_bf16 v[112:115], v[192:195], v[200:203], v[112:115]
	v_mfma_f32_16x16x32_bf16 v[100:103], v[184:187], v[208:211], v[100:103]
	v_mfma_f32_16x16x32_bf16 v[96:99], v[192:195], v[208:211], v[96:99]
	v_mfma_f32_16x16x32_bf16 v[84:87], v[184:187], v[216:219], v[84:87]
	v_mfma_f32_16x16x32_bf16 v[80:83], v[192:195], v[216:219], v[80:83]
	v_mfma_f32_16x16x32_bf16 v[68:71], v[184:187], v[224:227], v[68:71]
	v_mfma_f32_16x16x32_bf16 v[64:67], v[192:195], v[224:227], v[64:67]
	s_waitcnt vmcnt(8)
	s_barrier
	ds_read_b128 v[180:183], v161
	ds_read_b128 v[184:187], v161 offset:1024
	ds_read_b128 v[188:191], v161 offset:2048
	ds_read_b128 v[192:195], v161 offset:3072
	ds_read_b128 v[196:199], v162
	ds_read_b128 v[200:203], v162 offset:1024
	ds_read_b128 v[204:207], v162 offset:2048
	ds_read_b128 v[208:211], v162 offset:3072
	ds_read_b128 v[212:215], v162 offset:4096
	ds_read_b128 v[216:219], v162 offset:5120
	ds_read_b128 v[220:223], v162 offset:6144
	ds_read_b128 v[224:227], v162 offset:7168
	s_add_u32 s22, s22, 0x80
	s_addc_u32 s23, s23, 0
	s_add_u32 s24, s24, 0x80
	s_addc_u32 s25, s25, 0
	s_add_i32 m0, s0, 0xc000
	s_nop 0
	global_load_lds_dwordx4 v140, s[22:23]
	s_add_i32 m0, s0, 0xe000
	s_nop 0
	global_load_lds_dwordx4 v144, s[22:23]
	s_add_i32 m0, s0, 0x18000
	s_nop 0
	global_load_lds_dwordx4 v142, s[24:25]
	s_add_i32 m0, s0, 0x1a000
	s_nop 0
	global_load_lds_dwordx4 v146, s[24:25]
	s_waitcnt lgkmcnt(0)
	v_mfma_f32_16x16x32_bf16 v[116:119], v[180:183], v[196:199], v[116:119]
	v_mfma_f32_16x16x32_bf16 v[112:115], v[188:191], v[196:199], v[112:115]
	v_mfma_f32_16x16x32_bf16 v[100:103], v[180:183], v[204:207], v[100:103]
	v_mfma_f32_16x16x32_bf16 v[96:99], v[188:191], v[204:207], v[96:99]
	v_mfma_f32_16x16x32_bf16 v[84:87], v[180:183], v[212:215], v[84:87]
	v_mfma_f32_16x16x32_bf16 v[80:83], v[188:191], v[212:215], v[80:83]
	v_mfma_f32_16x16x32_bf16 v[68:71], v[180:183], v[220:223], v[68:71]
	v_mfma_f32_16x16x32_bf16 v[64:67], v[188:191], v[220:223], v[64:67]
	v_mfma_f32_16x16x32_bf16 v[116:119], v[184:187], v[200:203], v[116:119]
	v_mfma_f32_16x16x32_bf16 v[112:115], v[192:195], v[200:203], v[112:115]
	v_mfma_f32_16x16x32_bf16 v[100:103], v[184:187], v[208:211], v[100:103]
	v_mfma_f32_16x16x32_bf16 v[96:99], v[192:195], v[208:211], v[96:99]
	v_mfma_f32_16x16x32_bf16 v[84:87], v[184:187], v[216:219], v[84:87]
	v_mfma_f32_16x16x32_bf16 v[80:83], v[192:195], v[216:219], v[80:83]
	v_mfma_f32_16x16x32_bf16 v[68:71], v[184:187], v[224:227], v[68:71]
	v_mfma_f32_16x16x32_bf16 v[64:67], v[192:195], v[224:227], v[64:67]
	s_waitcnt vmcnt(8)
	s_barrier
; #define PG8_WAIT_V(n) asm volatile("s_waitcnt vmcnt(" #n ")" ::: "memory")
; template <class Epi, class Sched, bool ALIGN_EPI = false, bool SP2 = false>
; __device__ __forceinline__ void gemm_phase(PG8_LAS unsigned char* lds, const Gemm g, const Sched& S, const Epi& E) {
;     ...
;         for (int t = 0; t < nt; t += 2) {
;             const bool last = (t == nt - 2);
;             const char* a1 = cA + (size_t)(t + 1) * kstep;
;             const char* a2 = last ? nA : cA + (size_t)(t + 2) * kstep; const char* b2 = last ? nB : cB + (size_t)(t + 2) * kstep;
;             const char* a3 = a2 + kstep; const char* b3 = b2 + kstep;
;             if (last && has_next) S.a_ready(nxt);
;             if constexpr (SP2) {
;             PG8_LDB(B0, 0, 0); PG8_LDB(B1, 0, 1); PG8_SCHED; PG8_LDA(At, 0, 0); PG8_STAGE(PG8_SA(1, 1), a1 + hstep, voffA);
;             PG8_WAIT_V(8); PG8_WAIT_L(0); PG8_BAR; PG8_MMA(0, 0, At, B0); PG8_MMA(0, 1, At, B1); PG8_BAR; PG8_SCHED;
;             PG8_LDA(At, 0, 1); PG8_STAGE(PG8_SB(0, 0), b2, voffB); PG8_STAGE(PG8_SB(0, 1), b2 + hstep, voffB); PG8_STAGE(PG8_SA(0, 0), a2, voffA);
;             PG8_WAIT_V(8); PG8_WAIT_L(0); PG8_BAR; PG8_MMA(1, 0, At, B0); PG8_MMA(1, 1, At, B1); PG8_BAR; PG8_SCHED;
;             PG8_LDB(B0, 1, 0); PG8_LDB(B1, 1, 1); PG8_SCHED; PG8_LDA(At, 1, 0); PG8_STAGE(PG8_SA(0, 1), a2 + hstep, voffA);
;             PG8_WAIT_V(8); PG8_WAIT_L(0); PG8_BAR; PG8_MMA(0, 0, At, B0); PG8_MMA(0, 1, At, B1); PG8_BAR; PG8_SCHED;
;             PG8_LDA(At, 1, 1); PG8_STAGE(PG8_SB(1, 0), b3, voffB); PG8_STAGE(PG8_SB(1, 1), b3 + hstep, voffB); PG8_STAGE(PG8_SA(1, 0), a3, voffA);
;             PG8_WAIT_V(8); PG8_WAIT_L(0); PG8_BAR; PG8_MMA(1, 0, At, B0); PG8_MMA(1, 1, At, B1); PG8_BAR; PG8_SCHED;
;             } else {
;             PG8_LDB(B0, 0, 0); PG8_SCHED; PG8_LDA(At, 0, 0); PG8_STAGE(PG8_SA(1, 1), a1 + hstep, voffA);
;             PG8_WAIT_L(8); PG8_BAR; PG8_WAIT_L(0); PG8_MMA(0, 0, At, B0); PG8_BAR; PG8_SCHED;
;             PG8_LDB(B1, 0, 1); PG8_STAGE(PG8_SB(0, 0), b2, voffB);
;             PG8_BAR; PG8_WAIT_L(0); PG8_MMA(0, 1, At, B1); PG8_BAR;
;             PG8_LDA(At, 0, 1); PG8_STAGE(PG8_SA(0, 0), a2, voffA);
;             PG8_BAR; PG8_WAIT_L(0); PG8_MMA(1, 0, At, B0); PG8_BAR; PG8_SCHED;
;             PG8_STAGE(PG8_SB(0, 1), b2 + hstep, voffB);
;             PG8_WAIT_V(6); PG8_BAR; PG8_MMA(1, 1, At, B1); PG8_BAR;
	ds_read_b128 v[180:183], v164
	ds_read_b128 v[184:187], v164 offset:1024
	ds_read_b128 v[188:191], v164 offset:2048
	ds_read_b128 v[192:195], v164 offset:3072
	ds_read_b128 v[196:199], v162 offset:32768
	ds_read_b128 v[200:203], v162 offset:33792
	ds_read_b128 v[204:207], v162 offset:34816
	ds_read_b128 v[208:211], v162 offset:35840
	ds_read_b128 v[212:215], v162 offset:36864
	ds_read_b128 v[216:219], v162 offset:37888
	ds_read_b128 v[220:223], v162 offset:38912
	ds_read_b128 v[224:227], v162 offset:39936
	s_add_u32 s22, s22, 0x80
	s_addc_u32 s23, s23, 0
	s_add_u32 s24, s24, 0x80
	s_addc_u32 s25, s25, 0
	s_mov_b32 m0, s0
	s_nop 0
	global_load_lds_dwordx4 v140, s[22:23]
	s_add_i32 m0, s0, 0x2000
	s_nop 0
	global_load_lds_dwordx4 v144, s[22:23]
	s_add_i32 m0, s0, 0x14000
	s_nop 0
	global_load_lds_dwordx4 v142, s[24:25]
	s_add_i32 m0, s0, 0x16000
	s_nop 0
	global_load_lds_dwordx4 v146, s[24:25]
	s_waitcnt lgkmcnt(0)
	v_mfma_f32_16x16x32_bf16 v[116:119], v[180:183], v[196:199], v[116:119]
	v_mfma_f32_16x16x32_bf16 v[112:115], v[188:191], v[196:199], v[112:115]
	v_mfma_f32_16x16x32_bf16 v[100:103], v[180:183], v[204:207], v[100:103]
	v_mfma_f32_16x16x32_bf16 v[96:99], v[188:191], v[204:207], v[96:99]
	v_mfma_f32_16x16x32_bf16 v[84:87], v[180:183], v[212:215], v[84:87]
	v_mfma_f32_16x16x32_bf16 v[80:83], v[188:191], v[212:215], v[80:83]
	v_mfma_f32_16x16x32_bf16 v[68:71], v[180:183], v[220:223], v[68:71]
	v_mfma_f32_16x16x32_bf16 v[64:67], v[188:191], v[220:223], v[64:67]
	v_mfma_f32_16x16x32_bf16 v[116:119], v[184:187], v[200:203], v[116:119]
	v_mfma_f32_16x16x32_bf16 v[112:115], v[192:195], v[200:203], v[112:115]
	v_mfma_f32_16x16x32_bf16 v[100:103], v[184:187], v[208:211], v[100:103]
	v_mfma_f32_16x16x32_bf16 v[96:99], v[192:195], v[208:211], v[96:99]
	v_mfma_f32_16x16x32_bf16 v[84:87], v[184:187], v[216:219], v[84:87]
	v_mfma_f32_16x16x32_bf16 v[80:83], v[192:195], v[216:219], v[80:83]
	v_mfma_f32_16x16x32_bf16 v[68:71], v[184:187], v[224:227], v[68:71]
	v_mfma_f32_16x16x32_bf16 v[64:67], v[192:195], v[224:227], v[64:67]
	s_waitcnt vmcnt(8)
	s_barrier
	ds_read_b128 v[180:183], v160
	ds_read_b128 v[184:187], v160 offset:1024
	ds_read_b128 v[188:191], v160 offset:2048
	ds_read_b128 v[192:195], v160 offset:3072
	ds_read_b128 v[196:199], v162 offset:16384
	ds_read_b128 v[200:203], v162 offset:17408
	ds_read_b128 v[204:207], v162 offset:18432
	ds_read_b128 v[208:211], v162 offset:19456
	ds_read_b128 v[212:215], v162 offset:20480
	ds_read_b128 v[216:219], v162 offset:21504
	ds_read_b128 v[220:223], v162 offset:22528
	ds_read_b128 v[224:227], v162 offset:23552
	s_add_u32 s22, s22, 0x80
	s_addc_u32 s23, s23, 0
	s_add_u32 s24, s24, 0x80
	s_addc_u32 s25, s25, 0
	s_add_i32 m0, s0, 0x8000
	s_nop 0
	global_load_lds_dwordx4 v140, s[22:23]
	s_add_i32 m0, s0, 0xa000
	s_nop 0
	global_load_lds_dwordx4 v144, s[22:23]
	s_add_i32 m0, s0, 0x1c000
	s_nop 0
	global_load_lds_dwordx4 v142, s[24:25]
	s_add_i32 m0, s0, 0x1e000
	s_nop 0
	global_load_lds_dwordx4 v146, s[24:25]
	s_waitcnt lgkmcnt(0)
	v_mfma_f32_16x16x32_bf16 v[116:119], v[180:183], v[196:199], v[116:119]
	v_mfma_f32_16x16x32_bf16 v[112:115], v[188:191], v[196:199], v[112:115]
	v_mfma_f32_16x16x32_bf16 v[100:103], v[180:183], v[204:207], v[100:103]
	v_mfma_f32_16x16x32_bf16 v[96:99], v[188:191], v[204:207], v[96:99]
	v_mfma_f32_16x16x32_bf16 v[84:87], v[180:183], v[212:215], v[84:87]
	v_mfma_f32_16x16x32_bf16 v[80:83], v[188:191], v[212:215], v[80:83]
	v_mfma_f32_16x16x32_bf16 v[68:71], v[180:183], v[220:223], v[68:71]
	v_mfma_f32_16x16x32_bf16 v[64:67], v[188:191], v[220:223], v[64:67]
	v_mfma_f32_16x16x32_bf16 v[116:119], v[184:187], v[200:203], v[116:119]
	v_mfma_f32_16x16x32_bf16 v[112:115], v[192:195], v[200:203], v[112:115]
	v_mfma_f32_16x16x32_bf16 v[100:103], v[184:187], v[208:211], v[100:103]
	v_mfma_f32_16x16x32_bf16 v[96:99], v[192:195], v[208:211], v[96:99]
	v_mfma_f32_16x16x32_bf16 v[84:87], v[184:187], v[216:219], v[84:87]
	v_mfma_f32_16x16x32_bf16 v[80:83], v[192:195], v[216:219], v[80:83]
	v_mfma_f32_16x16x32_bf16 v[68:71], v[184:187], v[224:227], v[68:71]
	v_mfma_f32_16x16x32_bf16 v[64:67], v[192:195], v[224:227], v[64:67]
	s_waitcnt vmcnt(8)
	s_barrier
	ds_read_b128 v[180:183], v163
	ds_read_b128 v[184:187], v163 offset:1024
	ds_read_b128 v[188:191], v163 offset:2048
	ds_read_b128 v[192:195], v163 offset:3072
	ds_read_b128 v[196:199], v162 offset:49152
	ds_read_b128 v[200:203], v162 offset:50176
	ds_read_b128 v[204:207], v162 offset:51200
	ds_read_b128 v[208:211], v162 offset:52224
	ds_read_b128 v[212:215], v162 offset:53248
	ds_read_b128 v[216:219], v162 offset:54272
	ds_read_b128 v[220:223], v162 offset:55296
	ds_read_b128 v[224:227], v162 offset:56320
	s_add_u32 s22, s22, 0x80
	s_addc_u32 s23, s23, 0
	s_add_u32 s24, s24, 0x80
	s_addc_u32 s25, s25, 0
	s_add_i32 m0, s0, 0x4000
	s_nop 0
	global_load_lds_dwordx4 v140, s[22:23]
	s_add_i32 m0, s0, 0x6000
	s_nop 0
	global_load_lds_dwordx4 v144, s[22:23]
	s_add_i32 m0, s0, 0x10000
	s_nop 0
	global_load_lds_dwordx4 v142, s[24:25]
	s_add_i32 m0, s0, 0x12000
	s_nop 0
	global_load_lds_dwordx4 v146, s[24:25]
	s_waitcnt lgkmcnt(0)
	v_mfma_f32_16x16x32_bf16 v[116:119], v[180:183], v[196:199], v[116:119]
	v_mfma_f32_16x16x32_bf16 v[112:115], v[188:191], v[196:199], v[112:115]
	v_mfma_f32_16x16x32_bf16 v[100:103], v[180:183], v[204:207], v[100:103]
	v_mfma_f32_16x16x32_bf16 v[96:99], v[188:191], v[204:207], v[96:99]
	v_mfma_f32_16x16x32_bf16 v[84:87], v[180:183], v[212:215], v[84:87]
	v_mfma_f32_16x16x32_bf16 v[80:83], v[188:191], v[212:215], v[80:83]
	v_mfma_f32_16x16x32_bf16 v[68:71], v[180:183], v[220:223], v[68:71]
	v_mfma_f32_16x16x32_bf16 v[64:67], v[188:191], v[220:223], v[64:67]
	v_mfma_f32_16x16x32_bf16 v[116:119], v[184:187], v[200:203], v[116:119]
	v_mfma_f32_16x16x32_bf16 v[112:115], v[192:195], v[200:203], v[112:115]
	v_mfma_f32_16x16x32_bf16 v[100:103], v[184:187], v[208:211], v[100:103]
	v_mfma_f32_16x16x32_bf16 v[96:99], v[192:195], v[208:211], v[96:99]
	v_mfma_f32_16x16x32_bf16 v[84:87], v[184:187], v[216:219], v[84:87]
	v_mfma_f32_16x16x32_bf16 v[80:83], v[192:195], v[216:219], v[80:83]
	v_mfma_f32_16x16x32_bf16 v[68:71], v[184:187], v[224:227], v[68:71]
	v_mfma_f32_16x16x32_bf16 v[64:67], v[192:195], v[224:227], v[64:67]
	s_waitcnt vmcnt(8)
	s_barrier
; #define PG8_WAIT_V(n) asm volatile("s_waitcnt vmcnt(" #n ")" ::: "memory")
; template <class Epi, class Sched, bool ALIGN_EPI = false, bool SP2 = false>
; __device__ __forceinline__ void gemm_phase(PG8_LAS unsigned char* lds, const Gemm g, const Sched& S, const Epi& E) {
;     ...
;         for (int t = 0; t < nt; t += 2) {
;             const bool last = (t == nt - 2);
;             const char* a1 = cA + (size_t)(t + 1) * kstep;
;             const char* a2 = last ? nA : cA + (size_t)(t + 2) * kstep; const char* b2 = last ? nB : cB + (size_t)(t + 2) * kstep;
;             const char* a3 = a2 + kstep; const char* b3 = b2 + kstep;
;             if (last && has_next) S.a_ready(nxt);
;             if constexpr (SP2) {
;             PG8_LDB(B0, 0, 0); PG8_LDB(B1, 0, 1); PG8_SCHED; PG8_LDA(At, 0, 0); PG8_STAGE(PG8_SA(1, 1), a1 + hstep, voffA);
;             PG8_WAIT_V(8); PG8_WAIT_L(0); PG8_BAR; PG8_MMA(0, 0, At, B0); PG8_MMA(0, 1, At, B1); PG8_BAR; PG8_SCHED;
;             PG8_LDA(At, 0, 1); PG8_STAGE(PG8_SB(0, 0), b2, voffB); PG8_STAGE(PG8_SB(0, 1), b2 + hstep, voffB); PG8_STAGE(PG8_SA(0, 0), a2, voffA);
;             PG8_WAIT_V(8); PG8_WAIT_L(0); PG8_BAR; PG8_MMA(1, 0, At, B0); PG8_MMA(1, 1, At, B1); PG8_BAR; PG8_SCHED;
;             PG8_LDB(B0, 1, 0); PG8_LDB(B1, 1, 1); PG8_SCHED; PG8_LDA(At, 1, 0); PG8_STAGE(PG8_SA(0, 1), a2 + hstep, voffA);
;             PG8_WAIT_V(8); PG8_WAIT_L(0); PG8_BAR; PG8_MMA(0, 0, At, B0); PG8_MMA(0, 1, At, B1); PG8_BAR; PG8_SCHED;
;             PG8_LDA(At, 1, 1); PG8_STAGE(PG8_SB(1, 0), b3, voffB); PG8_STAGE(PG8_SB(1, 1), b3 + hstep, voffB); PG8_STAGE(PG8_SA(1, 0), a3, voffA);
;             PG8_WAIT_V(8); PG8_WAIT_L(0); PG8_BAR; PG8_MMA(1, 0, At, B0); PG8_MMA(1, 1, At, B1); PG8_BAR; PG8_SCHED;
;             } else {
;             PG8_LDB(B0, 0, 0); PG8_SCHED; PG8_LDA(At, 0, 0); PG8_STAGE(PG8_SA(1, 1), a1 + hstep, voffA);
;             PG8_WAIT_L(8); PG8_BAR; PG8_WAIT_L(0); PG8_MMA(0, 0, At, B0); PG8_BAR; PG8_SCHED;
;             PG8_LDB(B1, 0, 1); PG8_STAGE(PG8_SB(0, 0), b2, voffB);
;             PG8_BAR; PG8_WAIT_L(0); PG8_MMA(0, 1, At, B1); PG8_BAR;
;             PG8_LDA(At, 0, 1); PG8_STAGE(PG8_SA(0, 0), a2, voffA);
;             PG8_BAR; PG8_WAIT_L(0); PG8_MMA(1, 0, At, B0); PG8_BAR; PG8_SCHED;
;             PG8_STAGE(PG8_SB(0, 1), b2 + hstep, voffB);
;             PG8_WAIT_V(6); PG8_BAR; PG8_MMA(1, 1, At, B1); PG8_BAR;
	ds_read_b128 v[180:183], v161
	ds_read_b128 v[184:187], v161 offset:1024
	ds_read_b128 v[188:191], v161 offset:2048
	ds_read_b128 v[192:195], v161 offset:3072
	ds_read_b128 v[196:199], v162
	ds_read_b128 v[200:203], v162 offset:1024
	ds_read_b128 v[204:207], v162 offset:2048
	ds_read_b128 v[208:211], v162 offset:3072
	ds_read_b128 v[212:215], v162 offset:4096
	ds_read_b128 v[216:219], v162 offset:5120
	ds_read_b128 v[220:223], v162 offset:6144
	ds_read_b128 v[224:227], v162 offset:7168
	s_add_u32 s22, s22, 0x80
	s_addc_u32 s23, s23, 0
	s_add_u32 s24, s24, 0x80
	s_addc_u32 s25, s25, 0
	s_add_i32 m0, s0, 0xc000
	s_nop 0
	global_load_lds_dwordx4 v140, s[22:23]
	s_add_i32 m0, s0, 0xe000
	s_nop 0
	global_load_lds_dwordx4 v144, s[22:23]
	s_add_i32 m0, s0, 0x18000
	s_nop 0
	global_load_lds_dwordx4 v142, s[24:25]
	s_add_i32 m0, s0, 0x1a000
	s_nop 0
	global_load_lds_dwordx4 v146, s[24:25]
	s_waitcnt lgkmcnt(0)
	v_mfma_f32_16x16x32_bf16 v[116:119], v[180:183], v[196:199], v[116:119]
	v_mfma_f32_16x16x32_bf16 v[112:115], v[188:191], v[196:199], v[112:115]
	v_mfma_f32_16x16x32_bf16 v[100:103], v[180:183], v[204:207], v[100:103]
	v_mfma_f32_16x16x32_bf16 v[96:99], v[188:191], v[204:207], v[96:99]
	v_mfma_f32_16x16x32_bf16 v[84:87], v[180:183], v[212:215], v[84:87]
	v_mfma_f32_16x16x32_bf16 v[80:83], v[188:191], v[212:215], v[80:83]
	v_mfma_f32_16x16x32_bf16 v[68:71], v[180:183], v[220:223], v[68:71]
	v_mfma_f32_16x16x32_bf16 v[64:67], v[188:191], v[220:223], v[64:67]
	v_mfma_f32_16x16x32_bf16 v[116:119], v[184:187], v[200:203], v[116:119]
	v_mfma_f32_16x16x32_bf16 v[112:115], v[192:195], v[200:203], v[112:115]
	v_mfma_f32_16x16x32_bf16 v[100:103], v[184:187], v[208:211], v[100:103]
	v_mfma_f32_16x16x32_bf16 v[96:99], v[192:195], v[208:211], v[96:99]
	v_mfma_f32_16x16x32_bf16 v[84:87], v[184:187], v[216:219], v[84:87]
	v_mfma_f32_16x16x32_bf16 v[80:83], v[192:195], v[216:219], v[80:83]
	v_mfma_f32_16x16x32_bf16 v[68:71], v[184:187], v[224:227], v[68:71]
	v_mfma_f32_16x16x32_bf16 v[64:67], v[192:195], v[224:227], v[64:67]
	s_waitcnt vmcnt(8)
	s_barrier
	ds_read_b128 v[180:183], v164
	ds_read_b128 v[184:187], v164 offset:1024
	ds_read_b128 v[188:191], v164 offset:2048
	ds_read_b128 v[192:195], v164 offset:3072
	ds_read_b128 v[196:199], v162 offset:32768
	ds_read_b128 v[200:203], v162 offset:33792
	ds_read_b128 v[204:207], v162 offset:34816
	ds_read_b128 v[208:211], v162 offset:35840
	ds_read_b128 v[212:215], v162 offset:36864
	ds_read_b128 v[216:219], v162 offset:37888
	ds_read_b128 v[220:223], v162 offset:38912
	ds_read_b128 v[224:227], v162 offset:39936
	s_add_u32 s22, s22, 0x80
	s_addc_u32 s23, s23, 0
	s_add_u32 s24, s24, 0x80
	s_addc_u32 s25, s25, 0
	s_mov_b32 m0, s0
	s_nop 0
	global_load_lds_dwordx4 v140, s[22:23]
	s_add_i32 m0, s0, 0x2000
	s_nop 0
	global_load_lds_dwordx4 v144, s[22:23]
	s_add_i32 m0, s0, 0x14000
	s_nop 0
	global_load_lds_dwordx4 v142, s[24:25]
	s_add_i32 m0, s0, 0x16000
	s_nop 0
	global_load_lds_dwordx4 v146, s[24:25]
	s_waitcnt lgkmcnt(0)
	v_mfma_f32_16x16x32_bf16 v[116:119], v[180:183], v[196:199], v[116:119]
	v_mfma_f32_16x16x32_bf16 v[112:115], v[188:191], v[196:199], v[112:115]
	v_mfma_f32_16x16x32_bf16 v[100:103], v[180:183], v[204:207], v[100:103]
	v_mfma_f32_16x16x32_bf16 v[96:99], v[188:191], v[204:207], v[96:99]
	v_mfma_f32_16x16x32_bf16 v[84:87], v[180:183], v[212:215], v[84:87]
	v_mfma_f32_16x16x32_bf16 v[80:83], v[188:191], v[212:215], v[80:83]
	v_mfma_f32_16x16x32_bf16 v[68:71], v[180:183], v[220:223], v[68:71]
	v_mfma_f32_16x16x32_bf16 v[64:67], v[188:191], v[220:223], v[64:67]
	v_mfma_f32_16x16x32_bf16 v[116:119], v[184:187], v[200:203], v[116:119]
	v_mfma_f32_16x16x32_bf16 v[112:115], v[192:195], v[200:203], v[112:115]
	v_mfma_f32_16x16x32_bf16 v[100:103], v[184:187], v[208:211], v[100:103]
	v_mfma_f32_16x16x32_bf16 v[96:99], v[192:195], v[208:211], v[96:99]
	v_mfma_f32_16x16x32_bf16 v[84:87], v[184:187], v[216:219], v[84:87]
	v_mfma_f32_16x16x32_bf16 v[80:83], v[192:195], v[216:219], v[80:83]
	v_mfma_f32_16x16x32_bf16 v[68:71], v[184:187], v[224:227], v[68:71]
	v_mfma_f32_16x16x32_bf16 v[64:67], v[192:195], v[224:227], v[64:67]
	s_waitcnt vmcnt(8)
	s_barrier
	ds_read_b128 v[180:183], v160
	ds_read_b128 v[184:187], v160 offset:1024
	ds_read_b128 v[188:191], v160 offset:2048
	ds_read_b128 v[192:195], v160 offset:3072
	ds_read_b128 v[196:199], v162 offset:16384
	ds_read_b128 v[200:203], v162 offset:17408
	ds_read_b128 v[204:207], v162 offset:18432
	ds_read_b128 v[208:211], v162 offset:19456
	ds_read_b128 v[212:215], v162 offset:20480
	ds_read_b128 v[216:219], v162 offset:21504
	ds_read_b128 v[220:223], v162 offset:22528
	ds_read_b128 v[224:227], v162 offset:23552
	s_add_u32 s22, s22, 0x80
	s_addc_u32 s23, s23, 0
	s_add_u32 s24, s24, 0x80
	s_addc_u32 s25, s25, 0
	s_add_i32 m0, s0, 0x8000
	s_nop 0
	global_load_lds_dwordx4 v140, s[22:23]
	s_add_i32 m0, s0, 0xa000
	s_nop 0
	global_load_lds_dwordx4 v144, s[22:23]
	s_add_i32 m0, s0, 0x1c000
	s_nop 0
	global_load_lds_dwordx4 v142, s[24:25]
	s_add_i32 m0, s0, 0x1e000
	s_nop 0
	global_load_lds_dwordx4 v146, s[24:25]
	s_waitcnt lgkmcnt(0)
	v_mfma_f32_16x16x32_bf16 v[116:119], v[180:183], v[196:199], v[116:119]
	v_mfma_f32_16x16x32_bf16 v[112:115], v[188:191], v[196:199], v[112:115]
	v_mfma_f32_16x16x32_bf16 v[100:103], v[180:183], v[204:207], v[100:103]
	v_mfma_f32_16x16x32_bf16 v[96:99], v[188:191], v[204:207], v[96:99]
	v_mfma_f32_16x16x32_bf16 v[84:87], v[180:183], v[212:215], v[84:87]
	v_mfma_f32_16x16x32_bf16 v[80:83], v[188:191], v[212:215], v[80:83]
	v_mfma_f32_16x16x32_bf16 v[68:71], v[180:183], v[220:223], v[68:71]
	v_mfma_f32_16x16x32_bf16 v[64:67], v[188:191], v[220:223], v[64:67]
	v_mfma_f32_16x16x32_bf16 v[116:119], v[184:187], v[200:203], v[116:119]
	v_mfma_f32_16x16x32_bf16 v[112:115], v[192:195], v[200:203], v[112:115]
	v_mfma_f32_16x16x32_bf16 v[100:103], v[184:187], v[208:211], v[100:103]
	v_mfma_f32_16x16x32_bf16 v[96:99], v[192:195], v[208:211], v[96:99]
	v_mfma_f32_16x16x32_bf16 v[84:87], v[184:187], v[216:219], v[84:87]
	v_mfma_f32_16x16x32_bf16 v[80:83], v[192:195], v[216:219], v[80:83]
	v_mfma_f32_16x16x32_bf16 v[68:71], v[184:187], v[224:227], v[68:71]
	v_mfma_f32_16x16x32_bf16 v[64:67], v[192:195], v[224:227], v[64:67]
	s_waitcnt vmcnt(8)
	s_barrier
; #define PG8_STAGE(bufoff, gbase, voff) do { _Pragma("unroll") for (int _i = 0; _i < 2; ++_i) \
;         __builtin_amdgcn_global_load_lds((const unsigned*)((const char*)(gbase) + (voff)[_i]), (PG8_LAS unsigned*)(lds + (bufoff) + ldsw + _i * 8192), 16, 0, 0); } while (0)
; #define PG8_LDA(dst, b, h) do { _Pragma("unroll") for (int m = 0; m < 4; ++m) _Pragma("unroll") for (int k = 0; k < 2; ++k) dst[m][k] = *(const PG8_LAS bf16x8*)(lds + PG8_SA(b, h) + aoff + m * 2048 + k * 1024); } while (0)
; #define PG8_LDB(dst, b, h) do { _Pragma("unroll") for (int n = 0; n < 2; ++n) _Pragma("unroll") for (int k = 0; k < 2; ++k) dst[n][k] = *(const PG8_LAS bf16x8*)(lds + PG8_SB(b, h) + boff + n * 2048 + k * 1024); } while (0)
; #define PG8_WAIT_V(n) asm volatile("s_waitcnt vmcnt(" #n ")" ::: "memory")
; #define PG8_WAIT_L(n) asm volatile("s_waitcnt lgkmcnt(" #n ")" ::: "memory")
; template <class Epi, class Sched, bool ALIGN_EPI = false, bool SP2 = false>
; __device__ __forceinline__ void gemm_phase(PG8_LAS unsigned char* lds, const Gemm g, const Sched& S, const Epi& E) {
;     ...
;             PG8_LDB(B0, 1, 0); PG8_LDB(B1, 1, 1); PG8_SCHED; PG8_LDA(At, 1, 0); PG8_STAGE(PG8_SA(0, 1), a2 + hstep, voffA);
;             PG8_WAIT_V(8); PG8_WAIT_L(0); PG8_BAR; PG8_MMA(0, 0, At, B0); PG8_MMA(0, 1, At, B1); PG8_BAR; PG8_SCHED;
;             PG8_LDA(At, 1, 1); PG8_STAGE(PG8_SB(1, 0), b3, voffB); PG8_STAGE(PG8_SB(1, 1), b3 + hstep, voffB); PG8_STAGE(PG8_SA(1, 0), a3, voffA);
;     DI void operator()(const f32x4 (&acc)[2][2][4][2], const pg8::Unit& u, int wr, int wc, int fr, int fq) const {
;     ...
;                 const int R = u.pm * 256 + ai * 128 + wr * 64 + m * 16 + fr;
;                 const float* xs = nullptr; float* yd = nullptr;
;                 if (R < ROWS_P) { const int b = R / LPAD, t = R - b * LPAD; if (t >= NMETA && t < LP) { const size_t idx = ((size_t)b * SEQ + t - NMETA) * DM; xs = p.x_prompt + idx; yd = p.out + O_YP + idx; } }
;                 else { const size_t idx = (size_t)(R - ROWS_P) * DM; xs = p.x_sample + idx; yd = p.out + O_YS + idx; }
;                 float ss = 0.f;
;                 if (xs) {
; #pragma unroll
;                     for (int bj = 0; bj < 2; ++bj) {
;                         const int n = colt + bj * 128 + wc * 32 + 8 * fq;
;                         const f32x4 x0 = *(const f32x4*)(xs + n), x1 = *(const f32x4*)(xs + n + 4);
	ds_read_b128 v[180:183], v163
	ds_read_b128 v[184:187], v163 offset:1024
	ds_read_b128 v[188:191], v163 offset:2048
	ds_read_b128 v[192:195], v163 offset:3072
	ds_read_b128 v[196:199], v162 offset:49152
	ds_read_b128 v[200:203], v162 offset:50176
	ds_read_b128 v[204:207], v162 offset:51200
	ds_read_b128 v[208:211], v162 offset:52224
	ds_read_b128 v[212:215], v162 offset:53248
	ds_read_b128 v[216:219], v162 offset:54272
	ds_read_b128 v[220:223], v162 offset:55296
	ds_read_b128 v[224:227], v162 offset:56320
	s_add_u32 s22, s22, 0x80
	s_addc_u32 s23, s23, 0
	s_add_u32 s24, s24, 0x80
	s_addc_u32 s25, s25, 0
	s_add_i32 m0, s0, 0x4000
	s_nop 0
	global_load_lds_dwordx4 v140, s[22:23]
	s_add_i32 m0, s0, 0x6000
	s_nop 0
	global_load_lds_dwordx4 v144, s[22:23]
	s_add_i32 m0, s0, 0x10000
	s_nop 0
	global_load_lds_dwordx4 v142, s[24:25]
	s_add_i32 m0, s0, 0x12000
	s_nop 0
	global_load_lds_dwordx4 v146, s[24:25]
	s_waitcnt lgkmcnt(0)
	v_mfma_f32_16x16x32_bf16 v[116:119], v[180:183], v[196:199], v[116:119]
	v_mfma_f32_16x16x32_bf16 v[112:115], v[188:191], v[196:199], v[112:115]
	v_mfma_f32_16x16x32_bf16 v[100:103], v[180:183], v[204:207], v[100:103]
	v_mfma_f32_16x16x32_bf16 v[96:99], v[188:191], v[204:207], v[96:99]
	v_mfma_f32_16x16x32_bf16 v[84:87], v[180:183], v[212:215], v[84:87]
	v_mfma_f32_16x16x32_bf16 v[80:83], v[188:191], v[212:215], v[80:83]
	v_mfma_f32_16x16x32_bf16 v[68:71], v[180:183], v[220:223], v[68:71]
	v_mfma_f32_16x16x32_bf16 v[64:67], v[188:191], v[220:223], v[64:67]
	v_mfma_f32_16x16x32_bf16 v[116:119], v[184:187], v[200:203], v[116:119]
	v_mfma_f32_16x16x32_bf16 v[112:115], v[192:195], v[200:203], v[112:115]
	v_mfma_f32_16x16x32_bf16 v[100:103], v[184:187], v[208:211], v[100:103]
	v_mfma_f32_16x16x32_bf16 v[96:99], v[192:195], v[208:211], v[96:99]
	v_mfma_f32_16x16x32_bf16 v[84:87], v[184:187], v[216:219], v[84:87]
	v_mfma_f32_16x16x32_bf16 v[80:83], v[192:195], v[216:219], v[80:83]
	v_mfma_f32_16x16x32_bf16 v[68:71], v[184:187], v[224:227], v[68:71]
	v_mfma_f32_16x16x32_bf16 v[64:67], v[192:195], v[224:227], v[64:67]
	s_waitcnt vmcnt(8)
	s_barrier
	ds_read_b128 v[180:183], v161
	ds_read_b128 v[184:187], v161 offset:1024
	ds_read_b128 v[188:191], v161 offset:2048
	ds_read_b128 v[192:195], v161 offset:3072
	ds_read_b128 v[196:199], v162
	ds_read_b128 v[200:203], v162 offset:1024
	ds_read_b128 v[204:207], v162 offset:2048
	ds_read_b128 v[208:211], v162 offset:3072
	ds_read_b128 v[212:215], v162 offset:4096
	ds_read_b128 v[216:219], v162 offset:5120
	ds_read_b128 v[220:223], v162 offset:6144
	ds_read_b128 v[224:227], v162 offset:7168
	s_add_u32 s22, s22, 0x80
	s_addc_u32 s23, s23, 0
	s_add_u32 s24, s24, 0x80
	s_addc_u32 s25, s25, 0
	s_add_i32 m0, s0, 0xc000
	s_nop 0
	global_load_lds_dwordx4 v140, s[22:23]
	s_add_i32 m0, s0, 0xe000
	s_nop 0
	global_load_lds_dwordx4 v144, s[22:23]
	s_add_i32 m0, s0, 0x18000
	s_nop 0
	global_load_lds_dwordx4 v142, s[24:25]
	s_add_i32 m0, s0, 0x1a000
	s_nop 0
	global_load_lds_dwordx4 v146, s[24:25]
	v_lshl_or_b32 v236, s42, 8, v159
	v_and_b32_e32 v237, 15, v158
	v_lshlrev_b32_e32 v236, 2, v236
	v_lshl_or_b32 v236, v237, 12, v236
	s_and_b64 vcc, s[72:73], exec
	s_cselect_b32 s35, 64, 0
	s_lshl_b32 s32, s94, 8
	s_add_i32 s35, s35, s32
	s_add_i32 s32, s35, 0
	s_mul_hi_u32 s34, s32, 0x7e07e07f
	s_lshr_b32 s34, s34, 11
	s_mul_i32 vcc_lo, s34, 0x1040
	s_sub_i32 vcc_lo, s32, vcc_lo
	s_add_i32 vcc_lo, vcc_lo, -16
	s_lshl_b32 s34, s34, 12
	s_add_i32 s34, s34, vcc_lo
	s_cmp_lt_u32 vcc_lo, 0x1000
	s_cselect_b32 vcc_hi, 1, 0
	s_sub_i32 vcc_lo, s32, 0x4100
	s_cmp_ge_u32 s94, 65
	s_cselect_b32 s34, vcc_lo, s34
	s_cselect_b32 vcc_hi, 1, vcc_hi
	s_cselect_b32 s30, s78, s76
	s_cselect_b32 s31, s79, s77
	s_cmp_lg_u32 vcc_hi, 0
	s_cselect_b32 s34, s34, 0
	s_lshl_b32 s34, s34, 12
	s_add_u32 s30, s30, s34
	s_addc_u32 s31, s31, 0
	global_load_dwordx4 v[0:3], v236, s[30:31] offset:512
	global_load_dwordx4 v[4:7], v236, s[30:31] offset:528
	s_add_i32 s32, s35, 16
	s_mul_hi_u32 s34, s32, 0x7e07e07f
	s_lshr_b32 s34, s34, 11
	s_mul_i32 vcc_lo, s34, 0x1040
	s_sub_i32 vcc_lo, s32, vcc_lo
	s_add_i32 vcc_lo, vcc_lo, -16
	s_lshl_b32 s34, s34, 12
	s_add_i32 s34, s34, vcc_lo
	s_cmp_lt_u32 vcc_lo, 0x1000
	s_cselect_b32 vcc_hi, 1, 0
	s_sub_i32 vcc_lo, s32, 0x4100
	s_cmp_ge_u32 s94, 65
	s_cselect_b32 s34, vcc_lo, s34
	s_cselect_b32 vcc_hi, 1, vcc_hi
	s_cselect_b32 s30, s78, s76
	s_cselect_b32 s31, s79, s77
	s_cmp_lg_u32 vcc_hi, 0
	s_cselect_b32 s34, s34, 0
	s_lshl_b32 s34, s34, 12
	s_add_u32 s30, s30, s34
	s_addc_u32 s31, s31, 0
	global_load_dwordx4 v[8:11], v236, s[30:31] offset:512
	global_load_dwordx4 v[12:15], v236, s[30:31] offset:528
	s_add_i32 s32, s35, 32
	s_mul_hi_u32 s34, s32, 0x7e07e07f
	s_lshr_b32 s34, s34, 11
	s_mul_i32 vcc_lo, s34, 0x1040
	s_sub_i32 vcc_lo, s32, vcc_lo
	s_add_i32 vcc_lo, vcc_lo, -16
	s_lshl_b32 s34, s34, 12
	s_add_i32 s34, s34, vcc_lo
	s_cmp_lt_u32 vcc_lo, 0x1000
	s_cselect_b32 vcc_hi, 1, 0
	s_sub_i32 vcc_lo, s32, 0x4100
	s_cmp_ge_u32 s94, 65
	s_cselect_b32 s34, vcc_lo, s34
	s_cselect_b32 vcc_hi, 1, vcc_hi
	s_cselect_b32 s30, s78, s76
	s_cselect_b32 s31, s79, s77
	s_cmp_lg_u32 vcc_hi, 0
	s_cselect_b32 s34, s34, 0
	s_lshl_b32 s34, s34, 12
	s_add_u32 s30, s30, s34
	s_addc_u32 s31, s31, 0
	global_load_dwordx4 v[16:19], v236, s[30:31] offset:512
	global_load_dwordx4 v[20:23], v236, s[30:31] offset:528
	s_add_i32 s32, s35, 48
	s_mul_hi_u32 s34, s32, 0x7e07e07f
	s_lshr_b32 s34, s34, 11
	s_mul_i32 vcc_lo, s34, 0x1040
	s_sub_i32 vcc_lo, s32, vcc_lo
	s_add_i32 vcc_lo, vcc_lo, -16
	s_lshl_b32 s34, s34, 12
	s_add_i32 s34, s34, vcc_lo
	s_cmp_lt_u32 vcc_lo, 0x1000
	s_cselect_b32 vcc_hi, 1, 0
	s_sub_i32 vcc_lo, s32, 0x4100
	s_cmp_ge_u32 s94, 65
	s_cselect_b32 s34, vcc_lo, s34
	s_cselect_b32 vcc_hi, 1, vcc_hi
	s_cselect_b32 s30, s78, s76
	s_cselect_b32 s31, s79, s77
	s_cmp_lg_u32 vcc_hi, 0
	s_cselect_b32 s34, s34, 0
	s_lshl_b32 s34, s34, 12
	s_add_u32 s30, s30, s34
	s_addc_u32 s31, s31, 0
	global_load_dwordx4 v[24:27], v236, s[30:31] offset:512
	global_load_dwordx4 v[28:31], v236, s[30:31] offset:528
	s_waitcnt lgkmcnt(0)
; #define PG8_STAGE(bufoff, gbase, voff) do { _Pragma("unroll") for (int _i = 0; _i < 2; ++_i) \
;         __builtin_amdgcn_global_load_lds((const unsigned*)((const char*)(gbase) + (voff)[_i]), (PG8_LAS unsigned*)(lds + (bufoff) + ldsw + _i * 8192), 16, 0, 0); } while (0)
; #define PG8_LDA(dst, b, h) do { _Pragma("unroll") for (int m = 0; m < 4; ++m) _Pragma("unroll") for (int k = 0; k < 2; ++k) dst[m][k] = *(const PG8_LAS bf16x8*)(lds + PG8_SA(b, h) + aoff + m * 2048 + k * 1024); } while (0)
; #define PG8_LDB(dst, b, h) do { _Pragma("unroll") for (int n = 0; n < 2; ++n) _Pragma("unroll") for (int k = 0; k < 2; ++k) dst[n][k] = *(const PG8_LAS bf16x8*)(lds + PG8_SB(b, h) + boff + n * 2048 + k * 1024); } while (0)
; #define PG8_MMA(ai, bj, At, Bt) do { __builtin_amdgcn_s_setprio(1); _Pragma("unroll") for (int m = 0; m < 4; ++m) _Pragma("unroll") for (int n = 0; n < 2; ++n) _Pragma("unroll") for (int k = 0; k < 2; ++k) \
;         acc[ai][bj][m][n] = __builtin_amdgcn_mfma_f32_16x16x32_bf16(Bt[n][k], At[m][k], acc[ai][bj][m][n], 0, 0, 0); __builtin_amdgcn_s_setprio(0); } while (0)
; #define PG8_WAIT_V(n) asm volatile("s_waitcnt vmcnt(" #n ")" ::: "memory")
; template <class Epi, class Sched, bool ALIGN_EPI = false, bool SP2 = false>
; __device__ __forceinline__ void gemm_phase(PG8_LAS unsigned char* lds, const Gemm g, const Sched& S, const Epi& E) {
;     ...
;             PG8_LDB(B0, 0, 0); PG8_LDB(B1, 0, 1); PG8_SCHED; PG8_LDA(At, 0, 0); PG8_STAGE(PG8_SA(1, 1), a1 + hstep, voffA);
;             PG8_WAIT_V(8); PG8_WAIT_L(0); PG8_BAR; PG8_MMA(0, 0, At, B0); PG8_MMA(0, 1, At, B1); PG8_BAR; PG8_SCHED;
;             PG8_LDA(At, 0, 1); PG8_STAGE(PG8_SB(0, 0), b2, voffB); PG8_STAGE(PG8_SB(0, 1), b2 + hstep, voffB); PG8_STAGE(PG8_SA(0, 0), a2, voffA);
;             PG8_WAIT_V(8); PG8_WAIT_L(0); PG8_BAR; PG8_MMA(1, 0, At, B0); PG8_MMA(1, 1, At, B1); PG8_BAR; PG8_SCHED;
;             PG8_LDB(B0, 1, 0); PG8_LDB(B1, 1, 1); PG8_SCHED; PG8_LDA(At, 1, 0); PG8_STAGE(PG8_SA(0, 1), a2 + hstep, voffA);
;             PG8_WAIT_V(8); PG8_WAIT_L(0); PG8_BAR; PG8_MMA(0, 0, At, B0); PG8_MMA(0, 1, At, B1); PG8_BAR; PG8_SCHED;
;             PG8_LDA(At, 1, 1); PG8_STAGE(PG8_SB(1, 0), b3, voffB); PG8_STAGE(PG8_SB(1, 1), b3 + hstep, voffB); PG8_STAGE(PG8_SA(1, 0), a3, voffA);
;             PG8_WAIT_V(8); PG8_WAIT_L(0); PG8_BAR; PG8_MMA(1, 0, At, B0); PG8_MMA(1, 1, At, B1); PG8_BAR; PG8_SCHED;
	v_mfma_f32_16x16x32_bf16 v[116:119], v[180:183], v[196:199], v[116:119]
	v_mfma_f32_16x16x32_bf16 v[112:115], v[188:191], v[196:199], v[112:115]
	v_mfma_f32_16x16x32_bf16 v[100:103], v[180:183], v[204:207], v[100:103]
	v_mfma_f32_16x16x32_bf16 v[96:99], v[188:191], v[204:207], v[96:99]
	v_mfma_f32_16x16x32_bf16 v[84:87], v[180:183], v[212:215], v[84:87]
	v_mfma_f32_16x16x32_bf16 v[80:83], v[188:191], v[212:215], v[80:83]
	v_mfma_f32_16x16x32_bf16 v[68:71], v[180:183], v[220:223], v[68:71]
	v_mfma_f32_16x16x32_bf16 v[64:67], v[188:191], v[220:223], v[64:67]
	v_mfma_f32_16x16x32_bf16 v[116:119], v[184:187], v[200:203], v[116:119]
	v_mfma_f32_16x16x32_bf16 v[112:115], v[192:195], v[200:203], v[112:115]
	v_mfma_f32_16x16x32_bf16 v[100:103], v[184:187], v[208:211], v[100:103]
	v_mfma_f32_16x16x32_bf16 v[96:99], v[192:195], v[208:211], v[96:99]
	v_mfma_f32_16x16x32_bf16 v[84:87], v[184:187], v[216:219], v[84:87]
	v_mfma_f32_16x16x32_bf16 v[80:83], v[192:195], v[216:219], v[80:83]
	v_mfma_f32_16x16x32_bf16 v[68:71], v[184:187], v[224:227], v[68:71]
	v_mfma_f32_16x16x32_bf16 v[64:67], v[192:195], v[224:227], v[64:67]
	s_waitcnt vmcnt(16)
	s_barrier
	ds_read_b128 v[180:183], v164
	ds_read_b128 v[184:187], v164 offset:1024
	ds_read_b128 v[188:191], v164 offset:2048
	ds_read_b128 v[192:195], v164 offset:3072
	ds_read_b128 v[196:199], v162 offset:32768
	ds_read_b128 v[200:203], v162 offset:33792
	ds_read_b128 v[204:207], v162 offset:34816
	ds_read_b128 v[208:211], v162 offset:35840
	ds_read_b128 v[212:215], v162 offset:36864
	ds_read_b128 v[216:219], v162 offset:37888
	ds_read_b128 v[220:223], v162 offset:38912
	ds_read_b128 v[224:227], v162 offset:39936
	s_waitcnt lgkmcnt(0)
	v_mfma_f32_16x16x32_bf16 v[116:119], v[180:183], v[196:199], v[116:119]
	v_mfma_f32_16x16x32_bf16 v[112:115], v[188:191], v[196:199], v[112:115]
	v_mfma_f32_16x16x32_bf16 v[100:103], v[180:183], v[204:207], v[100:103]
	v_mfma_f32_16x16x32_bf16 v[96:99], v[188:191], v[204:207], v[96:99]
	v_mfma_f32_16x16x32_bf16 v[84:87], v[180:183], v[212:215], v[84:87]
	v_mfma_f32_16x16x32_bf16 v[80:83], v[188:191], v[212:215], v[80:83]
	v_mfma_f32_16x16x32_bf16 v[68:71], v[180:183], v[220:223], v[68:71]
	v_mfma_f32_16x16x32_bf16 v[64:67], v[188:191], v[220:223], v[64:67]
	v_mfma_f32_16x16x32_bf16 v[116:119], v[184:187], v[200:203], v[116:119]
	v_mfma_f32_16x16x32_bf16 v[112:115], v[192:195], v[200:203], v[112:115]
	v_mfma_f32_16x16x32_bf16 v[100:103], v[184:187], v[208:211], v[100:103]
	v_mfma_f32_16x16x32_bf16 v[96:99], v[192:195], v[208:211], v[96:99]
	v_mfma_f32_16x16x32_bf16 v[84:87], v[184:187], v[216:219], v[84:87]
	v_mfma_f32_16x16x32_bf16 v[80:83], v[192:195], v[216:219], v[80:83]
	v_mfma_f32_16x16x32_bf16 v[68:71], v[184:187], v[224:227], v[68:71]
	v_mfma_f32_16x16x32_bf16 v[64:67], v[192:195], v[224:227], v[64:67]
	s_waitcnt vmcnt(12)
	s_barrier
	ds_read_b128 v[180:183], v160
	ds_read_b128 v[184:187], v160 offset:1024
	ds_read_b128 v[188:191], v160 offset:2048
	ds_read_b128 v[192:195], v160 offset:3072
	ds_read_b128 v[196:199], v162 offset:16384
	ds_read_b128 v[200:203], v162 offset:17408
	ds_read_b128 v[204:207], v162 offset:18432
	ds_read_b128 v[208:211], v162 offset:19456
	ds_read_b128 v[212:215], v162 offset:20480
	ds_read_b128 v[216:219], v162 offset:21504
	ds_read_b128 v[220:223], v162 offset:22528
	ds_read_b128 v[224:227], v162 offset:23552
	s_waitcnt lgkmcnt(0)
	v_mfma_f32_16x16x32_bf16 v[116:119], v[180:183], v[196:199], v[116:119]
	v_mfma_f32_16x16x32_bf16 v[112:115], v[188:191], v[196:199], v[112:115]
	v_mfma_f32_16x16x32_bf16 v[100:103], v[180:183], v[204:207], v[100:103]
	v_mfma_f32_16x16x32_bf16 v[96:99], v[188:191], v[204:207], v[96:99]
	v_mfma_f32_16x16x32_bf16 v[84:87], v[180:183], v[212:215], v[84:87]
	v_mfma_f32_16x16x32_bf16 v[80:83], v[188:191], v[212:215], v[80:83]
	v_mfma_f32_16x16x32_bf16 v[68:71], v[180:183], v[220:223], v[68:71]
	v_mfma_f32_16x16x32_bf16 v[64:67], v[188:191], v[220:223], v[64:67]
	v_mfma_f32_16x16x32_bf16 v[116:119], v[184:187], v[200:203], v[116:119]
	v_mfma_f32_16x16x32_bf16 v[112:115], v[192:195], v[200:203], v[112:115]
	v_mfma_f32_16x16x32_bf16 v[100:103], v[184:187], v[208:211], v[100:103]
	v_mfma_f32_16x16x32_bf16 v[96:99], v[192:195], v[208:211], v[96:99]
	v_mfma_f32_16x16x32_bf16 v[84:87], v[184:187], v[216:219], v[84:87]
	v_mfma_f32_16x16x32_bf16 v[80:83], v[192:195], v[216:219], v[80:83]
	v_mfma_f32_16x16x32_bf16 v[68:71], v[184:187], v[224:227], v[68:71]
	v_mfma_f32_16x16x32_bf16 v[64:67], v[192:195], v[224:227], v[64:67]
	s_waitcnt vmcnt(8)
	s_barrier
	ds_read_b128 v[180:183], v163
	ds_read_b128 v[184:187], v163 offset:1024
	ds_read_b128 v[188:191], v163 offset:2048
	ds_read_b128 v[192:195], v163 offset:3072
	ds_read_b128 v[196:199], v162 offset:49152
	ds_read_b128 v[200:203], v162 offset:50176
	ds_read_b128 v[204:207], v162 offset:51200
	ds_read_b128 v[208:211], v162 offset:52224
	ds_read_b128 v[212:215], v162 offset:53248
	ds_read_b128 v[216:219], v162 offset:54272
	ds_read_b128 v[220:223], v162 offset:55296
	ds_read_b128 v[224:227], v162 offset:56320
	s_waitcnt lgkmcnt(0)
	v_mfma_f32_16x16x32_bf16 v[116:119], v[180:183], v[196:199], v[116:119]
	v_mfma_f32_16x16x32_bf16 v[112:115], v[188:191], v[196:199], v[112:115]
	v_mfma_f32_16x16x32_bf16 v[100:103], v[180:183], v[204:207], v[100:103]
	v_mfma_f32_16x16x32_bf16 v[96:99], v[188:191], v[204:207], v[96:99]
	v_mfma_f32_16x16x32_bf16 v[84:87], v[180:183], v[212:215], v[84:87]
	v_mfma_f32_16x16x32_bf16 v[80:83], v[188:191], v[212:215], v[80:83]
	v_mfma_f32_16x16x32_bf16 v[68:71], v[180:183], v[220:223], v[68:71]
	v_mfma_f32_16x16x32_bf16 v[64:67], v[188:191], v[220:223], v[64:67]
	v_mfma_f32_16x16x32_bf16 v[116:119], v[184:187], v[200:203], v[116:119]
	v_mfma_f32_16x16x32_bf16 v[112:115], v[192:195], v[200:203], v[112:115]
	v_mfma_f32_16x16x32_bf16 v[100:103], v[184:187], v[208:211], v[100:103]
	v_mfma_f32_16x16x32_bf16 v[96:99], v[192:195], v[208:211], v[96:99]
	v_mfma_f32_16x16x32_bf16 v[84:87], v[184:187], v[216:219], v[84:87]
	v_mfma_f32_16x16x32_bf16 v[80:83], v[192:195], v[216:219], v[80:83]
	v_mfma_f32_16x16x32_bf16 v[68:71], v[184:187], v[224:227], v[68:71]
	v_mfma_f32_16x16x32_bf16 v[64:67], v[192:195], v[224:227], v[64:67]
	s_branch .LBB0_620
; #define PG8_WAIT_V(n) asm volatile("s_waitcnt vmcnt(" #n ")" ::: "memory")
; template <class Epi, class Sched, bool ALIGN_EPI = false, bool SP2 = false>
; __device__ __forceinline__ void gemm_phase(PG8_LAS unsigned char* lds, const Gemm g, const Sched& S, const Epi& E) {
;     ...
;     const char* cA = (const char*)g.A + (size_t)cur.pm * tstep; const char* cB = (const char*)g.Bt + (size_t)cur.pn * tstep;
;     S.a_ready(cur);
;     if constexpr (SP2) {
;         PG8_STAGE(PG8_SB(0, 0), cB, voffB); PG8_STAGE(PG8_SB(0, 1), cB + hstep, voffB); PG8_STAGE(PG8_SA(0, 0), cA, voffA); PG8_STAGE(PG8_SA(0, 1), cA + hstep, voffA);
;         if (wr == 1) PG8_BAR;
;         PG8_WAIT_V(2); PG8_BAR;
;         PG8_STAGE(PG8_SB(1, 0), cB + kstep, voffB); PG8_STAGE(PG8_SA(1, 0), cA + kstep, voffA); PG8_STAGE(PG8_SB(1, 1), cB + hstep + kstep, voffB);
;         PG8_WAIT_V(6); PG8_BAR;
;     } else {
;         PG8_STAGE(PG8_SB(0, 0), cB, voffB); PG8_STAGE(PG8_SA(0, 0), cA, voffA); PG8_STAGE(PG8_SB(0, 1), cB + hstep, voffB); PG8_STAGE(PG8_SA(0, 1), cA + hstep, voffA);
;         if (wr == 1) PG8_BAR;
;         PG8_WAIT_V(4); PG8_BAR;
;         PG8_STAGE(PG8_SB(1, 0), cB + kstep, voffB); PG8_STAGE(PG8_SA(1, 0), cA + kstep, voffA); PG8_STAGE(PG8_SB(1, 1), cB + hstep + kstep, voffB);
;         PG8_WAIT_V(6); PG8_BAR;
;     }
;     for (;;) {
;         const bool has_next = S.next(ui + 1, nxt);
;         const char* nA = has_next ? (const char*)g.A + (size_t)nxt.pm * tstep : cA; const char* nB = has_next ? (const char*)g.Bt + (size_t)nxt.pn * tstep : cB;
;         for (int t = 0; t < nt; t += 2) {
;             const bool last = (t == nt - 2);
;             const char* a1 = cA + (size_t)(t + 1) * kstep;
;             const char* a2 = last ? nA : cA + (size_t)(t + 2) * kstep; const char* b2 = last ? nB : cB + (size_t)(t + 2) * kstep;
;             const char* a3 = a2 + kstep; const char* b3 = b2 + kstep;
;             if (last && has_next) S.a_ready(nxt);
;             if constexpr (SP2) {
;             PG8_LDB(B0, 0, 0); PG8_LDB(B1, 0, 1); PG8_SCHED; PG8_LDA(At, 0, 0); PG8_STAGE(PG8_SA(1, 1), a1 + hstep, voffA);
;             PG8_WAIT_V(8); PG8_WAIT_L(0); PG8_BAR; PG8_MMA(0, 0, At, B0); PG8_MMA(0, 1, At, B1); PG8_BAR; PG8_SCHED;
;             PG8_LDA(At, 0, 1); PG8_STAGE(PG8_SB(0, 0), b2, voffB); PG8_STAGE(PG8_SB(0, 1), b2 + hstep, voffB); PG8_STAGE(PG8_SA(0, 0), a2, voffA);
.Lp3q_lean_q2:
	s_mov_b32 s22, s94
	s_mov_b32 s23, 0
	s_lshl_b64 s[22:23], s[22:23], 19
	s_add_u32 s22, s22, s70
	s_addc_u32 s23, s23, s71
	s_add_u32 s22, s22, 0x80
	s_addc_u32 s23, s23, 0
	s_add_u32 s22, s22, 0x40000
	s_addc_u32 s23, s23, 0
	s_mov_b32 s24, s42
	s_mov_b32 s25, 0
	s_lshl_b64 s[24:25], s[24:25], 19
	s_add_u32 s24, s24, s64
	s_addc_u32 s25, s25, s65
	s_add_u32 s24, s24, 0x80
	s_addc_u32 s25, s25, 0
	s_waitcnt vmcnt(0) lgkmcnt(0)
	s_barrier
	s_add_i32 m0, s0, 0xc000
	s_nop 0
	global_load_lds_dwordx4 v140, s[22:23]
	s_add_i32 m0, s0, 0xe000
	s_nop 0
	global_load_lds_dwordx4 v144, s[22:23]
	s_add_u32 s22, s22, 0x80
	s_addc_u32 s23, s23, 0
	s_add_u32 s24, s24, 0x80
	s_addc_u32 s25, s25, 0
	s_mov_b32 m0, s0
	s_nop 0
	global_load_lds_dwordx4 v140, s[22:23]
	s_add_i32 m0, s0, 0x2000
	s_nop 0
	global_load_lds_dwordx4 v144, s[22:23]
	s_add_i32 m0, s0, 0x14000
	s_nop 0
	global_load_lds_dwordx4 v142, s[24:25]
	s_add_i32 m0, s0, 0x16000
	s_nop 0
	global_load_lds_dwordx4 v146, s[24:25]
	s_add_u32 s22, s22, 0x80
	s_addc_u32 s23, s23, 0
	s_add_u32 s24, s24, 0x80
	s_addc_u32 s25, s25, 0
	s_add_i32 m0, s0, 0x8000
	s_nop 0
	global_load_lds_dwordx4 v140, s[22:23]
	s_add_i32 m0, s0, 0xa000
	s_nop 0
	global_load_lds_dwordx4 v144, s[22:23]
	s_add_i32 m0, s0, 0x1c000
	s_nop 0
	global_load_lds_dwordx4 v142, s[24:25]
	s_add_i32 m0, s0, 0x1e000
	s_nop 0
	global_load_lds_dwordx4 v146, s[24:25]
	ds_read_b128 v[150:153], v160
	ds_read_b128 v[154:157], v160 offset:1024
	ds_read_b128 v[168:171], v160 offset:2048
	ds_read_b128 v[176:179], v160 offset:3072
	ds_read_b128 v[196:199], v162 offset:16384
	ds_read_b128 v[200:203], v162 offset:17408
	ds_read_b128 v[204:207], v162 offset:18432
	ds_read_b128 v[208:211], v162 offset:19456
	ds_read_b128 v[212:215], v162 offset:20480
	ds_read_b128 v[216:219], v162 offset:21504
	ds_read_b128 v[220:223], v162 offset:22528
	ds_read_b128 v[224:227], v162 offset:23552
	s_waitcnt lgkmcnt(0)
	v_mfma_f32_16x16x32_bf16 v[60:63], v[150:153], v[196:199], v[60:63]
	v_mfma_f32_16x16x32_bf16 v[56:59], v[168:171], v[196:199], v[56:59]
	v_mfma_f32_16x16x32_bf16 v[44:47], v[150:153], v[204:207], v[44:47]
	v_mfma_f32_16x16x32_bf16 v[40:43], v[168:171], v[204:207], v[40:43]
	v_mfma_f32_16x16x32_bf16 v[28:31], v[150:153], v[212:215], v[28:31]
	v_mfma_f32_16x16x32_bf16 v[24:27], v[168:171], v[212:215], v[24:27]
	v_mfma_f32_16x16x32_bf16 v[12:15], v[150:153], v[220:223], v[12:15]
	v_mfma_f32_16x16x32_bf16 v[8:11], v[168:171], v[220:223], v[8:11]
	v_mfma_f32_16x16x32_bf16 v[60:63], v[154:157], v[200:203], v[60:63]
	v_mfma_f32_16x16x32_bf16 v[56:59], v[176:179], v[200:203], v[56:59]
	v_mfma_f32_16x16x32_bf16 v[44:47], v[154:157], v[208:211], v[44:47]
	v_mfma_f32_16x16x32_bf16 v[40:43], v[176:179], v[208:211], v[40:43]
	v_mfma_f32_16x16x32_bf16 v[28:31], v[154:157], v[216:219], v[28:31]
	v_mfma_f32_16x16x32_bf16 v[24:27], v[176:179], v[216:219], v[24:27]
	v_mfma_f32_16x16x32_bf16 v[12:15], v[154:157], v[224:227], v[12:15]
	v_mfma_f32_16x16x32_bf16 v[8:11], v[176:179], v[224:227], v[8:11]
	s_waitcnt vmcnt(8)
	s_barrier
	ds_read_b128 v[150:153], v163
	ds_read_b128 v[154:157], v163 offset:1024
	ds_read_b128 v[168:171], v163 offset:2048
	ds_read_b128 v[176:179], v163 offset:3072
	ds_read_b128 v[196:199], v162 offset:49152
	ds_read_b128 v[200:203], v162 offset:50176
	ds_read_b128 v[204:207], v162 offset:51200
	ds_read_b128 v[208:211], v162 offset:52224
	ds_read_b128 v[212:215], v162 offset:53248
	ds_read_b128 v[216:219], v162 offset:54272
	ds_read_b128 v[220:223], v162 offset:55296
	ds_read_b128 v[224:227], v162 offset:56320
	s_add_u32 s22, s22, 0x80
	s_addc_u32 s23, s23, 0
	s_add_u32 s24, s24, 0x80
	s_addc_u32 s25, s25, 0
	s_add_i32 m0, s0, 0x4000
	s_nop 0
	global_load_lds_dwordx4 v140, s[22:23]
	s_add_i32 m0, s0, 0x6000
	s_nop 0
	global_load_lds_dwordx4 v144, s[22:23]
	s_add_i32 m0, s0, 0x10000
	s_nop 0
	global_load_lds_dwordx4 v142, s[24:25]
	s_add_i32 m0, s0, 0x12000
	s_nop 0
	global_load_lds_dwordx4 v146, s[24:25]
	s_waitcnt lgkmcnt(0)
	v_mfma_f32_16x16x32_bf16 v[60:63], v[150:153], v[196:199], v[60:63]
	v_mfma_f32_16x16x32_bf16 v[56:59], v[168:171], v[196:199], v[56:59]
	v_mfma_f32_16x16x32_bf16 v[44:47], v[150:153], v[204:207], v[44:47]
	v_mfma_f32_16x16x32_bf16 v[40:43], v[168:171], v[204:207], v[40:43]
	v_mfma_f32_16x16x32_bf16 v[28:31], v[150:153], v[212:215], v[28:31]
	v_mfma_f32_16x16x32_bf16 v[24:27], v[168:171], v[212:215], v[24:27]
	v_mfma_f32_16x16x32_bf16 v[12:15], v[150:153], v[220:223], v[12:15]
	v_mfma_f32_16x16x32_bf16 v[8:11], v[168:171], v[220:223], v[8:11]
	v_mfma_f32_16x16x32_bf16 v[60:63], v[154:157], v[200:203], v[60:63]
	v_mfma_f32_16x16x32_bf16 v[56:59], v[176:179], v[200:203], v[56:59]
	v_mfma_f32_16x16x32_bf16 v[44:47], v[154:157], v[208:211], v[44:47]
	v_mfma_f32_16x16x32_bf16 v[40:43], v[176:179], v[208:211], v[40:43]
	v_mfma_f32_16x16x32_bf16 v[28:31], v[154:157], v[216:219], v[28:31]
	v_mfma_f32_16x16x32_bf16 v[24:27], v[176:179], v[216:219], v[24:27]
	v_mfma_f32_16x16x32_bf16 v[12:15], v[154:157], v[224:227], v[12:15]
	v_mfma_f32_16x16x32_bf16 v[8:11], v[176:179], v[224:227], v[8:11]
	s_waitcnt vmcnt(8)
	s_barrier
; #define PG8_STAGE(bufoff, gbase, voff) do { _Pragma("unroll") for (int _i = 0; _i < 2; ++_i) \
;         __builtin_amdgcn_global_load_lds((const unsigned*)((const char*)(gbase) + (voff)[_i]), (PG8_LAS unsigned*)(lds + (bufoff) + ldsw + _i * 8192), 16, 0, 0); } while (0)
; #define PG8_LDA(dst, b, h) do { _Pragma("unroll") for (int m = 0; m < 4; ++m) _Pragma("unroll") for (int k = 0; k < 2; ++k) dst[m][k] = *(const PG8_LAS bf16x8*)(lds + PG8_SA(b, h) + aoff + m * 2048 + k * 1024); } while (0)
; #define PG8_LDB(dst, b, h) do { _Pragma("unroll") for (int n = 0; n < 2; ++n) _Pragma("unroll") for (int k = 0; k < 2; ++k) dst[n][k] = *(const PG8_LAS bf16x8*)(lds + PG8_SB(b, h) + boff + n * 2048 + k * 1024); } while (0)
; #define PG8_MMA(ai, bj, At, Bt) do { __builtin_amdgcn_s_setprio(1); _Pragma("unroll") for (int m = 0; m < 4; ++m) _Pragma("unroll") for (int n = 0; n < 2; ++n) _Pragma("unroll") for (int k = 0; k < 2; ++k) \
;         acc[ai][bj][m][n] = __builtin_amdgcn_mfma_f32_16x16x32_bf16(Bt[n][k], At[m][k], acc[ai][bj][m][n], 0, 0, 0); __builtin_amdgcn_s_setprio(0); } while (0)
; #define PG8_WAIT_V(n) asm volatile("s_waitcnt vmcnt(" #n ")" ::: "memory")
; template <class Epi, class Sched, bool ALIGN_EPI = false, bool SP2 = false>
; __device__ __forceinline__ void gemm_phase(PG8_LAS unsigned char* lds, const Gemm g, const Sched& S, const Epi& E) {
;     ...
;             PG8_LDB(B0, 0, 0); PG8_LDB(B1, 0, 1); PG8_SCHED; PG8_LDA(At, 0, 0); PG8_STAGE(PG8_SA(1, 1), a1 + hstep, voffA);
;             PG8_WAIT_V(8); PG8_WAIT_L(0); PG8_BAR; PG8_MMA(0, 0, At, B0); PG8_MMA(0, 1, At, B1); PG8_BAR; PG8_SCHED;
;             PG8_LDA(At, 0, 1); PG8_STAGE(PG8_SB(0, 0), b2, voffB); PG8_STAGE(PG8_SB(0, 1), b2 + hstep, voffB); PG8_STAGE(PG8_SA(0, 0), a2, voffA);
;             PG8_WAIT_V(8); PG8_WAIT_L(0); PG8_BAR; PG8_MMA(1, 0, At, B0); PG8_MMA(1, 1, At, B1); PG8_BAR; PG8_SCHED;
;             PG8_LDB(B0, 1, 0); PG8_LDB(B1, 1, 1); PG8_SCHED; PG8_LDA(At, 1, 0); PG8_STAGE(PG8_SA(0, 1), a2 + hstep, voffA);
;             PG8_WAIT_V(8); PG8_WAIT_L(0); PG8_BAR; PG8_MMA(0, 0, At, B0); PG8_MMA(0, 1, At, B1); PG8_BAR; PG8_SCHED;
;             PG8_LDA(At, 1, 1); PG8_STAGE(PG8_SB(1, 0), b3, voffB); PG8_STAGE(PG8_SB(1, 1), b3 + hstep, voffB); PG8_STAGE(PG8_SA(1, 0), a3, voffA);
;             PG8_WAIT_V(8); PG8_WAIT_L(0); PG8_BAR; PG8_MMA(1, 0, At, B0); PG8_MMA(1, 1, At, B1); PG8_BAR; PG8_SCHED;
	ds_read_b128 v[150:153], v161
	ds_read_b128 v[154:157], v161 offset:1024
	ds_read_b128 v[168:171], v161 offset:2048
	ds_read_b128 v[176:179], v161 offset:3072
	ds_read_b128 v[196:199], v162
	ds_read_b128 v[200:203], v162 offset:1024
	ds_read_b128 v[204:207], v162 offset:2048
	ds_read_b128 v[208:211], v162 offset:3072
	ds_read_b128 v[212:215], v162 offset:4096
	ds_read_b128 v[216:219], v162 offset:5120
	ds_read_b128 v[220:223], v162 offset:6144
	ds_read_b128 v[224:227], v162 offset:7168
	s_add_u32 s22, s22, 0x80
	s_addc_u32 s23, s23, 0
	s_add_u32 s24, s24, 0x80
	s_addc_u32 s25, s25, 0
	s_add_i32 m0, s0, 0xc000
	s_nop 0
	global_load_lds_dwordx4 v140, s[22:23]
	s_add_i32 m0, s0, 0xe000
	s_nop 0
	global_load_lds_dwordx4 v144, s[22:23]
	s_add_i32 m0, s0, 0x18000
	s_nop 0
	global_load_lds_dwordx4 v142, s[24:25]
	s_add_i32 m0, s0, 0x1a000
	s_nop 0
	global_load_lds_dwordx4 v146, s[24:25]
	s_waitcnt lgkmcnt(0)
	v_mfma_f32_16x16x32_bf16 v[60:63], v[150:153], v[196:199], v[60:63]
	v_mfma_f32_16x16x32_bf16 v[56:59], v[168:171], v[196:199], v[56:59]
	v_mfma_f32_16x16x32_bf16 v[44:47], v[150:153], v[204:207], v[44:47]
	v_mfma_f32_16x16x32_bf16 v[40:43], v[168:171], v[204:207], v[40:43]
	v_mfma_f32_16x16x32_bf16 v[28:31], v[150:153], v[212:215], v[28:31]
	v_mfma_f32_16x16x32_bf16 v[24:27], v[168:171], v[212:215], v[24:27]
	v_mfma_f32_16x16x32_bf16 v[12:15], v[150:153], v[220:223], v[12:15]
	v_mfma_f32_16x16x32_bf16 v[8:11], v[168:171], v[220:223], v[8:11]
	v_mfma_f32_16x16x32_bf16 v[60:63], v[154:157], v[200:203], v[60:63]
	v_mfma_f32_16x16x32_bf16 v[56:59], v[176:179], v[200:203], v[56:59]
	v_mfma_f32_16x16x32_bf16 v[44:47], v[154:157], v[208:211], v[44:47]
	v_mfma_f32_16x16x32_bf16 v[40:43], v[176:179], v[208:211], v[40:43]
	v_mfma_f32_16x16x32_bf16 v[28:31], v[154:157], v[216:219], v[28:31]
	v_mfma_f32_16x16x32_bf16 v[24:27], v[176:179], v[216:219], v[24:27]
	v_mfma_f32_16x16x32_bf16 v[12:15], v[154:157], v[224:227], v[12:15]
	v_mfma_f32_16x16x32_bf16 v[8:11], v[176:179], v[224:227], v[8:11]
	s_waitcnt vmcnt(8)
	s_barrier
	ds_read_b128 v[150:153], v164
	ds_read_b128 v[154:157], v164 offset:1024
	ds_read_b128 v[168:171], v164 offset:2048
	ds_read_b128 v[176:179], v164 offset:3072
	ds_read_b128 v[196:199], v162 offset:32768
	ds_read_b128 v[200:203], v162 offset:33792
	ds_read_b128 v[204:207], v162 offset:34816
	ds_read_b128 v[208:211], v162 offset:35840
	ds_read_b128 v[212:215], v162 offset:36864
	ds_read_b128 v[216:219], v162 offset:37888
	ds_read_b128 v[220:223], v162 offset:38912
	ds_read_b128 v[224:227], v162 offset:39936
	s_add_u32 s22, s22, 0x80
	s_addc_u32 s23, s23, 0
	s_add_u32 s24, s24, 0x80
	s_addc_u32 s25, s25, 0
	s_mov_b32 m0, s0
	s_nop 0
	global_load_lds_dwordx4 v140, s[22:23]
	s_add_i32 m0, s0, 0x2000
	s_nop 0
	global_load_lds_dwordx4 v144, s[22:23]
	s_add_i32 m0, s0, 0x14000
	s_nop 0
	global_load_lds_dwordx4 v142, s[24:25]
	s_add_i32 m0, s0, 0x16000
	s_nop 0
	global_load_lds_dwordx4 v146, s[24:25]
	s_waitcnt lgkmcnt(0)
	v_mfma_f32_16x16x32_bf16 v[60:63], v[150:153], v[196:199], v[60:63]
	v_mfma_f32_16x16x32_bf16 v[56:59], v[168:171], v[196:199], v[56:59]
	v_mfma_f32_16x16x32_bf16 v[44:47], v[150:153], v[204:207], v[44:47]
	v_mfma_f32_16x16x32_bf16 v[40:43], v[168:171], v[204:207], v[40:43]
	v_mfma_f32_16x16x32_bf16 v[28:31], v[150:153], v[212:215], v[28:31]
	v_mfma_f32_16x16x32_bf16 v[24:27], v[168:171], v[212:215], v[24:27]
	v_mfma_f32_16x16x32_bf16 v[12:15], v[150:153], v[220:223], v[12:15]
	v_mfma_f32_16x16x32_bf16 v[8:11], v[168:171], v[220:223], v[8:11]
	v_mfma_f32_16x16x32_bf16 v[60:63], v[154:157], v[200:203], v[60:63]
	v_mfma_f32_16x16x32_bf16 v[56:59], v[176:179], v[200:203], v[56:59]
	v_mfma_f32_16x16x32_bf16 v[44:47], v[154:157], v[208:211], v[44:47]
	v_mfma_f32_16x16x32_bf16 v[40:43], v[176:179], v[208:211], v[40:43]
	v_mfma_f32_16x16x32_bf16 v[28:31], v[154:157], v[216:219], v[28:31]
	v_mfma_f32_16x16x32_bf16 v[24:27], v[176:179], v[216:219], v[24:27]
	v_mfma_f32_16x16x32_bf16 v[12:15], v[154:157], v[224:227], v[12:15]
	v_mfma_f32_16x16x32_bf16 v[8:11], v[176:179], v[224:227], v[8:11]
	s_waitcnt vmcnt(8)
	s_barrier
	ds_read_b128 v[150:153], v160
	ds_read_b128 v[154:157], v160 offset:1024
	ds_read_b128 v[168:171], v160 offset:2048
	ds_read_b128 v[176:179], v160 offset:3072
	ds_read_b128 v[196:199], v162 offset:16384
	ds_read_b128 v[200:203], v162 offset:17408
	ds_read_b128 v[204:207], v162 offset:18432
	ds_read_b128 v[208:211], v162 offset:19456
	ds_read_b128 v[212:215], v162 offset:20480
	ds_read_b128 v[216:219], v162 offset:21504
	ds_read_b128 v[220:223], v162 offset:22528
	ds_read_b128 v[224:227], v162 offset:23552
	s_add_u32 s22, s22, 0x80
	s_addc_u32 s23, s23, 0
	s_add_u32 s24, s24, 0x80
	s_addc_u32 s25, s25, 0
	s_add_i32 m0, s0, 0x8000
	s_nop 0
	global_load_lds_dwordx4 v140, s[22:23]
	s_add_i32 m0, s0, 0xa000
	s_nop 0
	global_load_lds_dwordx4 v144, s[22:23]
	s_add_i32 m0, s0, 0x1c000
	s_nop 0
	global_load_lds_dwordx4 v142, s[24:25]
	s_add_i32 m0, s0, 0x1e000
	s_nop 0
	global_load_lds_dwordx4 v146, s[24:25]
	s_waitcnt lgkmcnt(0)
	v_mfma_f32_16x16x32_bf16 v[60:63], v[150:153], v[196:199], v[60:63]
	v_mfma_f32_16x16x32_bf16 v[56:59], v[168:171], v[196:199], v[56:59]
	v_mfma_f32_16x16x32_bf16 v[44:47], v[150:153], v[204:207], v[44:47]
	v_mfma_f32_16x16x32_bf16 v[40:43], v[168:171], v[204:207], v[40:43]
	v_mfma_f32_16x16x32_bf16 v[28:31], v[150:153], v[212:215], v[28:31]
	v_mfma_f32_16x16x32_bf16 v[24:27], v[168:171], v[212:215], v[24:27]
	v_mfma_f32_16x16x32_bf16 v[12:15], v[150:153], v[220:223], v[12:15]
	v_mfma_f32_16x16x32_bf16 v[8:11], v[168:171], v[220:223], v[8:11]
	v_mfma_f32_16x16x32_bf16 v[60:63], v[154:157], v[200:203], v[60:63]
	v_mfma_f32_16x16x32_bf16 v[56:59], v[176:179], v[200:203], v[56:59]
	v_mfma_f32_16x16x32_bf16 v[44:47], v[154:157], v[208:211], v[44:47]
	v_mfma_f32_16x16x32_bf16 v[40:43], v[176:179], v[208:211], v[40:43]
	v_mfma_f32_16x16x32_bf16 v[28:31], v[154:157], v[216:219], v[28:31]
	v_mfma_f32_16x16x32_bf16 v[24:27], v[176:179], v[216:219], v[24:27]
	v_mfma_f32_16x16x32_bf16 v[12:15], v[154:157], v[224:227], v[12:15]
	v_mfma_f32_16x16x32_bf16 v[8:11], v[176:179], v[224:227], v[8:11]
	s_waitcnt vmcnt(8)
	s_barrier
; #define PG8_STAGE(bufoff, gbase, voff) do { _Pragma("unroll") for (int _i = 0; _i < 2; ++_i) \
;         __builtin_amdgcn_global_load_lds((const unsigned*)((const char*)(gbase) + (voff)[_i]), (PG8_LAS unsigned*)(lds + (bufoff) + ldsw + _i * 8192), 16, 0, 0); } while (0)
; #define PG8_LDA(dst, b, h) do { _Pragma("unroll") for (int m = 0; m < 4; ++m) _Pragma("unroll") for (int k = 0; k < 2; ++k) dst[m][k] = *(const PG8_LAS bf16x8*)(lds + PG8_SA(b, h) + aoff + m * 2048 + k * 1024); } while (0)
; #define PG8_LDB(dst, b, h) do { _Pragma("unroll") for (int n = 0; n < 2; ++n) _Pragma("unroll") for (int k = 0; k < 2; ++k) dst[n][k] = *(const PG8_LAS bf16x8*)(lds + PG8_SB(b, h) + boff + n * 2048 + k * 1024); } while (0)
; #define PG8_MMA(ai, bj, At, Bt) do { __builtin_amdgcn_s_setprio(1); _Pragma("unroll") for (int m = 0; m < 4; ++m) _Pragma("unroll") for (int n = 0; n < 2; ++n) _Pragma("unroll") for (int k = 0; k < 2; ++k) \
;         acc[ai][bj][m][n] = __builtin_amdgcn_mfma_f32_16x16x32_bf16(Bt[n][k], At[m][k], acc[ai][bj][m][n], 0, 0, 0); __builtin_amdgcn_s_setprio(0); } while (0)
; #define PG8_WAIT_V(n) asm volatile("s_waitcnt vmcnt(" #n ")" ::: "memory")
; template <class Epi, class Sched, bool ALIGN_EPI = false, bool SP2 = false>
; __device__ __forceinline__ void gemm_phase(PG8_LAS unsigned char* lds, const Gemm g, const Sched& S, const Epi& E) {
;     ...
;             PG8_LDB(B0, 0, 0); PG8_LDB(B1, 0, 1); PG8_SCHED; PG8_LDA(At, 0, 0); PG8_STAGE(PG8_SA(1, 1), a1 + hstep, voffA);
;             PG8_WAIT_V(8); PG8_WAIT_L(0); PG8_BAR; PG8_MMA(0, 0, At, B0); PG8_MMA(0, 1, At, B1); PG8_BAR; PG8_SCHED;
;             PG8_LDA(At, 0, 1); PG8_STAGE(PG8_SB(0, 0), b2, voffB); PG8_STAGE(PG8_SB(0, 1), b2 + hstep, voffB); PG8_STAGE(PG8_SA(0, 0), a2, voffA);
;             PG8_WAIT_V(8); PG8_WAIT_L(0); PG8_BAR; PG8_MMA(1, 0, At, B0); PG8_MMA(1, 1, At, B1); PG8_BAR; PG8_SCHED;
;             PG8_LDB(B0, 1, 0); PG8_LDB(B1, 1, 1); PG8_SCHED; PG8_LDA(At, 1, 0); PG8_STAGE(PG8_SA(0, 1), a2 + hstep, voffA);
;             PG8_WAIT_V(8); PG8_WAIT_L(0); PG8_BAR; PG8_MMA(0, 0, At, B0); PG8_MMA(0, 1, At, B1); PG8_BAR; PG8_SCHED;
;             PG8_LDA(At, 1, 1); PG8_STAGE(PG8_SB(1, 0), b3, voffB); PG8_STAGE(PG8_SB(1, 1), b3 + hstep, voffB); PG8_STAGE(PG8_SA(1, 0), a3, voffA);
;             PG8_WAIT_V(8); PG8_WAIT_L(0); PG8_BAR; PG8_MMA(1, 0, At, B0); PG8_MMA(1, 1, At, B1); PG8_BAR; PG8_SCHED;
	ds_read_b128 v[150:153], v163
	ds_read_b128 v[154:157], v163 offset:1024
	ds_read_b128 v[168:171], v163 offset:2048
	ds_read_b128 v[176:179], v163 offset:3072
	ds_read_b128 v[196:199], v162 offset:49152
	ds_read_b128 v[200:203], v162 offset:50176
	ds_read_b128 v[204:207], v162 offset:51200
	ds_read_b128 v[208:211], v162 offset:52224
	ds_read_b128 v[212:215], v162 offset:53248
	ds_read_b128 v[216:219], v162 offset:54272
	ds_read_b128 v[220:223], v162 offset:55296
	ds_read_b128 v[224:227], v162 offset:56320
	s_add_u32 s22, s22, 0x80
	s_addc_u32 s23, s23, 0
	s_add_u32 s24, s24, 0x80
	s_addc_u32 s25, s25, 0
	s_add_i32 m0, s0, 0x4000
	s_nop 0
	global_load_lds_dwordx4 v140, s[22:23]
	s_add_i32 m0, s0, 0x6000
	s_nop 0
	global_load_lds_dwordx4 v144, s[22:23]
	s_add_i32 m0, s0, 0x10000
	s_nop 0
	global_load_lds_dwordx4 v142, s[24:25]
	s_add_i32 m0, s0, 0x12000
	s_nop 0
	global_load_lds_dwordx4 v146, s[24:25]
	s_waitcnt lgkmcnt(0)
	v_mfma_f32_16x16x32_bf16 v[60:63], v[150:153], v[196:199], v[60:63]
	v_mfma_f32_16x16x32_bf16 v[56:59], v[168:171], v[196:199], v[56:59]
	v_mfma_f32_16x16x32_bf16 v[44:47], v[150:153], v[204:207], v[44:47]
	v_mfma_f32_16x16x32_bf16 v[40:43], v[168:171], v[204:207], v[40:43]
	v_mfma_f32_16x16x32_bf16 v[28:31], v[150:153], v[212:215], v[28:31]
	v_mfma_f32_16x16x32_bf16 v[24:27], v[168:171], v[212:215], v[24:27]
	v_mfma_f32_16x16x32_bf16 v[12:15], v[150:153], v[220:223], v[12:15]
	v_mfma_f32_16x16x32_bf16 v[8:11], v[168:171], v[220:223], v[8:11]
	v_mfma_f32_16x16x32_bf16 v[60:63], v[154:157], v[200:203], v[60:63]
	v_mfma_f32_16x16x32_bf16 v[56:59], v[176:179], v[200:203], v[56:59]
	v_mfma_f32_16x16x32_bf16 v[44:47], v[154:157], v[208:211], v[44:47]
	v_mfma_f32_16x16x32_bf16 v[40:43], v[176:179], v[208:211], v[40:43]
	v_mfma_f32_16x16x32_bf16 v[28:31], v[154:157], v[216:219], v[28:31]
	v_mfma_f32_16x16x32_bf16 v[24:27], v[176:179], v[216:219], v[24:27]
	v_mfma_f32_16x16x32_bf16 v[12:15], v[154:157], v[224:227], v[12:15]
	v_mfma_f32_16x16x32_bf16 v[8:11], v[176:179], v[224:227], v[8:11]
	s_waitcnt vmcnt(8)
	s_barrier
	ds_read_b128 v[150:153], v161
	ds_read_b128 v[154:157], v161 offset:1024
	ds_read_b128 v[168:171], v161 offset:2048
	ds_read_b128 v[176:179], v161 offset:3072
	ds_read_b128 v[196:199], v162
	ds_read_b128 v[200:203], v162 offset:1024
	ds_read_b128 v[204:207], v162 offset:2048
	ds_read_b128 v[208:211], v162 offset:3072
	ds_read_b128 v[212:215], v162 offset:4096
	ds_read_b128 v[216:219], v162 offset:5120
	ds_read_b128 v[220:223], v162 offset:6144
	ds_read_b128 v[224:227], v162 offset:7168
	s_add_u32 s22, s22, 0x80
	s_addc_u32 s23, s23, 0
	s_add_u32 s24, s24, 0x80
	s_addc_u32 s25, s25, 0
	s_add_i32 m0, s0, 0xc000
	s_nop 0
	global_load_lds_dwordx4 v140, s[22:23]
	s_add_i32 m0, s0, 0xe000
	s_nop 0
	global_load_lds_dwordx4 v144, s[22:23]
	s_add_i32 m0, s0, 0x18000
	s_nop 0
	global_load_lds_dwordx4 v142, s[24:25]
	s_add_i32 m0, s0, 0x1a000
	s_nop 0
	global_load_lds_dwordx4 v146, s[24:25]
	s_waitcnt lgkmcnt(0)
	v_mfma_f32_16x16x32_bf16 v[60:63], v[150:153], v[196:199], v[60:63]
	v_mfma_f32_16x16x32_bf16 v[56:59], v[168:171], v[196:199], v[56:59]
	v_mfma_f32_16x16x32_bf16 v[44:47], v[150:153], v[204:207], v[44:47]
	v_mfma_f32_16x16x32_bf16 v[40:43], v[168:171], v[204:207], v[40:43]
	v_mfma_f32_16x16x32_bf16 v[28:31], v[150:153], v[212:215], v[28:31]
	v_mfma_f32_16x16x32_bf16 v[24:27], v[168:171], v[212:215], v[24:27]
	v_mfma_f32_16x16x32_bf16 v[12:15], v[150:153], v[220:223], v[12:15]
	v_mfma_f32_16x16x32_bf16 v[8:11], v[168:171], v[220:223], v[8:11]
	v_mfma_f32_16x16x32_bf16 v[60:63], v[154:157], v[200:203], v[60:63]
	v_mfma_f32_16x16x32_bf16 v[56:59], v[176:179], v[200:203], v[56:59]
	v_mfma_f32_16x16x32_bf16 v[44:47], v[154:157], v[208:211], v[44:47]
	v_mfma_f32_16x16x32_bf16 v[40:43], v[176:179], v[208:211], v[40:43]
	v_mfma_f32_16x16x32_bf16 v[28:31], v[154:157], v[216:219], v[28:31]
	v_mfma_f32_16x16x32_bf16 v[24:27], v[176:179], v[216:219], v[24:27]
	v_mfma_f32_16x16x32_bf16 v[12:15], v[154:157], v[224:227], v[12:15]
	v_mfma_f32_16x16x32_bf16 v[8:11], v[176:179], v[224:227], v[8:11]
	s_waitcnt vmcnt(8)
	s_barrier
	ds_read_b128 v[150:153], v164
	ds_read_b128 v[154:157], v164 offset:1024
	ds_read_b128 v[168:171], v164 offset:2048
	ds_read_b128 v[176:179], v164 offset:3072
	ds_read_b128 v[196:199], v162 offset:32768
	ds_read_b128 v[200:203], v162 offset:33792
	ds_read_b128 v[204:207], v162 offset:34816
	ds_read_b128 v[208:211], v162 offset:35840
	ds_read_b128 v[212:215], v162 offset:36864
	ds_read_b128 v[216:219], v162 offset:37888
	ds_read_b128 v[220:223], v162 offset:38912
	ds_read_b128 v[224:227], v162 offset:39936
	s_add_u32 s22, s22, 0x80
	s_addc_u32 s23, s23, 0
	s_add_u32 s24, s24, 0x80
	s_addc_u32 s25, s25, 0
	s_mov_b32 m0, s0
	s_nop 0
	global_load_lds_dwordx4 v140, s[22:23]
	s_add_i32 m0, s0, 0x2000
	s_nop 0
	global_load_lds_dwordx4 v144, s[22:23]
	s_add_i32 m0, s0, 0x14000
	s_nop 0
	global_load_lds_dwordx4 v142, s[24:25]
	s_add_i32 m0, s0, 0x16000
	s_nop 0
	global_load_lds_dwordx4 v146, s[24:25]
	s_waitcnt lgkmcnt(0)
	v_mfma_f32_16x16x32_bf16 v[60:63], v[150:153], v[196:199], v[60:63]
	v_mfma_f32_16x16x32_bf16 v[56:59], v[168:171], v[196:199], v[56:59]
	v_mfma_f32_16x16x32_bf16 v[44:47], v[150:153], v[204:207], v[44:47]
	v_mfma_f32_16x16x32_bf16 v[40:43], v[168:171], v[204:207], v[40:43]
	v_mfma_f32_16x16x32_bf16 v[28:31], v[150:153], v[212:215], v[28:31]
	v_mfma_f32_16x16x32_bf16 v[24:27], v[168:171], v[212:215], v[24:27]
	v_mfma_f32_16x16x32_bf16 v[12:15], v[150:153], v[220:223], v[12:15]
	v_mfma_f32_16x16x32_bf16 v[8:11], v[168:171], v[220:223], v[8:11]
	v_mfma_f32_16x16x32_bf16 v[60:63], v[154:157], v[200:203], v[60:63]
	v_mfma_f32_16x16x32_bf16 v[56:59], v[176:179], v[200:203], v[56:59]
	v_mfma_f32_16x16x32_bf16 v[44:47], v[154:157], v[208:211], v[44:47]
	v_mfma_f32_16x16x32_bf16 v[40:43], v[176:179], v[208:211], v[40:43]
	v_mfma_f32_16x16x32_bf16 v[28:31], v[154:157], v[216:219], v[28:31]
	v_mfma_f32_16x16x32_bf16 v[24:27], v[176:179], v[216:219], v[24:27]
	v_mfma_f32_16x16x32_bf16 v[12:15], v[154:157], v[224:227], v[12:15]
	v_mfma_f32_16x16x32_bf16 v[8:11], v[176:179], v[224:227], v[8:11]
	s_waitcnt vmcnt(8)
	s_barrier
; #define PG8_STAGE(bufoff, gbase, voff) do { _Pragma("unroll") for (int _i = 0; _i < 2; ++_i) \
;         __builtin_amdgcn_global_load_lds((const unsigned*)((const char*)(gbase) + (voff)[_i]), (PG8_LAS unsigned*)(lds + (bufoff) + ldsw + _i * 8192), 16, 0, 0); } while (0)
; #define PG8_LDA(dst, b, h) do { _Pragma("unroll") for (int m = 0; m < 4; ++m) _Pragma("unroll") for (int k = 0; k < 2; ++k) dst[m][k] = *(const PG8_LAS bf16x8*)(lds + PG8_SA(b, h) + aoff + m * 2048 + k * 1024); } while (0)
; #define PG8_LDB(dst, b, h) do { _Pragma("unroll") for (int n = 0; n < 2; ++n) _Pragma("unroll") for (int k = 0; k < 2; ++k) dst[n][k] = *(const PG8_LAS bf16x8*)(lds + PG8_SB(b, h) + boff + n * 2048 + k * 1024); } while (0)
; #define PG8_MMA(ai, bj, At, Bt) do { __builtin_amdgcn_s_setprio(1); _Pragma("unroll") for (int m = 0; m < 4; ++m) _Pragma("unroll") for (int n = 0; n < 2; ++n) _Pragma("unroll") for (int k = 0; k < 2; ++k) \
;         acc[ai][bj][m][n] = __builtin_amdgcn_mfma_f32_16x16x32_bf16(Bt[n][k], At[m][k], acc[ai][bj][m][n], 0, 0, 0); __builtin_amdgcn_s_setprio(0); } while (0)
; #define PG8_WAIT_V(n) asm volatile("s_waitcnt vmcnt(" #n ")" ::: "memory")
; template <class Epi, class Sched, bool ALIGN_EPI = false, bool SP2 = false>
; __device__ __forceinline__ void gemm_phase(PG8_LAS unsigned char* lds, const Gemm g, const Sched& S, const Epi& E) {
;     ...
;             PG8_LDB(B0, 0, 0); PG8_LDB(B1, 0, 1); PG8_SCHED; PG8_LDA(At, 0, 0); PG8_STAGE(PG8_SA(1, 1), a1 + hstep, voffA);
;             PG8_WAIT_V(8); PG8_WAIT_L(0); PG8_BAR; PG8_MMA(0, 0, At, B0); PG8_MMA(0, 1, At, B1); PG8_BAR; PG8_SCHED;
;             PG8_LDA(At, 0, 1); PG8_STAGE(PG8_SB(0, 0), b2, voffB); PG8_STAGE(PG8_SB(0, 1), b2 + hstep, voffB); PG8_STAGE(PG8_SA(0, 0), a2, voffA);
;             PG8_WAIT_V(8); PG8_WAIT_L(0); PG8_BAR; PG8_MMA(1, 0, At, B0); PG8_MMA(1, 1, At, B1); PG8_BAR; PG8_SCHED;
;             PG8_LDB(B0, 1, 0); PG8_LDB(B1, 1, 1); PG8_SCHED; PG8_LDA(At, 1, 0); PG8_STAGE(PG8_SA(0, 1), a2 + hstep, voffA);
;             PG8_WAIT_V(8); PG8_WAIT_L(0); PG8_BAR; PG8_MMA(0, 0, At, B0); PG8_MMA(0, 1, At, B1); PG8_BAR; PG8_SCHED;
;             PG8_LDA(At, 1, 1); PG8_STAGE(PG8_SB(1, 0), b3, voffB); PG8_STAGE(PG8_SB(1, 1), b3 + hstep, voffB); PG8_STAGE(PG8_SA(1, 0), a3, voffA);
;             PG8_WAIT_V(8); PG8_WAIT_L(0); PG8_BAR; PG8_MMA(1, 0, At, B0); PG8_MMA(1, 1, At, B1); PG8_BAR; PG8_SCHED;
	ds_read_b128 v[150:153], v160
	ds_read_b128 v[154:157], v160 offset:1024
	ds_read_b128 v[168:171], v160 offset:2048
	ds_read_b128 v[176:179], v160 offset:3072
	ds_read_b128 v[196:199], v162 offset:16384
	ds_read_b128 v[200:203], v162 offset:17408
	ds_read_b128 v[204:207], v162 offset:18432
	ds_read_b128 v[208:211], v162 offset:19456
	ds_read_b128 v[212:215], v162 offset:20480
	ds_read_b128 v[216:219], v162 offset:21504
	ds_read_b128 v[220:223], v162 offset:22528
	ds_read_b128 v[224:227], v162 offset:23552
	s_add_u32 s22, s22, 0x80
	s_addc_u32 s23, s23, 0
	s_add_u32 s24, s24, 0x80
	s_addc_u32 s25, s25, 0
	s_add_i32 m0, s0, 0x8000
	s_nop 0
	global_load_lds_dwordx4 v140, s[22:23]
	s_add_i32 m0, s0, 0xa000
	s_nop 0
	global_load_lds_dwordx4 v144, s[22:23]
	s_add_i32 m0, s0, 0x1c000
	s_nop 0
	global_load_lds_dwordx4 v142, s[24:25]
	s_add_i32 m0, s0, 0x1e000
	s_nop 0
	global_load_lds_dwordx4 v146, s[24:25]
	s_waitcnt lgkmcnt(0)
	v_mfma_f32_16x16x32_bf16 v[60:63], v[150:153], v[196:199], v[60:63]
	v_mfma_f32_16x16x32_bf16 v[56:59], v[168:171], v[196:199], v[56:59]
	v_mfma_f32_16x16x32_bf16 v[44:47], v[150:153], v[204:207], v[44:47]
	v_mfma_f32_16x16x32_bf16 v[40:43], v[168:171], v[204:207], v[40:43]
	v_mfma_f32_16x16x32_bf16 v[28:31], v[150:153], v[212:215], v[28:31]
	v_mfma_f32_16x16x32_bf16 v[24:27], v[168:171], v[212:215], v[24:27]
	v_mfma_f32_16x16x32_bf16 v[12:15], v[150:153], v[220:223], v[12:15]
	v_mfma_f32_16x16x32_bf16 v[8:11], v[168:171], v[220:223], v[8:11]
	v_mfma_f32_16x16x32_bf16 v[60:63], v[154:157], v[200:203], v[60:63]
	v_mfma_f32_16x16x32_bf16 v[56:59], v[176:179], v[200:203], v[56:59]
	v_mfma_f32_16x16x32_bf16 v[44:47], v[154:157], v[208:211], v[44:47]
	v_mfma_f32_16x16x32_bf16 v[40:43], v[176:179], v[208:211], v[40:43]
	v_mfma_f32_16x16x32_bf16 v[28:31], v[154:157], v[216:219], v[28:31]
	v_mfma_f32_16x16x32_bf16 v[24:27], v[176:179], v[216:219], v[24:27]
	v_mfma_f32_16x16x32_bf16 v[12:15], v[154:157], v[224:227], v[12:15]
	v_mfma_f32_16x16x32_bf16 v[8:11], v[176:179], v[224:227], v[8:11]
	s_waitcnt vmcnt(8)
	s_barrier
	ds_read_b128 v[150:153], v163
	ds_read_b128 v[154:157], v163 offset:1024
	ds_read_b128 v[168:171], v163 offset:2048
	ds_read_b128 v[176:179], v163 offset:3072
	ds_read_b128 v[196:199], v162 offset:49152
	ds_read_b128 v[200:203], v162 offset:50176
	ds_read_b128 v[204:207], v162 offset:51200
	ds_read_b128 v[208:211], v162 offset:52224
	ds_read_b128 v[212:215], v162 offset:53248
	ds_read_b128 v[216:219], v162 offset:54272
	ds_read_b128 v[220:223], v162 offset:55296
	ds_read_b128 v[224:227], v162 offset:56320
	s_add_u32 s22, s22, 0x80
	s_addc_u32 s23, s23, 0
	s_add_u32 s24, s24, 0x80
	s_addc_u32 s25, s25, 0
	s_add_i32 m0, s0, 0x4000
	s_nop 0
	global_load_lds_dwordx4 v140, s[22:23]
	s_add_i32 m0, s0, 0x6000
	s_nop 0
	global_load_lds_dwordx4 v144, s[22:23]
	s_add_i32 m0, s0, 0x10000
	s_nop 0
	global_load_lds_dwordx4 v142, s[24:25]
	s_add_i32 m0, s0, 0x12000
	s_nop 0
	global_load_lds_dwordx4 v146, s[24:25]
	s_waitcnt lgkmcnt(0)
	v_mfma_f32_16x16x32_bf16 v[60:63], v[150:153], v[196:199], v[60:63]
	v_mfma_f32_16x16x32_bf16 v[56:59], v[168:171], v[196:199], v[56:59]
	v_mfma_f32_16x16x32_bf16 v[44:47], v[150:153], v[204:207], v[44:47]
	v_mfma_f32_16x16x32_bf16 v[40:43], v[168:171], v[204:207], v[40:43]
	v_mfma_f32_16x16x32_bf16 v[28:31], v[150:153], v[212:215], v[28:31]
	v_mfma_f32_16x16x32_bf16 v[24:27], v[168:171], v[212:215], v[24:27]
	v_mfma_f32_16x16x32_bf16 v[12:15], v[150:153], v[220:223], v[12:15]
	v_mfma_f32_16x16x32_bf16 v[8:11], v[168:171], v[220:223], v[8:11]
	v_mfma_f32_16x16x32_bf16 v[60:63], v[154:157], v[200:203], v[60:63]
	v_mfma_f32_16x16x32_bf16 v[56:59], v[176:179], v[200:203], v[56:59]
	v_mfma_f32_16x16x32_bf16 v[44:47], v[154:157], v[208:211], v[44:47]
	v_mfma_f32_16x16x32_bf16 v[40:43], v[176:179], v[208:211], v[40:43]
	v_mfma_f32_16x16x32_bf16 v[28:31], v[154:157], v[216:219], v[28:31]
	v_mfma_f32_16x16x32_bf16 v[24:27], v[176:179], v[216:219], v[24:27]
	v_mfma_f32_16x16x32_bf16 v[12:15], v[154:157], v[224:227], v[12:15]
	v_mfma_f32_16x16x32_bf16 v[8:11], v[176:179], v[224:227], v[8:11]
	s_waitcnt vmcnt(8)
	s_barrier
	ds_read_b128 v[150:153], v161
	ds_read_b128 v[154:157], v161 offset:1024
	ds_read_b128 v[168:171], v161 offset:2048
	ds_read_b128 v[176:179], v161 offset:3072
	ds_read_b128 v[196:199], v162
	ds_read_b128 v[200:203], v162 offset:1024
	ds_read_b128 v[204:207], v162 offset:2048
	ds_read_b128 v[208:211], v162 offset:3072
	ds_read_b128 v[212:215], v162 offset:4096
	ds_read_b128 v[216:219], v162 offset:5120
	ds_read_b128 v[220:223], v162 offset:6144
	ds_read_b128 v[224:227], v162 offset:7168
	s_add_u32 s22, s22, 0x80
	s_addc_u32 s23, s23, 0
	s_add_u32 s24, s24, 0x80
	s_addc_u32 s25, s25, 0
	s_add_i32 m0, s0, 0xc000
	s_nop 0
	global_load_lds_dwordx4 v140, s[22:23]
	s_add_i32 m0, s0, 0xe000
	s_nop 0
	global_load_lds_dwordx4 v144, s[22:23]
	s_add_i32 m0, s0, 0x18000
	s_nop 0
	global_load_lds_dwordx4 v142, s[24:25]
	s_add_i32 m0, s0, 0x1a000
	s_nop 0
	global_load_lds_dwordx4 v146, s[24:25]
	s_waitcnt lgkmcnt(0)
	v_mfma_f32_16x16x32_bf16 v[60:63], v[150:153], v[196:199], v[60:63]
	v_mfma_f32_16x16x32_bf16 v[56:59], v[168:171], v[196:199], v[56:59]
	v_mfma_f32_16x16x32_bf16 v[44:47], v[150:153], v[204:207], v[44:47]
	v_mfma_f32_16x16x32_bf16 v[40:43], v[168:171], v[204:207], v[40:43]
	v_mfma_f32_16x16x32_bf16 v[28:31], v[150:153], v[212:215], v[28:31]
	v_mfma_f32_16x16x32_bf16 v[24:27], v[168:171], v[212:215], v[24:27]
	v_mfma_f32_16x16x32_bf16 v[12:15], v[150:153], v[220:223], v[12:15]
	v_mfma_f32_16x16x32_bf16 v[8:11], v[168:171], v[220:223], v[8:11]
	v_mfma_f32_16x16x32_bf16 v[60:63], v[154:157], v[200:203], v[60:63]
	v_mfma_f32_16x16x32_bf16 v[56:59], v[176:179], v[200:203], v[56:59]
	v_mfma_f32_16x16x32_bf16 v[44:47], v[154:157], v[208:211], v[44:47]
	v_mfma_f32_16x16x32_bf16 v[40:43], v[176:179], v[208:211], v[40:43]
	v_mfma_f32_16x16x32_bf16 v[28:31], v[154:157], v[216:219], v[28:31]
	v_mfma_f32_16x16x32_bf16 v[24:27], v[176:179], v[216:219], v[24:27]
	v_mfma_f32_16x16x32_bf16 v[12:15], v[154:157], v[224:227], v[12:15]
	v_mfma_f32_16x16x32_bf16 v[8:11], v[176:179], v[224:227], v[8:11]
	s_waitcnt vmcnt(8)
	s_barrier
; #define PG8_STAGE(bufoff, gbase, voff) do { _Pragma("unroll") for (int _i = 0; _i < 2; ++_i) \
;         __builtin_amdgcn_global_load_lds((const unsigned*)((const char*)(gbase) + (voff)[_i]), (PG8_LAS unsigned*)(lds + (bufoff) + ldsw + _i * 8192), 16, 0, 0); } while (0)
; #define PG8_LDA(dst, b, h) do { _Pragma("unroll") for (int m = 0; m < 4; ++m) _Pragma("unroll") for (int k = 0; k < 2; ++k) dst[m][k] = *(const PG8_LAS bf16x8*)(lds + PG8_SA(b, h) + aoff + m * 2048 + k * 1024); } while (0)
; #define PG8_LDB(dst, b, h) do { _Pragma("unroll") for (int n = 0; n < 2; ++n) _Pragma("unroll") for (int k = 0; k < 2; ++k) dst[n][k] = *(const PG8_LAS bf16x8*)(lds + PG8_SB(b, h) + boff + n * 2048 + k * 1024); } while (0)
; #define PG8_WAIT_V(n) asm volatile("s_waitcnt vmcnt(" #n ")" ::: "memory")
; #define PG8_WAIT_L(n) asm volatile("s_waitcnt lgkmcnt(" #n ")" ::: "memory")
; template <class Epi, class Sched, bool ALIGN_EPI = false, bool SP2 = false>
; __device__ __forceinline__ void gemm_phase(PG8_LAS unsigned char* lds, const Gemm g, const Sched& S, const Epi& E) {
;     ...
;             PG8_LDB(B0, 1, 0); PG8_LDB(B1, 1, 1); PG8_SCHED; PG8_LDA(At, 1, 0); PG8_STAGE(PG8_SA(0, 1), a2 + hstep, voffA);
;             PG8_WAIT_V(8); PG8_WAIT_L(0); PG8_BAR; PG8_MMA(0, 0, At, B0); PG8_MMA(0, 1, At, B1); PG8_BAR; PG8_SCHED;
;             PG8_LDA(At, 1, 1); PG8_STAGE(PG8_SB(1, 0), b3, voffB); PG8_STAGE(PG8_SB(1, 1), b3 + hstep, voffB); PG8_STAGE(PG8_SA(1, 0), a3, voffA);
;     DI void operator()(const f32x4 (&acc)[2][2][4][2], const pg8::Unit& u, int wr, int wc, int fr, int fq) const {
;     ...
;                 const int R = u.pm * 256 + ai * 128 + wr * 64 + m * 16 + fr;
;                 const float* xs = nullptr; float* yd = nullptr;
;                 if (R < ROWS_P) { const int b = R / LPAD, t = R - b * LPAD; if (t >= NMETA && t < LP) { const size_t idx = ((size_t)b * SEQ + t - NMETA) * DM; xs = p.x_prompt + idx; yd = p.out + O_YP + idx; } }
;                 else { const size_t idx = (size_t)(R - ROWS_P) * DM; xs = p.x_sample + idx; yd = p.out + O_YS + idx; }
;                 float ss = 0.f;
;                 if (xs) {
; #pragma unroll
;                     for (int bj = 0; bj < 2; ++bj) {
;                         const int n = colt + bj * 128 + wc * 32 + 8 * fq;
;                         const f32x4 x0 = *(const f32x4*)(xs + n), x1 = *(const f32x4*)(xs + n + 4);
	ds_read_b128 v[150:153], v164
	ds_read_b128 v[154:157], v164 offset:1024
	ds_read_b128 v[168:171], v164 offset:2048
	ds_read_b128 v[176:179], v164 offset:3072
	ds_read_b128 v[196:199], v162 offset:32768
	ds_read_b128 v[200:203], v162 offset:33792
	ds_read_b128 v[204:207], v162 offset:34816
	ds_read_b128 v[208:211], v162 offset:35840
	ds_read_b128 v[212:215], v162 offset:36864
	ds_read_b128 v[216:219], v162 offset:37888
	ds_read_b128 v[220:223], v162 offset:38912
	ds_read_b128 v[224:227], v162 offset:39936
	s_add_u32 s22, s22, 0x80
	s_addc_u32 s23, s23, 0
	s_add_u32 s24, s24, 0x80
	s_addc_u32 s25, s25, 0
	s_mov_b32 m0, s0
	s_nop 0
	global_load_lds_dwordx4 v140, s[22:23]
	s_add_i32 m0, s0, 0x2000
	s_nop 0
	global_load_lds_dwordx4 v144, s[22:23]
	s_add_i32 m0, s0, 0x14000
	s_nop 0
	global_load_lds_dwordx4 v142, s[24:25]
	s_add_i32 m0, s0, 0x16000
	s_nop 0
	global_load_lds_dwordx4 v146, s[24:25]
	s_waitcnt lgkmcnt(0)
	v_mfma_f32_16x16x32_bf16 v[60:63], v[150:153], v[196:199], v[60:63]
	v_mfma_f32_16x16x32_bf16 v[56:59], v[168:171], v[196:199], v[56:59]
	v_mfma_f32_16x16x32_bf16 v[44:47], v[150:153], v[204:207], v[44:47]
	v_mfma_f32_16x16x32_bf16 v[40:43], v[168:171], v[204:207], v[40:43]
	v_mfma_f32_16x16x32_bf16 v[28:31], v[150:153], v[212:215], v[28:31]
	v_mfma_f32_16x16x32_bf16 v[24:27], v[168:171], v[212:215], v[24:27]
	v_mfma_f32_16x16x32_bf16 v[12:15], v[150:153], v[220:223], v[12:15]
	v_mfma_f32_16x16x32_bf16 v[8:11], v[168:171], v[220:223], v[8:11]
	v_mfma_f32_16x16x32_bf16 v[60:63], v[154:157], v[200:203], v[60:63]
	v_mfma_f32_16x16x32_bf16 v[56:59], v[176:179], v[200:203], v[56:59]
	v_mfma_f32_16x16x32_bf16 v[44:47], v[154:157], v[208:211], v[44:47]
	v_mfma_f32_16x16x32_bf16 v[40:43], v[176:179], v[208:211], v[40:43]
	v_mfma_f32_16x16x32_bf16 v[28:31], v[154:157], v[216:219], v[28:31]
	v_mfma_f32_16x16x32_bf16 v[24:27], v[176:179], v[216:219], v[24:27]
	v_mfma_f32_16x16x32_bf16 v[12:15], v[154:157], v[224:227], v[12:15]
	v_mfma_f32_16x16x32_bf16 v[8:11], v[176:179], v[224:227], v[8:11]
	s_waitcnt vmcnt(8)
	s_barrier
	ds_read_b128 v[150:153], v160
	ds_read_b128 v[154:157], v160 offset:1024
	ds_read_b128 v[168:171], v160 offset:2048
	ds_read_b128 v[176:179], v160 offset:3072
	ds_read_b128 v[196:199], v162 offset:16384
	ds_read_b128 v[200:203], v162 offset:17408
	ds_read_b128 v[204:207], v162 offset:18432
	ds_read_b128 v[208:211], v162 offset:19456
	ds_read_b128 v[212:215], v162 offset:20480
	ds_read_b128 v[216:219], v162 offset:21504
	ds_read_b128 v[220:223], v162 offset:22528
	ds_read_b128 v[224:227], v162 offset:23552
	s_add_u32 s22, s22, 0x80
	s_addc_u32 s23, s23, 0
	s_add_u32 s24, s24, 0x80
	s_addc_u32 s25, s25, 0
	s_add_i32 m0, s0, 0x8000
	s_nop 0
	global_load_lds_dwordx4 v140, s[22:23]
	s_add_i32 m0, s0, 0xa000
	s_nop 0
	global_load_lds_dwordx4 v144, s[22:23]
	s_add_i32 m0, s0, 0x1c000
	s_nop 0
	global_load_lds_dwordx4 v142, s[24:25]
	s_add_i32 m0, s0, 0x1e000
	s_nop 0
	global_load_lds_dwordx4 v146, s[24:25]
	v_lshl_or_b32 v236, s42, 8, v159
	v_and_b32_e32 v237, 15, v158
	v_lshlrev_b32_e32 v236, 2, v236
	v_lshl_or_b32 v236, v237, 12, v236
	s_and_b64 vcc, s[72:73], exec
	s_cselect_b32 s35, 64, 0
	s_lshl_b32 s32, s94, 8
	s_add_i32 s35, s35, s32
	s_add_i32 s32, s35, 128
	s_mul_hi_u32 s34, s32, 0x7e07e07f
	s_lshr_b32 s34, s34, 11
	s_mul_i32 vcc_lo, s34, 0x1040
	s_sub_i32 vcc_lo, s32, vcc_lo
	s_add_i32 vcc_lo, vcc_lo, -16
	s_lshl_b32 s34, s34, 12
	s_add_i32 s34, s34, vcc_lo
	s_cmp_lt_u32 vcc_lo, 0x1000
	s_cselect_b32 vcc_hi, 1, 0
	s_sub_i32 vcc_lo, s32, 0x4100
	s_cmp_ge_u32 s94, 65
	s_cselect_b32 s34, vcc_lo, s34
	s_cselect_b32 vcc_hi, 1, vcc_hi
	s_cselect_b32 s30, s78, s76
	s_cselect_b32 s31, s79, s77
	s_cmp_lg_u32 vcc_hi, 0
	s_cselect_b32 s34, s34, 0
	s_lshl_b32 s34, s34, 12
	s_add_u32 s30, s30, s34
	s_addc_u32 s31, s31, 0
	global_load_dwordx4 v[64:67], v236, s[30:31]
	global_load_dwordx4 v[68:71], v236, s[30:31] offset:16
	s_add_i32 s32, s35, 144
	s_mul_hi_u32 s34, s32, 0x7e07e07f
	s_lshr_b32 s34, s34, 11
	s_mul_i32 vcc_lo, s34, 0x1040
	s_sub_i32 vcc_lo, s32, vcc_lo
	s_add_i32 vcc_lo, vcc_lo, -16
	s_lshl_b32 s34, s34, 12
	s_add_i32 s34, s34, vcc_lo
	s_cmp_lt_u32 vcc_lo, 0x1000
	s_cselect_b32 vcc_hi, 1, 0
	s_sub_i32 vcc_lo, s32, 0x4100
	s_cmp_ge_u32 s94, 65
	s_cselect_b32 s34, vcc_lo, s34
	s_cselect_b32 vcc_hi, 1, vcc_hi
	s_cselect_b32 s30, s78, s76
	s_cselect_b32 s31, s79, s77
	s_cmp_lg_u32 vcc_hi, 0
	s_cselect_b32 s34, s34, 0
	s_lshl_b32 s34, s34, 12
	s_add_u32 s30, s30, s34
	s_addc_u32 s31, s31, 0
	global_load_dwordx4 v[72:75], v236, s[30:31]
	global_load_dwordx4 v[76:79], v236, s[30:31] offset:16
	s_add_i32 s32, s35, 160
	s_mul_hi_u32 s34, s32, 0x7e07e07f
	s_lshr_b32 s34, s34, 11
	s_mul_i32 vcc_lo, s34, 0x1040
	s_sub_i32 vcc_lo, s32, vcc_lo
	s_add_i32 vcc_lo, vcc_lo, -16
	s_lshl_b32 s34, s34, 12
	s_add_i32 s34, s34, vcc_lo
	s_cmp_lt_u32 vcc_lo, 0x1000
	s_cselect_b32 vcc_hi, 1, 0
	s_sub_i32 vcc_lo, s32, 0x4100
	s_cmp_ge_u32 s94, 65
	s_cselect_b32 s34, vcc_lo, s34
	s_cselect_b32 vcc_hi, 1, vcc_hi
	s_cselect_b32 s30, s78, s76
	s_cselect_b32 s31, s79, s77
	s_cmp_lg_u32 vcc_hi, 0
	s_cselect_b32 s34, s34, 0
	s_lshl_b32 s34, s34, 12
	s_add_u32 s30, s30, s34
	s_addc_u32 s31, s31, 0
	global_load_dwordx4 v[80:83], v236, s[30:31]
	global_load_dwordx4 v[84:87], v236, s[30:31] offset:16
	s_add_i32 s32, s35, 176
	s_mul_hi_u32 s34, s32, 0x7e07e07f
	s_lshr_b32 s34, s34, 11
	s_mul_i32 vcc_lo, s34, 0x1040
	s_sub_i32 vcc_lo, s32, vcc_lo
	s_add_i32 vcc_lo, vcc_lo, -16
	s_lshl_b32 s34, s34, 12
	s_add_i32 s34, s34, vcc_lo
	s_cmp_lt_u32 vcc_lo, 0x1000
	s_cselect_b32 vcc_hi, 1, 0
	s_sub_i32 vcc_lo, s32, 0x4100
	s_cmp_ge_u32 s94, 65
	s_cselect_b32 s34, vcc_lo, s34
	s_cselect_b32 vcc_hi, 1, vcc_hi
	s_cselect_b32 s30, s78, s76
	s_cselect_b32 s31, s79, s77
	s_cmp_lg_u32 vcc_hi, 0
	s_cselect_b32 s34, s34, 0
	s_lshl_b32 s34, s34, 12
	s_add_u32 s30, s30, s34
	s_addc_u32 s31, s31, 0
	global_load_dwordx4 v[88:91], v236, s[30:31]
	global_load_dwordx4 v[92:95], v236, s[30:31] offset:16
	s_waitcnt lgkmcnt(0)
; #define PG8_STAGE(bufoff, gbase, voff) do { _Pragma("unroll") for (int _i = 0; _i < 2; ++_i) \
;         __builtin_amdgcn_global_load_lds((const unsigned*)((const char*)(gbase) + (voff)[_i]), (PG8_LAS unsigned*)(lds + (bufoff) + ldsw + _i * 8192), 16, 0, 0); } while (0)
; #define PG8_LDA(dst, b, h) do { _Pragma("unroll") for (int m = 0; m < 4; ++m) _Pragma("unroll") for (int k = 0; k < 2; ++k) dst[m][k] = *(const PG8_LAS bf16x8*)(lds + PG8_SA(b, h) + aoff + m * 2048 + k * 1024); } while (0)
; #define PG8_LDB(dst, b, h) do { _Pragma("unroll") for (int n = 0; n < 2; ++n) _Pragma("unroll") for (int k = 0; k < 2; ++k) dst[n][k] = *(const PG8_LAS bf16x8*)(lds + PG8_SB(b, h) + boff + n * 2048 + k * 1024); } while (0)
; #define PG8_MMA(ai, bj, At, Bt) do { __builtin_amdgcn_s_setprio(1); _Pragma("unroll") for (int m = 0; m < 4; ++m) _Pragma("unroll") for (int n = 0; n < 2; ++n) _Pragma("unroll") for (int k = 0; k < 2; ++k) \
;         acc[ai][bj][m][n] = __builtin_amdgcn_mfma_f32_16x16x32_bf16(Bt[n][k], At[m][k], acc[ai][bj][m][n], 0, 0, 0); __builtin_amdgcn_s_setprio(0); } while (0)
; #define PG8_WAIT_V(n) asm volatile("s_waitcnt vmcnt(" #n ")" ::: "memory")
; template <class Epi, class Sched, bool ALIGN_EPI = false, bool SP2 = false>
; __device__ __forceinline__ void gemm_phase(PG8_LAS unsigned char* lds, const Gemm g, const Sched& S, const Epi& E) {
;     ...
;             PG8_LDB(B0, 0, 0); PG8_LDB(B1, 0, 1); PG8_SCHED; PG8_LDA(At, 0, 0); PG8_STAGE(PG8_SA(1, 1), a1 + hstep, voffA);
;             PG8_WAIT_V(8); PG8_WAIT_L(0); PG8_BAR; PG8_MMA(0, 0, At, B0); PG8_MMA(0, 1, At, B1); PG8_BAR; PG8_SCHED;
;             PG8_LDA(At, 0, 1); PG8_STAGE(PG8_SB(0, 0), b2, voffB); PG8_STAGE(PG8_SB(0, 1), b2 + hstep, voffB); PG8_STAGE(PG8_SA(0, 0), a2, voffA);
;             PG8_WAIT_V(8); PG8_WAIT_L(0); PG8_BAR; PG8_MMA(1, 0, At, B0); PG8_MMA(1, 1, At, B1); PG8_BAR; PG8_SCHED;
;             PG8_LDB(B0, 1, 0); PG8_LDB(B1, 1, 1); PG8_SCHED; PG8_LDA(At, 1, 0); PG8_STAGE(PG8_SA(0, 1), a2 + hstep, voffA);
;             PG8_WAIT_V(8); PG8_WAIT_L(0); PG8_BAR; PG8_MMA(0, 0, At, B0); PG8_MMA(0, 1, At, B1); PG8_BAR; PG8_SCHED;
;             PG8_LDA(At, 1, 1); PG8_STAGE(PG8_SB(1, 0), b3, voffB); PG8_STAGE(PG8_SB(1, 1), b3 + hstep, voffB); PG8_STAGE(PG8_SA(1, 0), a3, voffA);
;             PG8_WAIT_V(8); PG8_WAIT_L(0); PG8_BAR; PG8_MMA(1, 0, At, B0); PG8_MMA(1, 1, At, B1); PG8_BAR; PG8_SCHED;
	v_mfma_f32_16x16x32_bf16 v[60:63], v[150:153], v[196:199], v[60:63]
	v_mfma_f32_16x16x32_bf16 v[56:59], v[168:171], v[196:199], v[56:59]
	v_mfma_f32_16x16x32_bf16 v[44:47], v[150:153], v[204:207], v[44:47]
	v_mfma_f32_16x16x32_bf16 v[40:43], v[168:171], v[204:207], v[40:43]
	v_mfma_f32_16x16x32_bf16 v[28:31], v[150:153], v[212:215], v[28:31]
	v_mfma_f32_16x16x32_bf16 v[24:27], v[168:171], v[212:215], v[24:27]
	v_mfma_f32_16x16x32_bf16 v[12:15], v[150:153], v[220:223], v[12:15]
	v_mfma_f32_16x16x32_bf16 v[8:11], v[168:171], v[220:223], v[8:11]
	v_mfma_f32_16x16x32_bf16 v[60:63], v[154:157], v[200:203], v[60:63]
	v_mfma_f32_16x16x32_bf16 v[56:59], v[176:179], v[200:203], v[56:59]
	v_mfma_f32_16x16x32_bf16 v[44:47], v[154:157], v[208:211], v[44:47]
	v_mfma_f32_16x16x32_bf16 v[40:43], v[176:179], v[208:211], v[40:43]
	v_mfma_f32_16x16x32_bf16 v[28:31], v[154:157], v[216:219], v[28:31]
	v_mfma_f32_16x16x32_bf16 v[24:27], v[176:179], v[216:219], v[24:27]
	v_mfma_f32_16x16x32_bf16 v[12:15], v[154:157], v[224:227], v[12:15]
	v_mfma_f32_16x16x32_bf16 v[8:11], v[176:179], v[224:227], v[8:11]
	s_waitcnt vmcnt(16)
	s_barrier
	ds_read_b128 v[150:153], v163
	ds_read_b128 v[154:157], v163 offset:1024
	ds_read_b128 v[168:171], v163 offset:2048
	ds_read_b128 v[176:179], v163 offset:3072
	ds_read_b128 v[196:199], v162 offset:49152
	ds_read_b128 v[200:203], v162 offset:50176
	ds_read_b128 v[204:207], v162 offset:51200
	ds_read_b128 v[208:211], v162 offset:52224
	ds_read_b128 v[212:215], v162 offset:53248
	ds_read_b128 v[216:219], v162 offset:54272
	ds_read_b128 v[220:223], v162 offset:55296
	ds_read_b128 v[224:227], v162 offset:56320
	s_waitcnt lgkmcnt(0)
	v_mfma_f32_16x16x32_bf16 v[60:63], v[150:153], v[196:199], v[60:63]
	v_mfma_f32_16x16x32_bf16 v[56:59], v[168:171], v[196:199], v[56:59]
	v_mfma_f32_16x16x32_bf16 v[44:47], v[150:153], v[204:207], v[44:47]
	v_mfma_f32_16x16x32_bf16 v[40:43], v[168:171], v[204:207], v[40:43]
	v_mfma_f32_16x16x32_bf16 v[28:31], v[150:153], v[212:215], v[28:31]
	v_mfma_f32_16x16x32_bf16 v[24:27], v[168:171], v[212:215], v[24:27]
	v_mfma_f32_16x16x32_bf16 v[12:15], v[150:153], v[220:223], v[12:15]
	v_mfma_f32_16x16x32_bf16 v[8:11], v[168:171], v[220:223], v[8:11]
	v_mfma_f32_16x16x32_bf16 v[60:63], v[154:157], v[200:203], v[60:63]
	v_mfma_f32_16x16x32_bf16 v[56:59], v[176:179], v[200:203], v[56:59]
	v_mfma_f32_16x16x32_bf16 v[44:47], v[154:157], v[208:211], v[44:47]
	v_mfma_f32_16x16x32_bf16 v[40:43], v[176:179], v[208:211], v[40:43]
	v_mfma_f32_16x16x32_bf16 v[28:31], v[154:157], v[216:219], v[28:31]
	v_mfma_f32_16x16x32_bf16 v[24:27], v[176:179], v[216:219], v[24:27]
	v_mfma_f32_16x16x32_bf16 v[12:15], v[154:157], v[224:227], v[12:15]
	v_mfma_f32_16x16x32_bf16 v[8:11], v[176:179], v[224:227], v[8:11]
	s_waitcnt vmcnt(12)
	s_barrier
	ds_read_b128 v[150:153], v161
	ds_read_b128 v[154:157], v161 offset:1024
	ds_read_b128 v[168:171], v161 offset:2048
	ds_read_b128 v[176:179], v161 offset:3072
	ds_read_b128 v[196:199], v162
	ds_read_b128 v[200:203], v162 offset:1024
	ds_read_b128 v[204:207], v162 offset:2048
	ds_read_b128 v[208:211], v162 offset:3072
	ds_read_b128 v[212:215], v162 offset:4096
	ds_read_b128 v[216:219], v162 offset:5120
	ds_read_b128 v[220:223], v162 offset:6144
	ds_read_b128 v[224:227], v162 offset:7168
	s_waitcnt lgkmcnt(0)
	v_mfma_f32_16x16x32_bf16 v[60:63], v[150:153], v[196:199], v[60:63]
	v_mfma_f32_16x16x32_bf16 v[56:59], v[168:171], v[196:199], v[56:59]
	v_mfma_f32_16x16x32_bf16 v[44:47], v[150:153], v[204:207], v[44:47]
	v_mfma_f32_16x16x32_bf16 v[40:43], v[168:171], v[204:207], v[40:43]
	v_mfma_f32_16x16x32_bf16 v[28:31], v[150:153], v[212:215], v[28:31]
	v_mfma_f32_16x16x32_bf16 v[24:27], v[168:171], v[212:215], v[24:27]
	v_mfma_f32_16x16x32_bf16 v[12:15], v[150:153], v[220:223], v[12:15]
	v_mfma_f32_16x16x32_bf16 v[8:11], v[168:171], v[220:223], v[8:11]
	v_mfma_f32_16x16x32_bf16 v[60:63], v[154:157], v[200:203], v[60:63]
	v_mfma_f32_16x16x32_bf16 v[56:59], v[176:179], v[200:203], v[56:59]
	v_mfma_f32_16x16x32_bf16 v[44:47], v[154:157], v[208:211], v[44:47]
	v_mfma_f32_16x16x32_bf16 v[40:43], v[176:179], v[208:211], v[40:43]
	v_mfma_f32_16x16x32_bf16 v[28:31], v[154:157], v[216:219], v[28:31]
	v_mfma_f32_16x16x32_bf16 v[24:27], v[176:179], v[216:219], v[24:27]
	v_mfma_f32_16x16x32_bf16 v[12:15], v[154:157], v[224:227], v[12:15]
	v_mfma_f32_16x16x32_bf16 v[8:11], v[176:179], v[224:227], v[8:11]
	s_waitcnt vmcnt(8)
	s_barrier
	ds_read_b128 v[150:153], v164
	ds_read_b128 v[154:157], v164 offset:1024
	ds_read_b128 v[168:171], v164 offset:2048
	ds_read_b128 v[176:179], v164 offset:3072
	ds_read_b128 v[196:199], v162 offset:32768
	ds_read_b128 v[200:203], v162 offset:33792
	ds_read_b128 v[204:207], v162 offset:34816
	ds_read_b128 v[208:211], v162 offset:35840
	ds_read_b128 v[212:215], v162 offset:36864
	ds_read_b128 v[216:219], v162 offset:37888
	ds_read_b128 v[220:223], v162 offset:38912
	ds_read_b128 v[224:227], v162 offset:39936
	s_waitcnt lgkmcnt(0)
	v_mfma_f32_16x16x32_bf16 v[60:63], v[150:153], v[196:199], v[60:63]
	v_mfma_f32_16x16x32_bf16 v[56:59], v[168:171], v[196:199], v[56:59]
	v_mfma_f32_16x16x32_bf16 v[44:47], v[150:153], v[204:207], v[44:47]
	v_mfma_f32_16x16x32_bf16 v[40:43], v[168:171], v[204:207], v[40:43]
	v_mfma_f32_16x16x32_bf16 v[28:31], v[150:153], v[212:215], v[28:31]
	v_mfma_f32_16x16x32_bf16 v[24:27], v[168:171], v[212:215], v[24:27]
	v_mfma_f32_16x16x32_bf16 v[12:15], v[150:153], v[220:223], v[12:15]
	v_mfma_f32_16x16x32_bf16 v[8:11], v[168:171], v[220:223], v[8:11]
	v_mfma_f32_16x16x32_bf16 v[60:63], v[154:157], v[200:203], v[60:63]
	v_mfma_f32_16x16x32_bf16 v[56:59], v[176:179], v[200:203], v[56:59]
	v_mfma_f32_16x16x32_bf16 v[44:47], v[154:157], v[208:211], v[44:47]
	v_mfma_f32_16x16x32_bf16 v[40:43], v[176:179], v[208:211], v[40:43]
	v_mfma_f32_16x16x32_bf16 v[28:31], v[154:157], v[216:219], v[28:31]
	v_mfma_f32_16x16x32_bf16 v[24:27], v[176:179], v[216:219], v[24:27]
	v_mfma_f32_16x16x32_bf16 v[12:15], v[154:157], v[224:227], v[12:15]
	v_mfma_f32_16x16x32_bf16 v[8:11], v[176:179], v[224:227], v[8:11]
	s_branch .LBB0_620
; #define PG8_WAIT_V(n) asm volatile("s_waitcnt vmcnt(" #n ")" ::: "memory")
; template <class Epi, class Sched, bool ALIGN_EPI = false, bool SP2 = false>
; __device__ __forceinline__ void gemm_phase(PG8_LAS unsigned char* lds, const Gemm g, const Sched& S, const Epi& E) {
;     ...
;     const char* cA = (const char*)g.A + (size_t)cur.pm * tstep; const char* cB = (const char*)g.Bt + (size_t)cur.pn * tstep;
;     S.a_ready(cur);
;     if constexpr (SP2) {
;         PG8_STAGE(PG8_SB(0, 0), cB, voffB); PG8_STAGE(PG8_SB(0, 1), cB + hstep, voffB); PG8_STAGE(PG8_SA(0, 0), cA, voffA); PG8_STAGE(PG8_SA(0, 1), cA + hstep, voffA);
;         if (wr == 1) PG8_BAR;
;         PG8_WAIT_V(2); PG8_BAR;
;         PG8_STAGE(PG8_SB(1, 0), cB + kstep, voffB); PG8_STAGE(PG8_SA(1, 0), cA + kstep, voffA); PG8_STAGE(PG8_SB(1, 1), cB + hstep + kstep, voffB);
;         PG8_WAIT_V(6); PG8_BAR;
;     } else {
;         PG8_STAGE(PG8_SB(0, 0), cB, voffB); PG8_STAGE(PG8_SA(0, 0), cA, voffA); PG8_STAGE(PG8_SB(0, 1), cB + hstep, voffB); PG8_STAGE(PG8_SA(0, 1), cA + hstep, voffA);
;         if (wr == 1) PG8_BAR;
;         PG8_WAIT_V(4); PG8_BAR;
;         PG8_STAGE(PG8_SB(1, 0), cB + kstep, voffB); PG8_STAGE(PG8_SA(1, 0), cA + kstep, voffA); PG8_STAGE(PG8_SB(1, 1), cB + hstep + kstep, voffB);
;         PG8_WAIT_V(6); PG8_BAR;
;     }
;     for (;;) {
;         const bool has_next = S.next(ui + 1, nxt);
;         const char* nA = has_next ? (const char*)g.A + (size_t)nxt.pm * tstep : cA; const char* nB = has_next ? (const char*)g.Bt + (size_t)nxt.pn * tstep : cB;
;         for (int t = 0; t < nt; t += 2) {
;             const bool last = (t == nt - 2);
;             const char* a1 = cA + (size_t)(t + 1) * kstep;
;             const char* a2 = last ? nA : cA + (size_t)(t + 2) * kstep; const char* b2 = last ? nB : cB + (size_t)(t + 2) * kstep;
;             const char* a3 = a2 + kstep; const char* b3 = b2 + kstep;
;             if (last && has_next) S.a_ready(nxt);
;             if constexpr (SP2) {
;             PG8_LDB(B0, 0, 0); PG8_LDB(B1, 0, 1); PG8_SCHED; PG8_LDA(At, 0, 0); PG8_STAGE(PG8_SA(1, 1), a1 + hstep, voffA);
;             PG8_WAIT_V(8); PG8_WAIT_L(0); PG8_BAR; PG8_MMA(0, 0, At, B0); PG8_MMA(0, 1, At, B1); PG8_BAR; PG8_SCHED;
;             PG8_LDA(At, 0, 1); PG8_STAGE(PG8_SB(0, 0), b2, voffB); PG8_STAGE(PG8_SB(0, 1), b2 + hstep, voffB); PG8_STAGE(PG8_SA(0, 0), a2, voffA);
.Lp3q_lean_q3:
	s_mov_b32 s22, s94
	s_mov_b32 s23, 0
	s_lshl_b64 s[22:23], s[22:23], 19
	s_add_u32 s22, s22, s70
	s_addc_u32 s23, s23, s71
	s_add_u32 s22, s22, 0x80
	s_addc_u32 s23, s23, 0
	s_add_u32 s22, s22, 0x40000
	s_addc_u32 s23, s23, 0
	s_mov_b32 s24, s42
	s_mov_b32 s25, 0
	s_lshl_b64 s[24:25], s[24:25], 19
	s_add_u32 s24, s24, s64
	s_addc_u32 s25, s25, s65
	s_add_u32 s24, s24, 0x80
	s_addc_u32 s25, s25, 0
	s_add_u32 s24, s24, 0x40000
	s_addc_u32 s25, s25, 0
	s_waitcnt vmcnt(0) lgkmcnt(0)
	s_barrier
	s_add_i32 m0, s0, 0xc000
	s_nop 0
	global_load_lds_dwordx4 v140, s[22:23]
	s_add_i32 m0, s0, 0xe000
	s_nop 0
	global_load_lds_dwordx4 v144, s[22:23]
	s_add_u32 s22, s22, 0x80
	s_addc_u32 s23, s23, 0
	s_add_u32 s24, s24, 0x80
	s_addc_u32 s25, s25, 0
	s_mov_b32 m0, s0
	s_nop 0
	global_load_lds_dwordx4 v140, s[22:23]
	s_add_i32 m0, s0, 0x2000
	s_nop 0
	global_load_lds_dwordx4 v144, s[22:23]
	s_add_i32 m0, s0, 0x10000
	s_nop 0
	global_load_lds_dwordx4 v142, s[24:25]
	s_add_i32 m0, s0, 0x12000
	s_nop 0
	global_load_lds_dwordx4 v146, s[24:25]
	s_add_u32 s22, s22, 0x80
	s_addc_u32 s23, s23, 0
	s_add_u32 s24, s24, 0x80
	s_addc_u32 s25, s25, 0
	s_add_i32 m0, s0, 0x8000
	s_nop 0
	global_load_lds_dwordx4 v140, s[22:23]
	s_add_i32 m0, s0, 0xa000
	s_nop 0
	global_load_lds_dwordx4 v144, s[22:23]
	s_add_i32 m0, s0, 0x18000
	s_nop 0
	global_load_lds_dwordx4 v142, s[24:25]
	s_add_i32 m0, s0, 0x1a000
	s_nop 0
	global_load_lds_dwordx4 v146, s[24:25]
	ds_read_b128 v[180:183], v161
	ds_read_b128 v[184:187], v161 offset:1024
	ds_read_b128 v[188:191], v161 offset:2048
	ds_read_b128 v[192:195], v161 offset:3072
	ds_read_b128 v[196:199], v162 offset:16384
	ds_read_b128 v[200:203], v162 offset:17408
	ds_read_b128 v[204:207], v162 offset:18432
	ds_read_b128 v[208:211], v162 offset:19456
	ds_read_b128 v[212:215], v162 offset:20480
	ds_read_b128 v[216:219], v162 offset:21504
	ds_read_b128 v[220:223], v162 offset:22528
	ds_read_b128 v[224:227], v162 offset:23552
	s_waitcnt lgkmcnt(0)
	v_mfma_f32_16x16x32_bf16 v[52:55], v[180:183], v[196:199], v[52:55]
	v_mfma_f32_16x16x32_bf16 v[48:51], v[188:191], v[196:199], v[48:51]
	v_mfma_f32_16x16x32_bf16 v[36:39], v[180:183], v[204:207], v[36:39]
	v_mfma_f32_16x16x32_bf16 v[32:35], v[188:191], v[204:207], v[32:35]
	v_mfma_f32_16x16x32_bf16 v[20:23], v[180:183], v[212:215], v[20:23]
	v_mfma_f32_16x16x32_bf16 v[16:19], v[188:191], v[212:215], v[16:19]
	v_mfma_f32_16x16x32_bf16 v[4:7], v[180:183], v[220:223], v[4:7]
	v_mfma_f32_16x16x32_bf16 v[0:3], v[188:191], v[220:223], v[0:3]
	v_mfma_f32_16x16x32_bf16 v[52:55], v[184:187], v[200:203], v[52:55]
	v_mfma_f32_16x16x32_bf16 v[48:51], v[192:195], v[200:203], v[48:51]
	v_mfma_f32_16x16x32_bf16 v[36:39], v[184:187], v[208:211], v[36:39]
	v_mfma_f32_16x16x32_bf16 v[32:35], v[192:195], v[208:211], v[32:35]
	v_mfma_f32_16x16x32_bf16 v[20:23], v[184:187], v[216:219], v[20:23]
	v_mfma_f32_16x16x32_bf16 v[16:19], v[192:195], v[216:219], v[16:19]
	v_mfma_f32_16x16x32_bf16 v[4:7], v[184:187], v[224:227], v[4:7]
	v_mfma_f32_16x16x32_bf16 v[0:3], v[192:195], v[224:227], v[0:3]
	s_waitcnt vmcnt(8)
	s_barrier
	ds_read_b128 v[180:183], v164
	ds_read_b128 v[184:187], v164 offset:1024
	ds_read_b128 v[188:191], v164 offset:2048
	ds_read_b128 v[192:195], v164 offset:3072
	ds_read_b128 v[196:199], v162 offset:49152
	ds_read_b128 v[200:203], v162 offset:50176
	ds_read_b128 v[204:207], v162 offset:51200
	ds_read_b128 v[208:211], v162 offset:52224
	ds_read_b128 v[212:215], v162 offset:53248
	ds_read_b128 v[216:219], v162 offset:54272
	ds_read_b128 v[220:223], v162 offset:55296
	ds_read_b128 v[224:227], v162 offset:56320
	s_add_u32 s22, s22, 0x80
	s_addc_u32 s23, s23, 0
	s_add_u32 s24, s24, 0x80
	s_addc_u32 s25, s25, 0
	s_add_i32 m0, s0, 0x4000
	s_nop 0
	global_load_lds_dwordx4 v140, s[22:23]
	s_add_i32 m0, s0, 0x6000
	s_nop 0
	global_load_lds_dwordx4 v144, s[22:23]
	s_add_i32 m0, s0, 0x14000
	s_nop 0
	global_load_lds_dwordx4 v142, s[24:25]
	s_add_i32 m0, s0, 0x16000
	s_nop 0
	global_load_lds_dwordx4 v146, s[24:25]
	s_waitcnt lgkmcnt(0)
	v_mfma_f32_16x16x32_bf16 v[52:55], v[180:183], v[196:199], v[52:55]
	v_mfma_f32_16x16x32_bf16 v[48:51], v[188:191], v[196:199], v[48:51]
	v_mfma_f32_16x16x32_bf16 v[36:39], v[180:183], v[204:207], v[36:39]
	v_mfma_f32_16x16x32_bf16 v[32:35], v[188:191], v[204:207], v[32:35]
	v_mfma_f32_16x16x32_bf16 v[20:23], v[180:183], v[212:215], v[20:23]
	v_mfma_f32_16x16x32_bf16 v[16:19], v[188:191], v[212:215], v[16:19]
	v_mfma_f32_16x16x32_bf16 v[4:7], v[180:183], v[220:223], v[4:7]
	v_mfma_f32_16x16x32_bf16 v[0:3], v[188:191], v[220:223], v[0:3]
	v_mfma_f32_16x16x32_bf16 v[52:55], v[184:187], v[200:203], v[52:55]
	v_mfma_f32_16x16x32_bf16 v[48:51], v[192:195], v[200:203], v[48:51]
	v_mfma_f32_16x16x32_bf16 v[36:39], v[184:187], v[208:211], v[36:39]
	v_mfma_f32_16x16x32_bf16 v[32:35], v[192:195], v[208:211], v[32:35]
	v_mfma_f32_16x16x32_bf16 v[20:23], v[184:187], v[216:219], v[20:23]
	v_mfma_f32_16x16x32_bf16 v[16:19], v[192:195], v[216:219], v[16:19]
	v_mfma_f32_16x16x32_bf16 v[4:7], v[184:187], v[224:227], v[4:7]
	v_mfma_f32_16x16x32_bf16 v[0:3], v[192:195], v[224:227], v[0:3]
	s_waitcnt vmcnt(8)
	s_barrier
; #define PG8_STAGE(bufoff, gbase, voff) do { _Pragma("unroll") for (int _i = 0; _i < 2; ++_i) \
;         __builtin_amdgcn_global_load_lds((const unsigned*)((const char*)(gbase) + (voff)[_i]), (PG8_LAS unsigned*)(lds + (bufoff) + ldsw + _i * 8192), 16, 0, 0); } while (0)
; #define PG8_LDA(dst, b, h) do { _Pragma("unroll") for (int m = 0; m < 4; ++m) _Pragma("unroll") for (int k = 0; k < 2; ++k) dst[m][k] = *(const PG8_LAS bf16x8*)(lds + PG8_SA(b, h) + aoff + m * 2048 + k * 1024); } while (0)
; #define PG8_LDB(dst, b, h) do { _Pragma("unroll") for (int n = 0; n < 2; ++n) _Pragma("unroll") for (int k = 0; k < 2; ++k) dst[n][k] = *(const PG8_LAS bf16x8*)(lds + PG8_SB(b, h) + boff + n * 2048 + k * 1024); } while (0)
; #define PG8_MMA(ai, bj, At, Bt) do { __builtin_amdgcn_s_setprio(1); _Pragma("unroll") for (int m = 0; m < 4; ++m) _Pragma("unroll") for (int n = 0; n < 2; ++n) _Pragma("unroll") for (int k = 0; k < 2; ++k) \
;         acc[ai][bj][m][n] = __builtin_amdgcn_mfma_f32_16x16x32_bf16(Bt[n][k], At[m][k], acc[ai][bj][m][n], 0, 0, 0); __builtin_amdgcn_s_setprio(0); } while (0)
; #define PG8_WAIT_V(n) asm volatile("s_waitcnt vmcnt(" #n ")" ::: "memory")
; template <class Epi, class Sched, bool ALIGN_EPI = false, bool SP2 = false>
; __device__ __forceinline__ void gemm_phase(PG8_LAS unsigned char* lds, const Gemm g, const Sched& S, const Epi& E) {
;     ...
;             PG8_LDB(B0, 0, 0); PG8_LDB(B1, 0, 1); PG8_SCHED; PG8_LDA(At, 0, 0); PG8_STAGE(PG8_SA(1, 1), a1 + hstep, voffA);
;             PG8_WAIT_V(8); PG8_WAIT_L(0); PG8_BAR; PG8_MMA(0, 0, At, B0); PG8_MMA(0, 1, At, B1); PG8_BAR; PG8_SCHED;
;             PG8_LDA(At, 0, 1); PG8_STAGE(PG8_SB(0, 0), b2, voffB); PG8_STAGE(PG8_SB(0, 1), b2 + hstep, voffB); PG8_STAGE(PG8_SA(0, 0), a2, voffA);
;             PG8_WAIT_V(8); PG8_WAIT_L(0); PG8_BAR; PG8_MMA(1, 0, At, B0); PG8_MMA(1, 1, At, B1); PG8_BAR; PG8_SCHED;
;             PG8_LDB(B0, 1, 0); PG8_LDB(B1, 1, 1); PG8_SCHED; PG8_LDA(At, 1, 0); PG8_STAGE(PG8_SA(0, 1), a2 + hstep, voffA);
;             PG8_WAIT_V(8); PG8_WAIT_L(0); PG8_BAR; PG8_MMA(0, 0, At, B0); PG8_MMA(0, 1, At, B1); PG8_BAR; PG8_SCHED;
;             PG8_LDA(At, 1, 1); PG8_STAGE(PG8_SB(1, 0), b3, voffB); PG8_STAGE(PG8_SB(1, 1), b3 + hstep, voffB); PG8_STAGE(PG8_SA(1, 0), a3, voffA);
;             PG8_WAIT_V(8); PG8_WAIT_L(0); PG8_BAR; PG8_MMA(1, 0, At, B0); PG8_MMA(1, 1, At, B1); PG8_BAR; PG8_SCHED;
	ds_read_b128 v[180:183], v160
	ds_read_b128 v[184:187], v160 offset:1024
	ds_read_b128 v[188:191], v160 offset:2048
	ds_read_b128 v[192:195], v160 offset:3072
	ds_read_b128 v[196:199], v162
	ds_read_b128 v[200:203], v162 offset:1024
	ds_read_b128 v[204:207], v162 offset:2048
	ds_read_b128 v[208:211], v162 offset:3072
	ds_read_b128 v[212:215], v162 offset:4096
	ds_read_b128 v[216:219], v162 offset:5120
	ds_read_b128 v[220:223], v162 offset:6144
	ds_read_b128 v[224:227], v162 offset:7168
	s_add_u32 s22, s22, 0x80
	s_addc_u32 s23, s23, 0
	s_add_u32 s24, s24, 0x80
	s_addc_u32 s25, s25, 0
	s_add_i32 m0, s0, 0xc000
	s_nop 0
	global_load_lds_dwordx4 v140, s[22:23]
	s_add_i32 m0, s0, 0xe000
	s_nop 0
	global_load_lds_dwordx4 v144, s[22:23]
	s_add_i32 m0, s0, 0x1c000
	s_nop 0
	global_load_lds_dwordx4 v142, s[24:25]
	s_add_i32 m0, s0, 0x1e000
	s_nop 0
	global_load_lds_dwordx4 v146, s[24:25]
	s_waitcnt lgkmcnt(0)
	v_mfma_f32_16x16x32_bf16 v[52:55], v[180:183], v[196:199], v[52:55]
	v_mfma_f32_16x16x32_bf16 v[48:51], v[188:191], v[196:199], v[48:51]
	v_mfma_f32_16x16x32_bf16 v[36:39], v[180:183], v[204:207], v[36:39]
	v_mfma_f32_16x16x32_bf16 v[32:35], v[188:191], v[204:207], v[32:35]
	v_mfma_f32_16x16x32_bf16 v[20:23], v[180:183], v[212:215], v[20:23]
	v_mfma_f32_16x16x32_bf16 v[16:19], v[188:191], v[212:215], v[16:19]
	v_mfma_f32_16x16x32_bf16 v[4:7], v[180:183], v[220:223], v[4:7]
	v_mfma_f32_16x16x32_bf16 v[0:3], v[188:191], v[220:223], v[0:3]
	v_mfma_f32_16x16x32_bf16 v[52:55], v[184:187], v[200:203], v[52:55]
	v_mfma_f32_16x16x32_bf16 v[48:51], v[192:195], v[200:203], v[48:51]
	v_mfma_f32_16x16x32_bf16 v[36:39], v[184:187], v[208:211], v[36:39]
	v_mfma_f32_16x16x32_bf16 v[32:35], v[192:195], v[208:211], v[32:35]
	v_mfma_f32_16x16x32_bf16 v[20:23], v[184:187], v[216:219], v[20:23]
	v_mfma_f32_16x16x32_bf16 v[16:19], v[192:195], v[216:219], v[16:19]
	v_mfma_f32_16x16x32_bf16 v[4:7], v[184:187], v[224:227], v[4:7]
	v_mfma_f32_16x16x32_bf16 v[0:3], v[192:195], v[224:227], v[0:3]
	s_waitcnt vmcnt(8)
	s_barrier
	ds_read_b128 v[180:183], v163
	ds_read_b128 v[184:187], v163 offset:1024
	ds_read_b128 v[188:191], v163 offset:2048
	ds_read_b128 v[192:195], v163 offset:3072
	ds_read_b128 v[196:199], v162 offset:32768
	ds_read_b128 v[200:203], v162 offset:33792
	ds_read_b128 v[204:207], v162 offset:34816
	ds_read_b128 v[208:211], v162 offset:35840
	ds_read_b128 v[212:215], v162 offset:36864
	ds_read_b128 v[216:219], v162 offset:37888
	ds_read_b128 v[220:223], v162 offset:38912
	ds_read_b128 v[224:227], v162 offset:39936
	s_add_u32 s22, s22, 0x80
	s_addc_u32 s23, s23, 0
	s_add_u32 s24, s24, 0x80
	s_addc_u32 s25, s25, 0
	s_mov_b32 m0, s0
	s_nop 0
	global_load_lds_dwordx4 v140, s[22:23]
	s_add_i32 m0, s0, 0x2000
	s_nop 0
	global_load_lds_dwordx4 v144, s[22:23]
	s_add_i32 m0, s0, 0x10000
	s_nop 0
	global_load_lds_dwordx4 v142, s[24:25]
	s_add_i32 m0, s0, 0x12000
	s_nop 0
	global_load_lds_dwordx4 v146, s[24:25]
	s_waitcnt lgkmcnt(0)
	v_mfma_f32_16x16x32_bf16 v[52:55], v[180:183], v[196:199], v[52:55]
	v_mfma_f32_16x16x32_bf16 v[48:51], v[188:191], v[196:199], v[48:51]
	v_mfma_f32_16x16x32_bf16 v[36:39], v[180:183], v[204:207], v[36:39]
	v_mfma_f32_16x16x32_bf16 v[32:35], v[188:191], v[204:207], v[32:35]
	v_mfma_f32_16x16x32_bf16 v[20:23], v[180:183], v[212:215], v[20:23]
	v_mfma_f32_16x16x32_bf16 v[16:19], v[188:191], v[212:215], v[16:19]
	v_mfma_f32_16x16x32_bf16 v[4:7], v[180:183], v[220:223], v[4:7]
	v_mfma_f32_16x16x32_bf16 v[0:3], v[188:191], v[220:223], v[0:3]
	v_mfma_f32_16x16x32_bf16 v[52:55], v[184:187], v[200:203], v[52:55]
	v_mfma_f32_16x16x32_bf16 v[48:51], v[192:195], v[200:203], v[48:51]
	v_mfma_f32_16x16x32_bf16 v[36:39], v[184:187], v[208:211], v[36:39]
	v_mfma_f32_16x16x32_bf16 v[32:35], v[192:195], v[208:211], v[32:35]
	v_mfma_f32_16x16x32_bf16 v[20:23], v[184:187], v[216:219], v[20:23]
	v_mfma_f32_16x16x32_bf16 v[16:19], v[192:195], v[216:219], v[16:19]
	v_mfma_f32_16x16x32_bf16 v[4:7], v[184:187], v[224:227], v[4:7]
	v_mfma_f32_16x16x32_bf16 v[0:3], v[192:195], v[224:227], v[0:3]
	s_waitcnt vmcnt(8)
	s_barrier
	ds_read_b128 v[180:183], v161
	ds_read_b128 v[184:187], v161 offset:1024
	ds_read_b128 v[188:191], v161 offset:2048
	ds_read_b128 v[192:195], v161 offset:3072
	ds_read_b128 v[196:199], v162 offset:16384
	ds_read_b128 v[200:203], v162 offset:17408
	ds_read_b128 v[204:207], v162 offset:18432
	ds_read_b128 v[208:211], v162 offset:19456
	ds_read_b128 v[212:215], v162 offset:20480
	ds_read_b128 v[216:219], v162 offset:21504
	ds_read_b128 v[220:223], v162 offset:22528
	ds_read_b128 v[224:227], v162 offset:23552
	s_add_u32 s22, s22, 0x80
	s_addc_u32 s23, s23, 0
	s_add_u32 s24, s24, 0x80
	s_addc_u32 s25, s25, 0
	s_add_i32 m0, s0, 0x8000
	s_nop 0
	global_load_lds_dwordx4 v140, s[22:23]
	s_add_i32 m0, s0, 0xa000
	s_nop 0
	global_load_lds_dwordx4 v144, s[22:23]
	s_add_i32 m0, s0, 0x18000
	s_nop 0
	global_load_lds_dwordx4 v142, s[24:25]
	s_add_i32 m0, s0, 0x1a000
	s_nop 0
	global_load_lds_dwordx4 v146, s[24:25]
	s_waitcnt lgkmcnt(0)
	v_mfma_f32_16x16x32_bf16 v[52:55], v[180:183], v[196:199], v[52:55]
	v_mfma_f32_16x16x32_bf16 v[48:51], v[188:191], v[196:199], v[48:51]
	v_mfma_f32_16x16x32_bf16 v[36:39], v[180:183], v[204:207], v[36:39]
	v_mfma_f32_16x16x32_bf16 v[32:35], v[188:191], v[204:207], v[32:35]
	v_mfma_f32_16x16x32_bf16 v[20:23], v[180:183], v[212:215], v[20:23]
	v_mfma_f32_16x16x32_bf16 v[16:19], v[188:191], v[212:215], v[16:19]
	v_mfma_f32_16x16x32_bf16 v[4:7], v[180:183], v[220:223], v[4:7]
	v_mfma_f32_16x16x32_bf16 v[0:3], v[188:191], v[220:223], v[0:3]
	v_mfma_f32_16x16x32_bf16 v[52:55], v[184:187], v[200:203], v[52:55]
	v_mfma_f32_16x16x32_bf16 v[48:51], v[192:195], v[200:203], v[48:51]
	v_mfma_f32_16x16x32_bf16 v[36:39], v[184:187], v[208:211], v[36:39]
	v_mfma_f32_16x16x32_bf16 v[32:35], v[192:195], v[208:211], v[32:35]
	v_mfma_f32_16x16x32_bf16 v[20:23], v[184:187], v[216:219], v[20:23]
	v_mfma_f32_16x16x32_bf16 v[16:19], v[192:195], v[216:219], v[16:19]
	v_mfma_f32_16x16x32_bf16 v[4:7], v[184:187], v[224:227], v[4:7]
	v_mfma_f32_16x16x32_bf16 v[0:3], v[192:195], v[224:227], v[0:3]
	s_waitcnt vmcnt(8)
	s_barrier
; #define PG8_STAGE(bufoff, gbase, voff) do { _Pragma("unroll") for (int _i = 0; _i < 2; ++_i) \
;         __builtin_amdgcn_global_load_lds((const unsigned*)((const char*)(gbase) + (voff)[_i]), (PG8_LAS unsigned*)(lds + (bufoff) + ldsw + _i * 8192), 16, 0, 0); } while (0)
; #define PG8_LDA(dst, b, h) do { _Pragma("unroll") for (int m = 0; m < 4; ++m) _Pragma("unroll") for (int k = 0; k < 2; ++k) dst[m][k] = *(const PG8_LAS bf16x8*)(lds + PG8_SA(b, h) + aoff + m * 2048 + k * 1024); } while (0)
; #define PG8_LDB(dst, b, h) do { _Pragma("unroll") for (int n = 0; n < 2; ++n) _Pragma("unroll") for (int k = 0; k < 2; ++k) dst[n][k] = *(const PG8_LAS bf16x8*)(lds + PG8_SB(b, h) + boff + n * 2048 + k * 1024); } while (0)
; #define PG8_MMA(ai, bj, At, Bt) do { __builtin_amdgcn_s_setprio(1); _Pragma("unroll") for (int m = 0; m < 4; ++m) _Pragma("unroll") for (int n = 0; n < 2; ++n) _Pragma("unroll") for (int k = 0; k < 2; ++k) \
;         acc[ai][bj][m][n] = __builtin_amdgcn_mfma_f32_16x16x32_bf16(Bt[n][k], At[m][k], acc[ai][bj][m][n], 0, 0, 0); __builtin_amdgcn_s_setprio(0); } while (0)
; #define PG8_WAIT_V(n) asm volatile("s_waitcnt vmcnt(" #n ")" ::: "memory")
; template <class Epi, class Sched, bool ALIGN_EPI = false, bool SP2 = false>
; __device__ __forceinline__ void gemm_phase(PG8_LAS unsigned char* lds, const Gemm g, const Sched& S, const Epi& E) {
;     ...
;             PG8_LDB(B0, 0, 0); PG8_LDB(B1, 0, 1); PG8_SCHED; PG8_LDA(At, 0, 0); PG8_STAGE(PG8_SA(1, 1), a1 + hstep, voffA);
;             PG8_WAIT_V(8); PG8_WAIT_L(0); PG8_BAR; PG8_MMA(0, 0, At, B0); PG8_MMA(0, 1, At, B1); PG8_BAR; PG8_SCHED;
;             PG8_LDA(At, 0, 1); PG8_STAGE(PG8_SB(0, 0), b2, voffB); PG8_STAGE(PG8_SB(0, 1), b2 + hstep, voffB); PG8_STAGE(PG8_SA(0, 0), a2, voffA);
;             PG8_WAIT_V(8); PG8_WAIT_L(0); PG8_BAR; PG8_MMA(1, 0, At, B0); PG8_MMA(1, 1, At, B1); PG8_BAR; PG8_SCHED;
;             PG8_LDB(B0, 1, 0); PG8_LDB(B1, 1, 1); PG8_SCHED; PG8_LDA(At, 1, 0); PG8_STAGE(PG8_SA(0, 1), a2 + hstep, voffA);
;             PG8_WAIT_V(8); PG8_WAIT_L(0); PG8_BAR; PG8_MMA(0, 0, At, B0); PG8_MMA(0, 1, At, B1); PG8_BAR; PG8_SCHED;
;             PG8_LDA(At, 1, 1); PG8_STAGE(PG8_SB(1, 0), b3, voffB); PG8_STAGE(PG8_SB(1, 1), b3 + hstep, voffB); PG8_STAGE(PG8_SA(1, 0), a3, voffA);
;             PG8_WAIT_V(8); PG8_WAIT_L(0); PG8_BAR; PG8_MMA(1, 0, At, B0); PG8_MMA(1, 1, At, B1); PG8_BAR; PG8_SCHED;
	ds_read_b128 v[180:183], v164
	ds_read_b128 v[184:187], v164 offset:1024
	ds_read_b128 v[188:191], v164 offset:2048
	ds_read_b128 v[192:195], v164 offset:3072
	ds_read_b128 v[196:199], v162 offset:49152
	ds_read_b128 v[200:203], v162 offset:50176
	ds_read_b128 v[204:207], v162 offset:51200
	ds_read_b128 v[208:211], v162 offset:52224
	ds_read_b128 v[212:215], v162 offset:53248
	ds_read_b128 v[216:219], v162 offset:54272
	ds_read_b128 v[220:223], v162 offset:55296
	ds_read_b128 v[224:227], v162 offset:56320
	s_add_u32 s22, s22, 0x80
	s_addc_u32 s23, s23, 0
	s_add_u32 s24, s24, 0x80
	s_addc_u32 s25, s25, 0
	s_add_i32 m0, s0, 0x4000
	s_nop 0
	global_load_lds_dwordx4 v140, s[22:23]
	s_add_i32 m0, s0, 0x6000
	s_nop 0
	global_load_lds_dwordx4 v144, s[22:23]
	s_add_i32 m0, s0, 0x14000
	s_nop 0
	global_load_lds_dwordx4 v142, s[24:25]
	s_add_i32 m0, s0, 0x16000
	s_nop 0
	global_load_lds_dwordx4 v146, s[24:25]
	s_waitcnt lgkmcnt(0)
	v_mfma_f32_16x16x32_bf16 v[52:55], v[180:183], v[196:199], v[52:55]
	v_mfma_f32_16x16x32_bf16 v[48:51], v[188:191], v[196:199], v[48:51]
	v_mfma_f32_16x16x32_bf16 v[36:39], v[180:183], v[204:207], v[36:39]
	v_mfma_f32_16x16x32_bf16 v[32:35], v[188:191], v[204:207], v[32:35]
	v_mfma_f32_16x16x32_bf16 v[20:23], v[180:183], v[212:215], v[20:23]
	v_mfma_f32_16x16x32_bf16 v[16:19], v[188:191], v[212:215], v[16:19]
	v_mfma_f32_16x16x32_bf16 v[4:7], v[180:183], v[220:223], v[4:7]
	v_mfma_f32_16x16x32_bf16 v[0:3], v[188:191], v[220:223], v[0:3]
	v_mfma_f32_16x16x32_bf16 v[52:55], v[184:187], v[200:203], v[52:55]
	v_mfma_f32_16x16x32_bf16 v[48:51], v[192:195], v[200:203], v[48:51]
	v_mfma_f32_16x16x32_bf16 v[36:39], v[184:187], v[208:211], v[36:39]
	v_mfma_f32_16x16x32_bf16 v[32:35], v[192:195], v[208:211], v[32:35]
	v_mfma_f32_16x16x32_bf16 v[20:23], v[184:187], v[216:219], v[20:23]
	v_mfma_f32_16x16x32_bf16 v[16:19], v[192:195], v[216:219], v[16:19]
	v_mfma_f32_16x16x32_bf16 v[4:7], v[184:187], v[224:227], v[4:7]
	v_mfma_f32_16x16x32_bf16 v[0:3], v[192:195], v[224:227], v[0:3]
	s_waitcnt vmcnt(8)
	s_barrier
	ds_read_b128 v[180:183], v160
	ds_read_b128 v[184:187], v160 offset:1024
	ds_read_b128 v[188:191], v160 offset:2048
	ds_read_b128 v[192:195], v160 offset:3072
	ds_read_b128 v[196:199], v162
	ds_read_b128 v[200:203], v162 offset:1024
	ds_read_b128 v[204:207], v162 offset:2048
	ds_read_b128 v[208:211], v162 offset:3072
	ds_read_b128 v[212:215], v162 offset:4096
	ds_read_b128 v[216:219], v162 offset:5120
	ds_read_b128 v[220:223], v162 offset:6144
	ds_read_b128 v[224:227], v162 offset:7168
	s_add_u32 s22, s22, 0x80
	s_addc_u32 s23, s23, 0
	s_add_u32 s24, s24, 0x80
	s_addc_u32 s25, s25, 0
	s_add_i32 m0, s0, 0xc000
	s_nop 0
	global_load_lds_dwordx4 v140, s[22:23]
	s_add_i32 m0, s0, 0xe000
	s_nop 0
	global_load_lds_dwordx4 v144, s[22:23]
	s_add_i32 m0, s0, 0x1c000
	s_nop 0
	global_load_lds_dwordx4 v142, s[24:25]
	s_add_i32 m0, s0, 0x1e000
	s_nop 0
	global_load_lds_dwordx4 v146, s[24:25]
	s_waitcnt lgkmcnt(0)
	v_mfma_f32_16x16x32_bf16 v[52:55], v[180:183], v[196:199], v[52:55]
	v_mfma_f32_16x16x32_bf16 v[48:51], v[188:191], v[196:199], v[48:51]
	v_mfma_f32_16x16x32_bf16 v[36:39], v[180:183], v[204:207], v[36:39]
	v_mfma_f32_16x16x32_bf16 v[32:35], v[188:191], v[204:207], v[32:35]
	v_mfma_f32_16x16x32_bf16 v[20:23], v[180:183], v[212:215], v[20:23]
	v_mfma_f32_16x16x32_bf16 v[16:19], v[188:191], v[212:215], v[16:19]
	v_mfma_f32_16x16x32_bf16 v[4:7], v[180:183], v[220:223], v[4:7]
	v_mfma_f32_16x16x32_bf16 v[0:3], v[188:191], v[220:223], v[0:3]
	v_mfma_f32_16x16x32_bf16 v[52:55], v[184:187], v[200:203], v[52:55]
	v_mfma_f32_16x16x32_bf16 v[48:51], v[192:195], v[200:203], v[48:51]
	v_mfma_f32_16x16x32_bf16 v[36:39], v[184:187], v[208:211], v[36:39]
	v_mfma_f32_16x16x32_bf16 v[32:35], v[192:195], v[208:211], v[32:35]
	v_mfma_f32_16x16x32_bf16 v[20:23], v[184:187], v[216:219], v[20:23]
	v_mfma_f32_16x16x32_bf16 v[16:19], v[192:195], v[216:219], v[16:19]
	v_mfma_f32_16x16x32_bf16 v[4:7], v[184:187], v[224:227], v[4:7]
	v_mfma_f32_16x16x32_bf16 v[0:3], v[192:195], v[224:227], v[0:3]
	s_waitcnt vmcnt(8)
	s_barrier
	ds_read_b128 v[180:183], v163
	ds_read_b128 v[184:187], v163 offset:1024
	ds_read_b128 v[188:191], v163 offset:2048
	ds_read_b128 v[192:195], v163 offset:3072
	ds_read_b128 v[196:199], v162 offset:32768
	ds_read_b128 v[200:203], v162 offset:33792
	ds_read_b128 v[204:207], v162 offset:34816
	ds_read_b128 v[208:211], v162 offset:35840
	ds_read_b128 v[212:215], v162 offset:36864
	ds_read_b128 v[216:219], v162 offset:37888
	ds_read_b128 v[220:223], v162 offset:38912
	ds_read_b128 v[224:227], v162 offset:39936
	s_add_u32 s22, s22, 0x80
	s_addc_u32 s23, s23, 0
	s_add_u32 s24, s24, 0x80
	s_addc_u32 s25, s25, 0
	s_mov_b32 m0, s0
	s_nop 0
	global_load_lds_dwordx4 v140, s[22:23]
	s_add_i32 m0, s0, 0x2000
	s_nop 0
	global_load_lds_dwordx4 v144, s[22:23]
	s_add_i32 m0, s0, 0x10000
	s_nop 0
	global_load_lds_dwordx4 v142, s[24:25]
	s_add_i32 m0, s0, 0x12000
	s_nop 0
	global_load_lds_dwordx4 v146, s[24:25]
	s_waitcnt lgkmcnt(0)
	v_mfma_f32_16x16x32_bf16 v[52:55], v[180:183], v[196:199], v[52:55]
	v_mfma_f32_16x16x32_bf16 v[48:51], v[188:191], v[196:199], v[48:51]
	v_mfma_f32_16x16x32_bf16 v[36:39], v[180:183], v[204:207], v[36:39]
	v_mfma_f32_16x16x32_bf16 v[32:35], v[188:191], v[204:207], v[32:35]
	v_mfma_f32_16x16x32_bf16 v[20:23], v[180:183], v[212:215], v[20:23]
	v_mfma_f32_16x16x32_bf16 v[16:19], v[188:191], v[212:215], v[16:19]
	v_mfma_f32_16x16x32_bf16 v[4:7], v[180:183], v[220:223], v[4:7]
	v_mfma_f32_16x16x32_bf16 v[0:3], v[188:191], v[220:223], v[0:3]
	v_mfma_f32_16x16x32_bf16 v[52:55], v[184:187], v[200:203], v[52:55]
	v_mfma_f32_16x16x32_bf16 v[48:51], v[192:195], v[200:203], v[48:51]
	v_mfma_f32_16x16x32_bf16 v[36:39], v[184:187], v[208:211], v[36:39]
	v_mfma_f32_16x16x32_bf16 v[32:35], v[192:195], v[208:211], v[32:35]
	v_mfma_f32_16x16x32_bf16 v[20:23], v[184:187], v[216:219], v[20:23]
	v_mfma_f32_16x16x32_bf16 v[16:19], v[192:195], v[216:219], v[16:19]
	v_mfma_f32_16x16x32_bf16 v[4:7], v[184:187], v[224:227], v[4:7]
	v_mfma_f32_16x16x32_bf16 v[0:3], v[192:195], v[224:227], v[0:3]
	s_waitcnt vmcnt(8)
	s_barrier
; #define PG8_STAGE(bufoff, gbase, voff) do { _Pragma("unroll") for (int _i = 0; _i < 2; ++_i) \
;         __builtin_amdgcn_global_load_lds((const unsigned*)((const char*)(gbase) + (voff)[_i]), (PG8_LAS unsigned*)(lds + (bufoff) + ldsw + _i * 8192), 16, 0, 0); } while (0)
; #define PG8_LDA(dst, b, h) do { _Pragma("unroll") for (int m = 0; m < 4; ++m) _Pragma("unroll") for (int k = 0; k < 2; ++k) dst[m][k] = *(const PG8_LAS bf16x8*)(lds + PG8_SA(b, h) + aoff + m * 2048 + k * 1024); } while (0)
; #define PG8_LDB(dst, b, h) do { _Pragma("unroll") for (int n = 0; n < 2; ++n) _Pragma("unroll") for (int k = 0; k < 2; ++k) dst[n][k] = *(const PG8_LAS bf16x8*)(lds + PG8_SB(b, h) + boff + n * 2048 + k * 1024); } while (0)
; #define PG8_MMA(ai, bj, At, Bt) do { __builtin_amdgcn_s_setprio(1); _Pragma("unroll") for (int m = 0; m < 4; ++m) _Pragma("unroll") for (int n = 0; n < 2; ++n) _Pragma("unroll") for (int k = 0; k < 2; ++k) \
;         acc[ai][bj][m][n] = __builtin_amdgcn_mfma_f32_16x16x32_bf16(Bt[n][k], At[m][k], acc[ai][bj][m][n], 0, 0, 0); __builtin_amdgcn_s_setprio(0); } while (0)
; #define PG8_WAIT_V(n) asm volatile("s_waitcnt vmcnt(" #n ")" ::: "memory")
; template <class Epi, class Sched, bool ALIGN_EPI = false, bool SP2 = false>
; __device__ __forceinline__ void gemm_phase(PG8_LAS unsigned char* lds, const Gemm g, const Sched& S, const Epi& E) {
;     ...
;             PG8_LDB(B0, 0, 0); PG8_LDB(B1, 0, 1); PG8_SCHED; PG8_LDA(At, 0, 0); PG8_STAGE(PG8_SA(1, 1), a1 + hstep, voffA);
;             PG8_WAIT_V(8); PG8_WAIT_L(0); PG8_BAR; PG8_MMA(0, 0, At, B0); PG8_MMA(0, 1, At, B1); PG8_BAR; PG8_SCHED;
;             PG8_LDA(At, 0, 1); PG8_STAGE(PG8_SB(0, 0), b2, voffB); PG8_STAGE(PG8_SB(0, 1), b2 + hstep, voffB); PG8_STAGE(PG8_SA(0, 0), a2, voffA);
;             PG8_WAIT_V(8); PG8_WAIT_L(0); PG8_BAR; PG8_MMA(1, 0, At, B0); PG8_MMA(1, 1, At, B1); PG8_BAR; PG8_SCHED;
;             PG8_LDB(B0, 1, 0); PG8_LDB(B1, 1, 1); PG8_SCHED; PG8_LDA(At, 1, 0); PG8_STAGE(PG8_SA(0, 1), a2 + hstep, voffA);
;             PG8_WAIT_V(8); PG8_WAIT_L(0); PG8_BAR; PG8_MMA(0, 0, At, B0); PG8_MMA(0, 1, At, B1); PG8_BAR; PG8_SCHED;
;             PG8_LDA(At, 1, 1); PG8_STAGE(PG8_SB(1, 0), b3, voffB); PG8_STAGE(PG8_SB(1, 1), b3 + hstep, voffB); PG8_STAGE(PG8_SA(1, 0), a3, voffA);
;             PG8_WAIT_V(8); PG8_WAIT_L(0); PG8_BAR; PG8_MMA(1, 0, At, B0); PG8_MMA(1, 1, At, B1); PG8_BAR; PG8_SCHED;
	ds_read_b128 v[180:183], v161
	ds_read_b128 v[184:187], v161 offset:1024
	ds_read_b128 v[188:191], v161 offset:2048
	ds_read_b128 v[192:195], v161 offset:3072
	ds_read_b128 v[196:199], v162 offset:16384
	ds_read_b128 v[200:203], v162 offset:17408
	ds_read_b128 v[204:207], v162 offset:18432
	ds_read_b128 v[208:211], v162 offset:19456
	ds_read_b128 v[212:215], v162 offset:20480
	ds_read_b128 v[216:219], v162 offset:21504
	ds_read_b128 v[220:223], v162 offset:22528
	ds_read_b128 v[224:227], v162 offset:23552
	s_add_u32 s22, s22, 0x80
	s_addc_u32 s23, s23, 0
	s_add_u32 s24, s24, 0x80
	s_addc_u32 s25, s25, 0
	s_add_i32 m0, s0, 0x8000
	s_nop 0
	global_load_lds_dwordx4 v140, s[22:23]
	s_add_i32 m0, s0, 0xa000
	s_nop 0
	global_load_lds_dwordx4 v144, s[22:23]
	s_add_i32 m0, s0, 0x18000
	s_nop 0
	global_load_lds_dwordx4 v142, s[24:25]
	s_add_i32 m0, s0, 0x1a000
	s_nop 0
	global_load_lds_dwordx4 v146, s[24:25]
	s_waitcnt lgkmcnt(0)
	v_mfma_f32_16x16x32_bf16 v[52:55], v[180:183], v[196:199], v[52:55]
	v_mfma_f32_16x16x32_bf16 v[48:51], v[188:191], v[196:199], v[48:51]
	v_mfma_f32_16x16x32_bf16 v[36:39], v[180:183], v[204:207], v[36:39]
	v_mfma_f32_16x16x32_bf16 v[32:35], v[188:191], v[204:207], v[32:35]
	v_mfma_f32_16x16x32_bf16 v[20:23], v[180:183], v[212:215], v[20:23]
	v_mfma_f32_16x16x32_bf16 v[16:19], v[188:191], v[212:215], v[16:19]
	v_mfma_f32_16x16x32_bf16 v[4:7], v[180:183], v[220:223], v[4:7]
	v_mfma_f32_16x16x32_bf16 v[0:3], v[188:191], v[220:223], v[0:3]
	v_mfma_f32_16x16x32_bf16 v[52:55], v[184:187], v[200:203], v[52:55]
	v_mfma_f32_16x16x32_bf16 v[48:51], v[192:195], v[200:203], v[48:51]
	v_mfma_f32_16x16x32_bf16 v[36:39], v[184:187], v[208:211], v[36:39]
	v_mfma_f32_16x16x32_bf16 v[32:35], v[192:195], v[208:211], v[32:35]
	v_mfma_f32_16x16x32_bf16 v[20:23], v[184:187], v[216:219], v[20:23]
	v_mfma_f32_16x16x32_bf16 v[16:19], v[192:195], v[216:219], v[16:19]
	v_mfma_f32_16x16x32_bf16 v[4:7], v[184:187], v[224:227], v[4:7]
	v_mfma_f32_16x16x32_bf16 v[0:3], v[192:195], v[224:227], v[0:3]
	s_waitcnt vmcnt(8)
	s_barrier
	ds_read_b128 v[180:183], v164
	ds_read_b128 v[184:187], v164 offset:1024
	ds_read_b128 v[188:191], v164 offset:2048
	ds_read_b128 v[192:195], v164 offset:3072
	ds_read_b128 v[196:199], v162 offset:49152
	ds_read_b128 v[200:203], v162 offset:50176
	ds_read_b128 v[204:207], v162 offset:51200
	ds_read_b128 v[208:211], v162 offset:52224
	ds_read_b128 v[212:215], v162 offset:53248
	ds_read_b128 v[216:219], v162 offset:54272
	ds_read_b128 v[220:223], v162 offset:55296
	ds_read_b128 v[224:227], v162 offset:56320
	s_add_u32 s22, s22, 0x80
	s_addc_u32 s23, s23, 0
	s_add_u32 s24, s24, 0x80
	s_addc_u32 s25, s25, 0
	s_add_i32 m0, s0, 0x4000
	s_nop 0
	global_load_lds_dwordx4 v140, s[22:23]
	s_add_i32 m0, s0, 0x6000
	s_nop 0
	global_load_lds_dwordx4 v144, s[22:23]
	s_add_i32 m0, s0, 0x14000
	s_nop 0
	global_load_lds_dwordx4 v142, s[24:25]
	s_add_i32 m0, s0, 0x16000
	s_nop 0
	global_load_lds_dwordx4 v146, s[24:25]
	s_waitcnt lgkmcnt(0)
	v_mfma_f32_16x16x32_bf16 v[52:55], v[180:183], v[196:199], v[52:55]
	v_mfma_f32_16x16x32_bf16 v[48:51], v[188:191], v[196:199], v[48:51]
	v_mfma_f32_16x16x32_bf16 v[36:39], v[180:183], v[204:207], v[36:39]
	v_mfma_f32_16x16x32_bf16 v[32:35], v[188:191], v[204:207], v[32:35]
	v_mfma_f32_16x16x32_bf16 v[20:23], v[180:183], v[212:215], v[20:23]
	v_mfma_f32_16x16x32_bf16 v[16:19], v[188:191], v[212:215], v[16:19]
	v_mfma_f32_16x16x32_bf16 v[4:7], v[180:183], v[220:223], v[4:7]
	v_mfma_f32_16x16x32_bf16 v[0:3], v[188:191], v[220:223], v[0:3]
	v_mfma_f32_16x16x32_bf16 v[52:55], v[184:187], v[200:203], v[52:55]
	v_mfma_f32_16x16x32_bf16 v[48:51], v[192:195], v[200:203], v[48:51]
	v_mfma_f32_16x16x32_bf16 v[36:39], v[184:187], v[208:211], v[36:39]
	v_mfma_f32_16x16x32_bf16 v[32:35], v[192:195], v[208:211], v[32:35]
	v_mfma_f32_16x16x32_bf16 v[20:23], v[184:187], v[216:219], v[20:23]
	v_mfma_f32_16x16x32_bf16 v[16:19], v[192:195], v[216:219], v[16:19]
	v_mfma_f32_16x16x32_bf16 v[4:7], v[184:187], v[224:227], v[4:7]
	v_mfma_f32_16x16x32_bf16 v[0:3], v[192:195], v[224:227], v[0:3]
	s_waitcnt vmcnt(8)
	s_barrier
	ds_read_b128 v[180:183], v160
	ds_read_b128 v[184:187], v160 offset:1024
	ds_read_b128 v[188:191], v160 offset:2048
	ds_read_b128 v[192:195], v160 offset:3072
	ds_read_b128 v[196:199], v162
	ds_read_b128 v[200:203], v162 offset:1024
	ds_read_b128 v[204:207], v162 offset:2048
	ds_read_b128 v[208:211], v162 offset:3072
	ds_read_b128 v[212:215], v162 offset:4096
	ds_read_b128 v[216:219], v162 offset:5120
	ds_read_b128 v[220:223], v162 offset:6144
	ds_read_b128 v[224:227], v162 offset:7168
	s_add_u32 s22, s22, 0x80
	s_addc_u32 s23, s23, 0
	s_add_u32 s24, s24, 0x80
	s_addc_u32 s25, s25, 0
	s_add_i32 m0, s0, 0xc000
	s_nop 0
	global_load_lds_dwordx4 v140, s[22:23]
	s_add_i32 m0, s0, 0xe000
	s_nop 0
	global_load_lds_dwordx4 v144, s[22:23]
	s_add_i32 m0, s0, 0x1c000
	s_nop 0
	global_load_lds_dwordx4 v142, s[24:25]
	s_add_i32 m0, s0, 0x1e000
	s_nop 0
	global_load_lds_dwordx4 v146, s[24:25]
	s_waitcnt lgkmcnt(0)
	v_mfma_f32_16x16x32_bf16 v[52:55], v[180:183], v[196:199], v[52:55]
	v_mfma_f32_16x16x32_bf16 v[48:51], v[188:191], v[196:199], v[48:51]
	v_mfma_f32_16x16x32_bf16 v[36:39], v[180:183], v[204:207], v[36:39]
	v_mfma_f32_16x16x32_bf16 v[32:35], v[188:191], v[204:207], v[32:35]
	v_mfma_f32_16x16x32_bf16 v[20:23], v[180:183], v[212:215], v[20:23]
	v_mfma_f32_16x16x32_bf16 v[16:19], v[188:191], v[212:215], v[16:19]
	v_mfma_f32_16x16x32_bf16 v[4:7], v[180:183], v[220:223], v[4:7]
	v_mfma_f32_16x16x32_bf16 v[0:3], v[188:191], v[220:223], v[0:3]
	v_mfma_f32_16x16x32_bf16 v[52:55], v[184:187], v[200:203], v[52:55]
	v_mfma_f32_16x16x32_bf16 v[48:51], v[192:195], v[200:203], v[48:51]
	v_mfma_f32_16x16x32_bf16 v[36:39], v[184:187], v[208:211], v[36:39]
	v_mfma_f32_16x16x32_bf16 v[32:35], v[192:195], v[208:211], v[32:35]
	v_mfma_f32_16x16x32_bf16 v[20:23], v[184:187], v[216:219], v[20:23]
	v_mfma_f32_16x16x32_bf16 v[16:19], v[192:195], v[216:219], v[16:19]
	v_mfma_f32_16x16x32_bf16 v[4:7], v[184:187], v[224:227], v[4:7]
	v_mfma_f32_16x16x32_bf16 v[0:3], v[192:195], v[224:227], v[0:3]
	s_waitcnt vmcnt(8)
	s_barrier
; #define PG8_STAGE(bufoff, gbase, voff) do { _Pragma("unroll") for (int _i = 0; _i < 2; ++_i) \
;         __builtin_amdgcn_global_load_lds((const unsigned*)((const char*)(gbase) + (voff)[_i]), (PG8_LAS unsigned*)(lds + (bufoff) + ldsw + _i * 8192), 16, 0, 0); } while (0)
; #define PG8_LDA(dst, b, h) do { _Pragma("unroll") for (int m = 0; m < 4; ++m) _Pragma("unroll") for (int k = 0; k < 2; ++k) dst[m][k] = *(const PG8_LAS bf16x8*)(lds + PG8_SA(b, h) + aoff + m * 2048 + k * 1024); } while (0)
; #define PG8_LDB(dst, b, h) do { _Pragma("unroll") for (int n = 0; n < 2; ++n) _Pragma("unroll") for (int k = 0; k < 2; ++k) dst[n][k] = *(const PG8_LAS bf16x8*)(lds + PG8_SB(b, h) + boff + n * 2048 + k * 1024); } while (0)
; #define PG8_WAIT_V(n) asm volatile("s_waitcnt vmcnt(" #n ")" ::: "memory")
; #define PG8_WAIT_L(n) asm volatile("s_waitcnt lgkmcnt(" #n ")" ::: "memory")
; template <class Epi, class Sched, bool ALIGN_EPI = false, bool SP2 = false>
; __device__ __forceinline__ void gemm_phase(PG8_LAS unsigned char* lds, const Gemm g, const Sched& S, const Epi& E) {
;     ...
;             PG8_LDB(B0, 1, 0); PG8_LDB(B1, 1, 1); PG8_SCHED; PG8_LDA(At, 1, 0); PG8_STAGE(PG8_SA(0, 1), a2 + hstep, voffA);
;             PG8_WAIT_V(8); PG8_WAIT_L(0); PG8_BAR; PG8_MMA(0, 0, At, B0); PG8_MMA(0, 1, At, B1); PG8_BAR; PG8_SCHED;
;             PG8_LDA(At, 1, 1); PG8_STAGE(PG8_SB(1, 0), b3, voffB); PG8_STAGE(PG8_SB(1, 1), b3 + hstep, voffB); PG8_STAGE(PG8_SA(1, 0), a3, voffA);
;     DI void operator()(const f32x4 (&acc)[2][2][4][2], const pg8::Unit& u, int wr, int wc, int fr, int fq) const {
;     ...
;                 const int R = u.pm * 256 + ai * 128 + wr * 64 + m * 16 + fr;
;                 const float* xs = nullptr; float* yd = nullptr;
;                 if (R < ROWS_P) { const int b = R / LPAD, t = R - b * LPAD; if (t >= NMETA && t < LP) { const size_t idx = ((size_t)b * SEQ + t - NMETA) * DM; xs = p.x_prompt + idx; yd = p.out + O_YP + idx; } }
;                 else { const size_t idx = (size_t)(R - ROWS_P) * DM; xs = p.x_sample + idx; yd = p.out + O_YS + idx; }
;                 float ss = 0.f;
;                 if (xs) {
; #pragma unroll
;                     for (int bj = 0; bj < 2; ++bj) {
;                         const int n = colt + bj * 128 + wc * 32 + 8 * fq;
;                         const f32x4 x0 = *(const f32x4*)(xs + n), x1 = *(const f32x4*)(xs + n + 4);
	ds_read_b128 v[180:183], v163
	ds_read_b128 v[184:187], v163 offset:1024
	ds_read_b128 v[188:191], v163 offset:2048
	ds_read_b128 v[192:195], v163 offset:3072
	ds_read_b128 v[196:199], v162 offset:32768
	ds_read_b128 v[200:203], v162 offset:33792
	ds_read_b128 v[204:207], v162 offset:34816
	ds_read_b128 v[208:211], v162 offset:35840
	ds_read_b128 v[212:215], v162 offset:36864
	ds_read_b128 v[216:219], v162 offset:37888
	ds_read_b128 v[220:223], v162 offset:38912
	ds_read_b128 v[224:227], v162 offset:39936
	s_add_u32 s22, s22, 0x80
	s_addc_u32 s23, s23, 0
	s_add_u32 s24, s24, 0x80
	s_addc_u32 s25, s25, 0
	s_mov_b32 m0, s0
	s_nop 0
	global_load_lds_dwordx4 v140, s[22:23]
	s_add_i32 m0, s0, 0x2000
	s_nop 0
	global_load_lds_dwordx4 v144, s[22:23]
	s_add_i32 m0, s0, 0x10000
	s_nop 0
	global_load_lds_dwordx4 v142, s[24:25]
	s_add_i32 m0, s0, 0x12000
	s_nop 0
	global_load_lds_dwordx4 v146, s[24:25]
	s_waitcnt lgkmcnt(0)
	v_mfma_f32_16x16x32_bf16 v[52:55], v[180:183], v[196:199], v[52:55]
	v_mfma_f32_16x16x32_bf16 v[48:51], v[188:191], v[196:199], v[48:51]
	v_mfma_f32_16x16x32_bf16 v[36:39], v[180:183], v[204:207], v[36:39]
	v_mfma_f32_16x16x32_bf16 v[32:35], v[188:191], v[204:207], v[32:35]
	v_mfma_f32_16x16x32_bf16 v[20:23], v[180:183], v[212:215], v[20:23]
	v_mfma_f32_16x16x32_bf16 v[16:19], v[188:191], v[212:215], v[16:19]
	v_mfma_f32_16x16x32_bf16 v[4:7], v[180:183], v[220:223], v[4:7]
	v_mfma_f32_16x16x32_bf16 v[0:3], v[188:191], v[220:223], v[0:3]
	v_mfma_f32_16x16x32_bf16 v[52:55], v[184:187], v[200:203], v[52:55]
	v_mfma_f32_16x16x32_bf16 v[48:51], v[192:195], v[200:203], v[48:51]
	v_mfma_f32_16x16x32_bf16 v[36:39], v[184:187], v[208:211], v[36:39]
	v_mfma_f32_16x16x32_bf16 v[32:35], v[192:195], v[208:211], v[32:35]
	v_mfma_f32_16x16x32_bf16 v[20:23], v[184:187], v[216:219], v[20:23]
	v_mfma_f32_16x16x32_bf16 v[16:19], v[192:195], v[216:219], v[16:19]
	v_mfma_f32_16x16x32_bf16 v[4:7], v[184:187], v[224:227], v[4:7]
	v_mfma_f32_16x16x32_bf16 v[0:3], v[192:195], v[224:227], v[0:3]
	s_waitcnt vmcnt(8)
	s_barrier
	ds_read_b128 v[180:183], v161
	ds_read_b128 v[184:187], v161 offset:1024
	ds_read_b128 v[188:191], v161 offset:2048
	ds_read_b128 v[192:195], v161 offset:3072
	ds_read_b128 v[196:199], v162 offset:16384
	ds_read_b128 v[200:203], v162 offset:17408
	ds_read_b128 v[204:207], v162 offset:18432
	ds_read_b128 v[208:211], v162 offset:19456
	ds_read_b128 v[212:215], v162 offset:20480
	ds_read_b128 v[216:219], v162 offset:21504
	ds_read_b128 v[220:223], v162 offset:22528
	ds_read_b128 v[224:227], v162 offset:23552
	s_add_u32 s22, s22, 0x80
	s_addc_u32 s23, s23, 0
	s_add_u32 s24, s24, 0x80
	s_addc_u32 s25, s25, 0
	s_add_i32 m0, s0, 0x8000
	s_nop 0
	global_load_lds_dwordx4 v140, s[22:23]
	s_add_i32 m0, s0, 0xa000
	s_nop 0
	global_load_lds_dwordx4 v144, s[22:23]
	s_add_i32 m0, s0, 0x18000
	s_nop 0
	global_load_lds_dwordx4 v142, s[24:25]
	s_add_i32 m0, s0, 0x1a000
	s_nop 0
	global_load_lds_dwordx4 v146, s[24:25]
	v_lshl_or_b32 v236, s42, 8, v159
	v_and_b32_e32 v237, 15, v158
	v_lshlrev_b32_e32 v236, 2, v236
	v_lshl_or_b32 v236, v237, 12, v236
	s_and_b64 vcc, s[72:73], exec
	s_cselect_b32 s35, 64, 0
	s_lshl_b32 s32, s94, 8
	s_add_i32 s35, s35, s32
	s_add_i32 s32, s35, 128
	s_mul_hi_u32 s34, s32, 0x7e07e07f
	s_lshr_b32 s34, s34, 11
	s_mul_i32 vcc_lo, s34, 0x1040
	s_sub_i32 vcc_lo, s32, vcc_lo
	s_add_i32 vcc_lo, vcc_lo, -16
	s_lshl_b32 s34, s34, 12
	s_add_i32 s34, s34, vcc_lo
	s_cmp_lt_u32 vcc_lo, 0x1000
	s_cselect_b32 vcc_hi, 1, 0
	s_sub_i32 vcc_lo, s32, 0x4100
	s_cmp_ge_u32 s94, 65
	s_cselect_b32 s34, vcc_lo, s34
	s_cselect_b32 vcc_hi, 1, vcc_hi
	s_cselect_b32 s30, s78, s76
	s_cselect_b32 s31, s79, s77
	s_cmp_lg_u32 vcc_hi, 0
	s_cselect_b32 s34, s34, 0
	s_lshl_b32 s34, s34, 12
	s_add_u32 s30, s30, s34
	s_addc_u32 s31, s31, 0
	global_load_dwordx4 v[64:67], v236, s[30:31] offset:512
	global_load_dwordx4 v[68:71], v236, s[30:31] offset:528
	s_add_i32 s32, s35, 144
	s_mul_hi_u32 s34, s32, 0x7e07e07f
	s_lshr_b32 s34, s34, 11
	s_mul_i32 vcc_lo, s34, 0x1040
	s_sub_i32 vcc_lo, s32, vcc_lo
	s_add_i32 vcc_lo, vcc_lo, -16
	s_lshl_b32 s34, s34, 12
	s_add_i32 s34, s34, vcc_lo
	s_cmp_lt_u32 vcc_lo, 0x1000
	s_cselect_b32 vcc_hi, 1, 0
	s_sub_i32 vcc_lo, s32, 0x4100
	s_cmp_ge_u32 s94, 65
	s_cselect_b32 s34, vcc_lo, s34
	s_cselect_b32 vcc_hi, 1, vcc_hi
	s_cselect_b32 s30, s78, s76
	s_cselect_b32 s31, s79, s77
	s_cmp_lg_u32 vcc_hi, 0
	s_cselect_b32 s34, s34, 0
	s_lshl_b32 s34, s34, 12
	s_add_u32 s30, s30, s34
	s_addc_u32 s31, s31, 0
	global_load_dwordx4 v[72:75], v236, s[30:31] offset:512
	global_load_dwordx4 v[76:79], v236, s[30:31] offset:528
	s_add_i32 s32, s35, 160
	s_mul_hi_u32 s34, s32, 0x7e07e07f
	s_lshr_b32 s34, s34, 11
	s_mul_i32 vcc_lo, s34, 0x1040
	s_sub_i32 vcc_lo, s32, vcc_lo
	s_add_i32 vcc_lo, vcc_lo, -16
	s_lshl_b32 s34, s34, 12
	s_add_i32 s34, s34, vcc_lo
	s_cmp_lt_u32 vcc_lo, 0x1000
	s_cselect_b32 vcc_hi, 1, 0
	s_sub_i32 vcc_lo, s32, 0x4100
	s_cmp_ge_u32 s94, 65
	s_cselect_b32 s34, vcc_lo, s34
	s_cselect_b32 vcc_hi, 1, vcc_hi
	s_cselect_b32 s30, s78, s76
	s_cselect_b32 s31, s79, s77
	s_cmp_lg_u32 vcc_hi, 0
	s_cselect_b32 s34, s34, 0
	s_lshl_b32 s34, s34, 12
	s_add_u32 s30, s30, s34
	s_addc_u32 s31, s31, 0
	global_load_dwordx4 v[80:83], v236, s[30:31] offset:512
	global_load_dwordx4 v[84:87], v236, s[30:31] offset:528
	s_add_i32 s32, s35, 176
	s_mul_hi_u32 s34, s32, 0x7e07e07f
	s_lshr_b32 s34, s34, 11
	s_mul_i32 vcc_lo, s34, 0x1040
	s_sub_i32 vcc_lo, s32, vcc_lo
	s_add_i32 vcc_lo, vcc_lo, -16
	s_lshl_b32 s34, s34, 12
	s_add_i32 s34, s34, vcc_lo
	s_cmp_lt_u32 vcc_lo, 0x1000
	s_cselect_b32 vcc_hi, 1, 0
	s_sub_i32 vcc_lo, s32, 0x4100
	s_cmp_ge_u32 s94, 65
	s_cselect_b32 s34, vcc_lo, s34
	s_cselect_b32 vcc_hi, 1, vcc_hi
	s_cselect_b32 s30, s78, s76
	s_cselect_b32 s31, s79, s77
	s_cmp_lg_u32 vcc_hi, 0
	s_cselect_b32 s34, s34, 0
	s_lshl_b32 s34, s34, 12
	s_add_u32 s30, s30, s34
	s_addc_u32 s31, s31, 0
	global_load_dwordx4 v[88:91], v236, s[30:31] offset:512
	global_load_dwordx4 v[92:95], v236, s[30:31] offset:528
	s_waitcnt lgkmcnt(0)
; #define PG8_STAGE(bufoff, gbase, voff) do { _Pragma("unroll") for (int _i = 0; _i < 2; ++_i) \
;         __builtin_amdgcn_global_load_lds((const unsigned*)((const char*)(gbase) + (voff)[_i]), (PG8_LAS unsigned*)(lds + (bufoff) + ldsw + _i * 8192), 16, 0, 0); } while (0)
; #define PG8_LDA(dst, b, h) do { _Pragma("unroll") for (int m = 0; m < 4; ++m) _Pragma("unroll") for (int k = 0; k < 2; ++k) dst[m][k] = *(const PG8_LAS bf16x8*)(lds + PG8_SA(b, h) + aoff + m * 2048 + k * 1024); } while (0)
; #define PG8_LDB(dst, b, h) do { _Pragma("unroll") for (int n = 0; n < 2; ++n) _Pragma("unroll") for (int k = 0; k < 2; ++k) dst[n][k] = *(const PG8_LAS bf16x8*)(lds + PG8_SB(b, h) + boff + n * 2048 + k * 1024); } while (0)
; #define PG8_MMA(ai, bj, At, Bt) do { __builtin_amdgcn_s_setprio(1); _Pragma("unroll") for (int m = 0; m < 4; ++m) _Pragma("unroll") for (int n = 0; n < 2; ++n) _Pragma("unroll") for (int k = 0; k < 2; ++k) \
;         acc[ai][bj][m][n] = __builtin_amdgcn_mfma_f32_16x16x32_bf16(Bt[n][k], At[m][k], acc[ai][bj][m][n], 0, 0, 0); __builtin_amdgcn_s_setprio(0); } while (0)
; #define PG8_WAIT_V(n) asm volatile("s_waitcnt vmcnt(" #n ")" ::: "memory")
; template <class Epi, class Sched, bool ALIGN_EPI = false, bool SP2 = false>
; __device__ __forceinline__ void gemm_phase(PG8_LAS unsigned char* lds, const Gemm g, const Sched& S, const Epi& E) {
;     ...
;             PG8_LDB(B0, 0, 0); PG8_LDB(B1, 0, 1); PG8_SCHED; PG8_LDA(At, 0, 0); PG8_STAGE(PG8_SA(1, 1), a1 + hstep, voffA);
;             PG8_WAIT_V(8); PG8_WAIT_L(0); PG8_BAR; PG8_MMA(0, 0, At, B0); PG8_MMA(0, 1, At, B1); PG8_BAR; PG8_SCHED;
;             PG8_LDA(At, 0, 1); PG8_STAGE(PG8_SB(0, 0), b2, voffB); PG8_STAGE(PG8_SB(0, 1), b2 + hstep, voffB); PG8_STAGE(PG8_SA(0, 0), a2, voffA);
;             PG8_WAIT_V(8); PG8_WAIT_L(0); PG8_BAR; PG8_MMA(1, 0, At, B0); PG8_MMA(1, 1, At, B1); PG8_BAR; PG8_SCHED;
;             PG8_LDB(B0, 1, 0); PG8_LDB(B1, 1, 1); PG8_SCHED; PG8_LDA(At, 1, 0); PG8_STAGE(PG8_SA(0, 1), a2 + hstep, voffA);
;             PG8_WAIT_V(8); PG8_WAIT_L(0); PG8_BAR; PG8_MMA(0, 0, At, B0); PG8_MMA(0, 1, At, B1); PG8_BAR; PG8_SCHED;
;             PG8_LDA(At, 1, 1); PG8_STAGE(PG8_SB(1, 0), b3, voffB); PG8_STAGE(PG8_SB(1, 1), b3 + hstep, voffB); PG8_STAGE(PG8_SA(1, 0), a3, voffA);
;             PG8_WAIT_V(8); PG8_WAIT_L(0); PG8_BAR; PG8_MMA(1, 0, At, B0); PG8_MMA(1, 1, At, B1); PG8_BAR; PG8_SCHED;
	v_mfma_f32_16x16x32_bf16 v[52:55], v[180:183], v[196:199], v[52:55]
	v_mfma_f32_16x16x32_bf16 v[48:51], v[188:191], v[196:199], v[48:51]
	v_mfma_f32_16x16x32_bf16 v[36:39], v[180:183], v[204:207], v[36:39]
	v_mfma_f32_16x16x32_bf16 v[32:35], v[188:191], v[204:207], v[32:35]
	v_mfma_f32_16x16x32_bf16 v[20:23], v[180:183], v[212:215], v[20:23]
	v_mfma_f32_16x16x32_bf16 v[16:19], v[188:191], v[212:215], v[16:19]
	v_mfma_f32_16x16x32_bf16 v[4:7], v[180:183], v[220:223], v[4:7]
	v_mfma_f32_16x16x32_bf16 v[0:3], v[188:191], v[220:223], v[0:3]
	v_mfma_f32_16x16x32_bf16 v[52:55], v[184:187], v[200:203], v[52:55]
	v_mfma_f32_16x16x32_bf16 v[48:51], v[192:195], v[200:203], v[48:51]
	v_mfma_f32_16x16x32_bf16 v[36:39], v[184:187], v[208:211], v[36:39]
	v_mfma_f32_16x16x32_bf16 v[32:35], v[192:195], v[208:211], v[32:35]
	v_mfma_f32_16x16x32_bf16 v[20:23], v[184:187], v[216:219], v[20:23]
	v_mfma_f32_16x16x32_bf16 v[16:19], v[192:195], v[216:219], v[16:19]
	v_mfma_f32_16x16x32_bf16 v[4:7], v[184:187], v[224:227], v[4:7]
	v_mfma_f32_16x16x32_bf16 v[0:3], v[192:195], v[224:227], v[0:3]
	s_waitcnt vmcnt(16)
	s_barrier
	ds_read_b128 v[180:183], v164
	ds_read_b128 v[184:187], v164 offset:1024
	ds_read_b128 v[188:191], v164 offset:2048
	ds_read_b128 v[192:195], v164 offset:3072
	ds_read_b128 v[196:199], v162 offset:49152
	ds_read_b128 v[200:203], v162 offset:50176
	ds_read_b128 v[204:207], v162 offset:51200
	ds_read_b128 v[208:211], v162 offset:52224
	ds_read_b128 v[212:215], v162 offset:53248
	ds_read_b128 v[216:219], v162 offset:54272
	ds_read_b128 v[220:223], v162 offset:55296
	ds_read_b128 v[224:227], v162 offset:56320
	s_waitcnt lgkmcnt(0)
	v_mfma_f32_16x16x32_bf16 v[52:55], v[180:183], v[196:199], v[52:55]
	v_mfma_f32_16x16x32_bf16 v[48:51], v[188:191], v[196:199], v[48:51]
	v_mfma_f32_16x16x32_bf16 v[36:39], v[180:183], v[204:207], v[36:39]
	v_mfma_f32_16x16x32_bf16 v[32:35], v[188:191], v[204:207], v[32:35]
	v_mfma_f32_16x16x32_bf16 v[20:23], v[180:183], v[212:215], v[20:23]
	v_mfma_f32_16x16x32_bf16 v[16:19], v[188:191], v[212:215], v[16:19]
	v_mfma_f32_16x16x32_bf16 v[4:7], v[180:183], v[220:223], v[4:7]
	v_mfma_f32_16x16x32_bf16 v[0:3], v[188:191], v[220:223], v[0:3]
	v_mfma_f32_16x16x32_bf16 v[52:55], v[184:187], v[200:203], v[52:55]
	v_mfma_f32_16x16x32_bf16 v[48:51], v[192:195], v[200:203], v[48:51]
	v_mfma_f32_16x16x32_bf16 v[36:39], v[184:187], v[208:211], v[36:39]
	v_mfma_f32_16x16x32_bf16 v[32:35], v[192:195], v[208:211], v[32:35]
	v_mfma_f32_16x16x32_bf16 v[20:23], v[184:187], v[216:219], v[20:23]
	v_mfma_f32_16x16x32_bf16 v[16:19], v[192:195], v[216:219], v[16:19]
	v_mfma_f32_16x16x32_bf16 v[4:7], v[184:187], v[224:227], v[4:7]
	v_mfma_f32_16x16x32_bf16 v[0:3], v[192:195], v[224:227], v[0:3]
	s_waitcnt vmcnt(12)
	s_barrier
	ds_read_b128 v[180:183], v160
	ds_read_b128 v[184:187], v160 offset:1024
	ds_read_b128 v[188:191], v160 offset:2048
	ds_read_b128 v[192:195], v160 offset:3072
	ds_read_b128 v[196:199], v162
	ds_read_b128 v[200:203], v162 offset:1024
	ds_read_b128 v[204:207], v162 offset:2048
	ds_read_b128 v[208:211], v162 offset:3072
	ds_read_b128 v[212:215], v162 offset:4096
	ds_read_b128 v[216:219], v162 offset:5120
	ds_read_b128 v[220:223], v162 offset:6144
	ds_read_b128 v[224:227], v162 offset:7168
	s_waitcnt lgkmcnt(0)
	v_mfma_f32_16x16x32_bf16 v[52:55], v[180:183], v[196:199], v[52:55]
	v_mfma_f32_16x16x32_bf16 v[48:51], v[188:191], v[196:199], v[48:51]
	v_mfma_f32_16x16x32_bf16 v[36:39], v[180:183], v[204:207], v[36:39]
	v_mfma_f32_16x16x32_bf16 v[32:35], v[188:191], v[204:207], v[32:35]
	v_mfma_f32_16x16x32_bf16 v[20:23], v[180:183], v[212:215], v[20:23]
	v_mfma_f32_16x16x32_bf16 v[16:19], v[188:191], v[212:215], v[16:19]
	v_mfma_f32_16x16x32_bf16 v[4:7], v[180:183], v[220:223], v[4:7]
	v_mfma_f32_16x16x32_bf16 v[0:3], v[188:191], v[220:223], v[0:3]
	v_mfma_f32_16x16x32_bf16 v[52:55], v[184:187], v[200:203], v[52:55]
	v_mfma_f32_16x16x32_bf16 v[48:51], v[192:195], v[200:203], v[48:51]
	v_mfma_f32_16x16x32_bf16 v[36:39], v[184:187], v[208:211], v[36:39]
	v_mfma_f32_16x16x32_bf16 v[32:35], v[192:195], v[208:211], v[32:35]
	v_mfma_f32_16x16x32_bf16 v[20:23], v[184:187], v[216:219], v[20:23]
	v_mfma_f32_16x16x32_bf16 v[16:19], v[192:195], v[216:219], v[16:19]
	v_mfma_f32_16x16x32_bf16 v[4:7], v[184:187], v[224:227], v[4:7]
	v_mfma_f32_16x16x32_bf16 v[0:3], v[192:195], v[224:227], v[0:3]
	s_waitcnt vmcnt(8)
	s_barrier
	ds_read_b128 v[180:183], v163
	ds_read_b128 v[184:187], v163 offset:1024
	ds_read_b128 v[188:191], v163 offset:2048
	ds_read_b128 v[192:195], v163 offset:3072
	ds_read_b128 v[196:199], v162 offset:32768
	ds_read_b128 v[200:203], v162 offset:33792
	ds_read_b128 v[204:207], v162 offset:34816
	ds_read_b128 v[208:211], v162 offset:35840
	ds_read_b128 v[212:215], v162 offset:36864
	ds_read_b128 v[216:219], v162 offset:37888
	ds_read_b128 v[220:223], v162 offset:38912
	ds_read_b128 v[224:227], v162 offset:39936
	s_waitcnt lgkmcnt(0)
	v_mfma_f32_16x16x32_bf16 v[52:55], v[180:183], v[196:199], v[52:55]
	v_mfma_f32_16x16x32_bf16 v[48:51], v[188:191], v[196:199], v[48:51]
	v_mfma_f32_16x16x32_bf16 v[36:39], v[180:183], v[204:207], v[36:39]
	v_mfma_f32_16x16x32_bf16 v[32:35], v[188:191], v[204:207], v[32:35]
	v_mfma_f32_16x16x32_bf16 v[20:23], v[180:183], v[212:215], v[20:23]
	v_mfma_f32_16x16x32_bf16 v[16:19], v[188:191], v[212:215], v[16:19]
	v_mfma_f32_16x16x32_bf16 v[4:7], v[180:183], v[220:223], v[4:7]
	v_mfma_f32_16x16x32_bf16 v[0:3], v[188:191], v[220:223], v[0:3]
	v_mfma_f32_16x16x32_bf16 v[52:55], v[184:187], v[200:203], v[52:55]
	v_mfma_f32_16x16x32_bf16 v[48:51], v[192:195], v[200:203], v[48:51]
	v_mfma_f32_16x16x32_bf16 v[36:39], v[184:187], v[208:211], v[36:39]
	v_mfma_f32_16x16x32_bf16 v[32:35], v[192:195], v[208:211], v[32:35]
	v_mfma_f32_16x16x32_bf16 v[20:23], v[184:187], v[216:219], v[20:23]
	v_mfma_f32_16x16x32_bf16 v[16:19], v[192:195], v[216:219], v[16:19]
	v_mfma_f32_16x16x32_bf16 v[4:7], v[184:187], v[224:227], v[4:7]
	v_mfma_f32_16x16x32_bf16 v[0:3], v[192:195], v[224:227], v[0:3]
	s_branch .LBB0_620
